# MFMA order variant: srcA-stationary (4 MFMAs per srcA register back-to-back, 24 srcA shares, only 4 accumulate chains per block)
# baseline (speedup 1.0000x reference)
; #define PG8_STAGE(bufoff, gbase, voff) do { _Pragma("unroll") for (int _i = 0; _i < 2; ++_i) \
;         __builtin_amdgcn_global_load_lds((const unsigned*)((const char*)(gbase) + (voff)[_i]), (PG8_LAS unsigned*)(lds + (bufoff) + ldsw + _i * 8192), 16, 0, 0); } while (0)
; #define PG8_LDA(dst, b, h) do { _Pragma("unroll") for (int m = 0; m < 4; ++m) _Pragma("unroll") for (int k = 0; k < 2; ++k) dst[m][k] = *(const PG8_LAS bf16x8*)(lds + PG8_SA(b, h) + aoff + m * 2048 + k * 1024); } while (0)
; #define PG8_LDB(dst, b, h) do { _Pragma("unroll") for (int n = 0; n < 2; ++n) _Pragma("unroll") for (int k = 0; k < 2; ++k) dst[n][k] = *(const PG8_LAS bf16x8*)(lds + PG8_SB(b, h) + boff + n * 2048 + k * 1024); } while (0)
; #define PG8_MMA(ai, bj, At, Bt) do { __builtin_amdgcn_s_setprio(1); _Pragma("unroll") for (int m = 0; m < 4; ++m) _Pragma("unroll") for (int n = 0; n < 2; ++n) _Pragma("unroll") for (int k = 0; k < 2; ++k) \
;         acc[ai][bj][m][n] = __builtin_amdgcn_mfma_f32_16x16x32_bf16(Bt[n][k], At[m][k], acc[ai][bj][m][n], 0, 0, 0); __builtin_amdgcn_s_setprio(0); } while (0)
; #define PG8_WAIT_V(n) asm volatile("s_waitcnt vmcnt(" #n ")" ::: "memory")
; #define PG8_WAIT_L(n) asm volatile("s_waitcnt lgkmcnt(" #n ")" ::: "memory")
; template <class Epi, class Sched, bool ALIGN_EPI = false, bool SP2 = false>
; __device__ __forceinline__ void gemm_phase(PG8_LAS unsigned char* lds, const Gemm g, const Sched& S, const Epi& E) {
;     ...
;             const bool last = (t == nt - 2);
;             const char* a1 = cA + (size_t)(t + 1) * kstep;
;             const char* a2 = last ? nA : cA + (size_t)(t + 2) * kstep; const char* b2 = last ? nB : cB + (size_t)(t + 2) * kstep;
;             const char* a3 = a2 + kstep; const char* b3 = b2 + kstep;
;             if (last && has_next) S.a_ready(nxt);
;             if constexpr (SP2) {
;             PG8_LDB(B0, 0, 0); PG8_LDB(B1, 0, 1); PG8_SCHED; PG8_LDA(At, 0, 0); PG8_STAGE(PG8_SA(1, 1), a1 + hstep, voffA);
;             PG8_WAIT_V(8); PG8_WAIT_L(0); PG8_BAR; PG8_MMA(0, 0, At, B0); PG8_MMA(0, 1, At, B1); PG8_BAR; PG8_SCHED;
;             PG8_LDA(At, 0, 1); PG8_STAGE(PG8_SB(0, 0), b2, voffB); PG8_STAGE(PG8_SB(0, 1), b2 + hstep, voffB); PG8_STAGE(PG8_SA(0, 0), a2, voffA);
;             PG8_WAIT_V(8); PG8_WAIT_L(0); PG8_BAR; PG8_MMA(1, 0, At, B0); PG8_MMA(1, 1, At, B1); PG8_BAR; PG8_SCHED;
.LBB0_673:
	ds_read_b128 v[148:151], v241 offset:0
	ds_read_b128 v[156:159], v241 offset:1024
	ds_read_b128 v[166:169], v241 offset:2048
	ds_read_b128 v[170:173], v241 offset:3072
	ds_read_b128 v[174:177], v241 offset:16384
	ds_read_b128 v[178:181], v241 offset:17408
	ds_read_b128 v[182:185], v241 offset:18432
	ds_read_b128 v[186:189], v241 offset:19456
	s_add_u32 s20, s22, 0xfff00080
	s_addc_u32 s21, s23, -1
	s_cmp_eq_u32 s35, 60
	s_cselect_b32 s25, s11, s21
	s_cselect_b32 s24, s52, s20
	s_cselect_b32 s21, s13, s34
	s_cselect_b32 s20, s53, s62
	s_add_i32 m0, s19, 0xc000
	ds_read_b128 v[190:193], v161
	ds_read_b128 v[194:197], v161 offset:1024
	ds_read_b128 v[198:201], v161 offset:2048
	ds_read_b128 v[202:205], v161 offset:3072
	ds_read_b128 v[206:209], v161 offset:4096
	ds_read_b128 v[210:213], v161 offset:5120
	ds_read_b128 v[214:217], v161 offset:6144
	ds_read_b128 v[218:221], v161 offset:7168
	global_load_lds_dwordx4 v138, s[22:23]
	s_add_i32 m0, s19, 0xe000
	s_nop 0
	global_load_lds_dwordx4 v140, s[22:23]
	s_waitcnt vmcnt(8)
	s_waitcnt lgkmcnt(0)
	s_barrier
	s_waitcnt lgkmcnt(0)
	v_mfma_f32_16x16x32_bf16 v[118:121], v[148:151], v[190:193], v[118:121]
	v_mfma_f32_16x16x32_bf16 v[102:105], v[148:151], v[198:201], v[102:105]
	v_mfma_f32_16x16x32_bf16 v[86:89], v[148:151], v[206:209], v[86:89]
	v_mfma_f32_16x16x32_bf16 v[70:73], v[148:151], v[214:217], v[70:73]
	v_mfma_f32_16x16x32_bf16 v[70:73], v[156:159], v[218:221], v[70:73]
	v_mfma_f32_16x16x32_bf16 v[86:89], v[156:159], v[210:213], v[86:89]
	v_mfma_f32_16x16x32_bf16 v[102:105], v[156:159], v[202:205], v[102:105]
	v_mfma_f32_16x16x32_bf16 v[118:121], v[156:159], v[194:197], v[118:121]
	v_mfma_f32_16x16x32_bf16 v[114:117], v[170:173], v[194:197], v[114:117]
	v_mfma_f32_16x16x32_bf16 v[98:101], v[170:173], v[202:205], v[98:101]
	v_mfma_f32_16x16x32_bf16 v[82:85], v[170:173], v[210:213], v[82:85]
	v_mfma_f32_16x16x32_bf16 v[66:69], v[170:173], v[218:221], v[66:69]
	v_mfma_f32_16x16x32_bf16 v[66:69], v[166:169], v[214:217], v[66:69]
	v_mfma_f32_16x16x32_bf16 v[82:85], v[166:169], v[206:209], v[82:85]
	v_mfma_f32_16x16x32_bf16 v[98:101], v[166:169], v[198:201], v[98:101]
	v_mfma_f32_16x16x32_bf16 v[114:117], v[166:169], v[190:193], v[114:117]
	v_mfma_f32_16x16x32_bf16 v[126:129], v[174:177], v[190:193], v[126:129]
	v_mfma_f32_16x16x32_bf16 v[110:113], v[174:177], v[198:201], v[110:113]
	v_mfma_f32_16x16x32_bf16 v[94:97], v[174:177], v[206:209], v[94:97]
	v_mfma_f32_16x16x32_bf16 v[78:81], v[174:177], v[214:217], v[78:81]
	v_mfma_f32_16x16x32_bf16 v[78:81], v[178:181], v[218:221], v[78:81]
	v_mfma_f32_16x16x32_bf16 v[94:97], v[178:181], v[210:213], v[94:97]
	v_mfma_f32_16x16x32_bf16 v[110:113], v[178:181], v[202:205], v[110:113]
	v_mfma_f32_16x16x32_bf16 v[126:129], v[178:181], v[194:197], v[126:129]
	v_mfma_f32_16x16x32_bf16 v[122:125], v[186:189], v[194:197], v[122:125]
	v_mfma_f32_16x16x32_bf16 v[106:109], v[186:189], v[202:205], v[106:109]
	v_mfma_f32_16x16x32_bf16 v[90:93], v[186:189], v[210:213], v[90:93]
	v_mfma_f32_16x16x32_bf16 v[74:77], v[186:189], v[218:221], v[74:77]
	v_mfma_f32_16x16x32_bf16 v[74:77], v[182:185], v[214:217], v[74:77]
	v_mfma_f32_16x16x32_bf16 v[90:93], v[182:185], v[206:209], v[90:93]
	v_mfma_f32_16x16x32_bf16 v[106:109], v[182:185], v[198:201], v[106:109]
	v_mfma_f32_16x16x32_bf16 v[122:125], v[182:185], v[190:193], v[122:125]
	s_barrier
	s_add_i32 s63, s43, s26
	s_mov_b32 m0, s63
	ds_read_b128 v[190:193], v161 offset:16384
	ds_read_b128 v[194:197], v161 offset:17408
	ds_read_b128 v[198:201], v161 offset:18432
	ds_read_b128 v[202:205], v161 offset:19456
	ds_read_b128 v[206:209], v161 offset:20480
	ds_read_b128 v[210:213], v161 offset:21504
	ds_read_b128 v[214:217], v161 offset:22528
	ds_read_b128 v[218:221], v161 offset:23552
	global_load_lds_dwordx4 v132, s[20:21]
	s_add_i32 m0, s63, 0x2000
	s_add_u32 s64, s20, 0x100000
	s_addc_u32 s65, s21, 0
	s_add_i32 s63, s46, s26
	global_load_lds_dwordx4 v136, s[20:21]
	s_mov_b32 m0, s63
	s_add_u32 s100, s24, 0x80
	s_addc_u32 s101, s25, 0
	global_load_lds_dwordx4 v132, s[64:65]
	s_add_i32 m0, s63, 0x2000
	s_nop 0
	global_load_lds_dwordx4 v136, s[64:65]
	s_mov_b32 m0, s19
	s_nop 0
	global_load_lds_dwordx4 v130, s[24:25]
	s_mov_b32 m0, s29
	s_nop 0
	global_load_lds_dwordx4 v134, s[24:25]
	s_waitcnt vmcnt(8)
	s_waitcnt lgkmcnt(0)
	s_barrier
	s_waitcnt lgkmcnt(0)
	v_mfma_f32_16x16x32_bf16 v[54:57], v[148:151], v[190:193], v[54:57]
	v_mfma_f32_16x16x32_bf16 v[38:41], v[148:151], v[198:201], v[38:41]
	v_mfma_f32_16x16x32_bf16 v[22:25], v[148:151], v[206:209], v[22:25]
	v_mfma_f32_16x16x32_bf16 v[6:9], v[148:151], v[214:217], v[6:9]
	v_mfma_f32_16x16x32_bf16 v[6:9], v[156:159], v[218:221], v[6:9]
	v_mfma_f32_16x16x32_bf16 v[22:25], v[156:159], v[210:213], v[22:25]
	v_mfma_f32_16x16x32_bf16 v[38:41], v[156:159], v[202:205], v[38:41]
	v_mfma_f32_16x16x32_bf16 v[54:57], v[156:159], v[194:197], v[54:57]
	v_mfma_f32_16x16x32_bf16 v[50:53], v[170:173], v[194:197], v[50:53]
	v_mfma_f32_16x16x32_bf16 v[34:37], v[170:173], v[202:205], v[34:37]
	v_mfma_f32_16x16x32_bf16 v[18:21], v[170:173], v[210:213], v[18:21]
	v_mfma_f32_16x16x32_bf16 v[2:5], v[170:173], v[218:221], v[2:5]
	v_mfma_f32_16x16x32_bf16 v[2:5], v[166:169], v[214:217], v[2:5]
	v_mfma_f32_16x16x32_bf16 v[18:21], v[166:169], v[206:209], v[18:21]
	v_mfma_f32_16x16x32_bf16 v[34:37], v[166:169], v[198:201], v[34:37]
	v_mfma_f32_16x16x32_bf16 v[50:53], v[166:169], v[190:193], v[50:53]
	v_mfma_f32_16x16x32_bf16 v[62:65], v[174:177], v[190:193], v[62:65]
	v_mfma_f32_16x16x32_bf16 v[46:49], v[174:177], v[198:201], v[46:49]
	v_mfma_f32_16x16x32_bf16 v[30:33], v[174:177], v[206:209], v[30:33]
	v_mfma_f32_16x16x32_bf16 v[10:13], v[174:177], v[214:217], v[10:13]
	v_mfma_f32_16x16x32_bf16 v[10:13], v[178:181], v[218:221], v[10:13]
	v_mfma_f32_16x16x32_bf16 v[30:33], v[178:181], v[210:213], v[30:33]
	v_mfma_f32_16x16x32_bf16 v[46:49], v[178:181], v[202:205], v[46:49]
	v_mfma_f32_16x16x32_bf16 v[62:65], v[178:181], v[194:197], v[62:65]
	v_mfma_f32_16x16x32_bf16 v[58:61], v[186:189], v[194:197], v[58:61]
	v_mfma_f32_16x16x32_bf16 v[42:45], v[186:189], v[202:205], v[42:45]
	v_mfma_f32_16x16x32_bf16 v[26:29], v[186:189], v[210:213], v[26:29]
	v_mfma_f32_16x16x32_bf16 v[14:17], v[186:189], v[218:221], v[14:17]
	v_mfma_f32_16x16x32_bf16 v[14:17], v[182:185], v[214:217], v[14:17]
	v_mfma_f32_16x16x32_bf16 v[26:29], v[182:185], v[206:209], v[26:29]
	v_mfma_f32_16x16x32_bf16 v[42:45], v[182:185], v[198:201], v[42:45]
	v_mfma_f32_16x16x32_bf16 v[58:61], v[182:185], v[190:193], v[58:61]
	s_barrier
; #define PG8_STAGE(bufoff, gbase, voff) do { _Pragma("unroll") for (int _i = 0; _i < 2; ++_i) \
;         __builtin_amdgcn_global_load_lds((const unsigned*)((const char*)(gbase) + (voff)[_i]), (PG8_LAS unsigned*)(lds + (bufoff) + ldsw + _i * 8192), 16, 0, 0); } while (0)
; #define PG8_LDA(dst, b, h) do { _Pragma("unroll") for (int m = 0; m < 4; ++m) _Pragma("unroll") for (int k = 0; k < 2; ++k) dst[m][k] = *(const PG8_LAS bf16x8*)(lds + PG8_SA(b, h) + aoff + m * 2048 + k * 1024); } while (0)
; #define PG8_LDB(dst, b, h) do { _Pragma("unroll") for (int n = 0; n < 2; ++n) _Pragma("unroll") for (int k = 0; k < 2; ++k) dst[n][k] = *(const PG8_LAS bf16x8*)(lds + PG8_SB(b, h) + boff + n * 2048 + k * 1024); } while (0)
; #define PG8_MMA(ai, bj, At, Bt) do { __builtin_amdgcn_s_setprio(1); _Pragma("unroll") for (int m = 0; m < 4; ++m) _Pragma("unroll") for (int n = 0; n < 2; ++n) _Pragma("unroll") for (int k = 0; k < 2; ++k) \
;         acc[ai][bj][m][n] = __builtin_amdgcn_mfma_f32_16x16x32_bf16(Bt[n][k], At[m][k], acc[ai][bj][m][n], 0, 0, 0); __builtin_amdgcn_s_setprio(0); } while (0)
; #define PG8_WAIT_V(n) asm volatile("s_waitcnt vmcnt(" #n ")" ::: "memory")
; #define PG8_WAIT_L(n) asm volatile("s_waitcnt lgkmcnt(" #n ")" ::: "memory")
; #define PG8_BAR __builtin_amdgcn_s_barrier()
; template <class Epi, class Sched, bool ALIGN_EPI = false, bool SP2 = false>
; __device__ __forceinline__ void gemm_phase(PG8_LAS unsigned char* lds, const Gemm g, const Sched& S, const Epi& E) {
;     ...
;         for (int t = 0; t < nt; t += 2) {
;             const bool last = (t == nt - 2);
;             const char* a1 = cA + (size_t)(t + 1) * kstep;
;             const char* a2 = last ? nA : cA + (size_t)(t + 2) * kstep; const char* b2 = last ? nB : cB + (size_t)(t + 2) * kstep;
;             const char* a3 = a2 + kstep; const char* b3 = b2 + kstep;
;     ...
;             PG8_LDB(B0, 1, 0); PG8_LDB(B1, 1, 1); PG8_SCHED; PG8_LDA(At, 1, 0); PG8_STAGE(PG8_SA(0, 1), a2 + hstep, voffA);
;             PG8_WAIT_V(8); PG8_WAIT_L(0); PG8_BAR; PG8_MMA(0, 0, At, B0); PG8_MMA(0, 1, At, B1); PG8_BAR; PG8_SCHED;
;             PG8_LDA(At, 1, 1); PG8_STAGE(PG8_SB(1, 0), b3, voffB); PG8_STAGE(PG8_SB(1, 1), b3 + hstep, voffB); PG8_STAGE(PG8_SA(1, 0), a3, voffA);
;             PG8_WAIT_V(8); PG8_WAIT_L(0); PG8_BAR; PG8_MMA(1, 0, At, B0); PG8_MMA(1, 1, At, B1); PG8_BAR; PG8_SCHED;
	s_add_i32 s63, 0, 0x18000
	s_add_i32 s64, 0, 0x1c000
	ds_read_b128 v[148:151], v241 offset:32768
	ds_read_b128 v[156:159], v241 offset:33792
	ds_read_b128 v[166:169], v241 offset:34816
	ds_read_b128 v[170:173], v241 offset:35840
	ds_read_b128 v[174:177], v241 offset:49152
	ds_read_b128 v[178:181], v241 offset:50176
	ds_read_b128 v[182:185], v241 offset:51200
	ds_read_b128 v[186:189], v241 offset:52224
	s_add_u32 s24, s24, 0x100000
	s_addc_u32 s25, s25, 0
	s_mov_b32 m0, s30
	ds_read_b128 v[190:193], v161 offset:32768
	ds_read_b128 v[194:197], v161 offset:33792
	ds_read_b128 v[198:201], v161 offset:34816
	ds_read_b128 v[202:205], v161 offset:35840
	ds_read_b128 v[206:209], v161 offset:36864
	ds_read_b128 v[210:213], v161 offset:37888
	ds_read_b128 v[214:217], v161 offset:38912
	ds_read_b128 v[218:221], v161 offset:39936
	global_load_lds_dwordx4 v130, s[24:25]
	s_mov_b32 m0, s31
	s_nop 0
	global_load_lds_dwordx4 v134, s[24:25]
	s_waitcnt vmcnt(8)
	s_waitcnt lgkmcnt(0)
	s_barrier
	s_waitcnt lgkmcnt(0)
	v_mfma_f32_16x16x32_bf16 v[118:121], v[148:151], v[190:193], v[118:121]
	v_mfma_f32_16x16x32_bf16 v[102:105], v[148:151], v[198:201], v[102:105]
	v_mfma_f32_16x16x32_bf16 v[86:89], v[148:151], v[206:209], v[86:89]
	v_mfma_f32_16x16x32_bf16 v[70:73], v[148:151], v[214:217], v[70:73]
	v_mfma_f32_16x16x32_bf16 v[70:73], v[156:159], v[218:221], v[70:73]
	v_mfma_f32_16x16x32_bf16 v[86:89], v[156:159], v[210:213], v[86:89]
	v_mfma_f32_16x16x32_bf16 v[102:105], v[156:159], v[202:205], v[102:105]
	v_mfma_f32_16x16x32_bf16 v[118:121], v[156:159], v[194:197], v[118:121]
	v_mfma_f32_16x16x32_bf16 v[114:117], v[170:173], v[194:197], v[114:117]
	v_mfma_f32_16x16x32_bf16 v[98:101], v[170:173], v[202:205], v[98:101]
	v_mfma_f32_16x16x32_bf16 v[82:85], v[170:173], v[210:213], v[82:85]
	v_mfma_f32_16x16x32_bf16 v[66:69], v[170:173], v[218:221], v[66:69]
	v_mfma_f32_16x16x32_bf16 v[66:69], v[166:169], v[214:217], v[66:69]
	v_mfma_f32_16x16x32_bf16 v[82:85], v[166:169], v[206:209], v[82:85]
	v_mfma_f32_16x16x32_bf16 v[98:101], v[166:169], v[198:201], v[98:101]
	v_mfma_f32_16x16x32_bf16 v[114:117], v[166:169], v[190:193], v[114:117]
	v_mfma_f32_16x16x32_bf16 v[126:129], v[174:177], v[190:193], v[126:129]
	v_mfma_f32_16x16x32_bf16 v[110:113], v[174:177], v[198:201], v[110:113]
	v_mfma_f32_16x16x32_bf16 v[94:97], v[174:177], v[206:209], v[94:97]
	v_mfma_f32_16x16x32_bf16 v[78:81], v[174:177], v[214:217], v[78:81]
	v_mfma_f32_16x16x32_bf16 v[78:81], v[178:181], v[218:221], v[78:81]
	v_mfma_f32_16x16x32_bf16 v[94:97], v[178:181], v[210:213], v[94:97]
	v_mfma_f32_16x16x32_bf16 v[110:113], v[178:181], v[202:205], v[110:113]
	v_mfma_f32_16x16x32_bf16 v[126:129], v[178:181], v[194:197], v[126:129]
	v_mfma_f32_16x16x32_bf16 v[122:125], v[186:189], v[194:197], v[122:125]
	v_mfma_f32_16x16x32_bf16 v[106:109], v[186:189], v[202:205], v[106:109]
	v_mfma_f32_16x16x32_bf16 v[90:93], v[186:189], v[210:213], v[90:93]
	v_mfma_f32_16x16x32_bf16 v[74:77], v[186:189], v[218:221], v[74:77]
	v_mfma_f32_16x16x32_bf16 v[74:77], v[182:185], v[214:217], v[74:77]
	v_mfma_f32_16x16x32_bf16 v[90:93], v[182:185], v[206:209], v[90:93]
	v_mfma_f32_16x16x32_bf16 v[106:109], v[182:185], v[198:201], v[106:109]
	v_mfma_f32_16x16x32_bf16 v[122:125], v[182:185], v[190:193], v[122:125]
	s_barrier
	s_add_i32 s24, s63, s26
	s_add_i32 m0, s24, 0xffffff80
	ds_read_b128 v[190:193], v161 offset:49152
	ds_read_b128 v[194:197], v161 offset:50176
	ds_read_b128 v[198:201], v161 offset:51200
	ds_read_b128 v[202:205], v161 offset:52224
	ds_read_b128 v[206:209], v161 offset:53248
	ds_read_b128 v[210:213], v161 offset:54272
	ds_read_b128 v[214:217], v161 offset:55296
	ds_read_b128 v[218:221], v161 offset:56320
	global_load_lds_dwordx4 v132, s[20:21] offset:128
	s_add_i32 m0, s24, 0x1f80
	s_add_i32 s24, s64, s26
	global_load_lds_dwordx4 v136, s[20:21] offset:128
	s_add_u32 s20, s20, 0x100080
	s_addc_u32 s21, s21, 0
	s_mov_b32 m0, s24
	s_nop 0
	global_load_lds_dwordx4 v132, s[20:21]
	s_add_i32 m0, s24, 0x2000
	s_nop 0
	global_load_lds_dwordx4 v136, s[20:21]
	s_mov_b32 m0, s40
	s_nop 0
	global_load_lds_dwordx4 v130, s[100:101]
	s_mov_b32 m0, s41
	s_nop 0
	global_load_lds_dwordx4 v134, s[100:101]
	s_waitcnt vmcnt(8)
	s_waitcnt lgkmcnt(0)
	s_barrier
	s_waitcnt lgkmcnt(0)
	v_mfma_f32_16x16x32_bf16 v[54:57], v[148:151], v[190:193], v[54:57]
	v_mfma_f32_16x16x32_bf16 v[38:41], v[148:151], v[198:201], v[38:41]
	v_mfma_f32_16x16x32_bf16 v[22:25], v[148:151], v[206:209], v[22:25]
	v_mfma_f32_16x16x32_bf16 v[6:9], v[148:151], v[214:217], v[6:9]
	v_mfma_f32_16x16x32_bf16 v[6:9], v[156:159], v[218:221], v[6:9]
	v_mfma_f32_16x16x32_bf16 v[22:25], v[156:159], v[210:213], v[22:25]
	v_mfma_f32_16x16x32_bf16 v[38:41], v[156:159], v[202:205], v[38:41]
	v_mfma_f32_16x16x32_bf16 v[54:57], v[156:159], v[194:197], v[54:57]
	v_mfma_f32_16x16x32_bf16 v[50:53], v[170:173], v[194:197], v[50:53]
	v_mfma_f32_16x16x32_bf16 v[34:37], v[170:173], v[202:205], v[34:37]
	v_mfma_f32_16x16x32_bf16 v[18:21], v[170:173], v[210:213], v[18:21]
	v_mfma_f32_16x16x32_bf16 v[2:5], v[170:173], v[218:221], v[2:5]
	v_mfma_f32_16x16x32_bf16 v[2:5], v[166:169], v[214:217], v[2:5]
	v_mfma_f32_16x16x32_bf16 v[18:21], v[166:169], v[206:209], v[18:21]
	v_mfma_f32_16x16x32_bf16 v[34:37], v[166:169], v[198:201], v[34:37]
	v_mfma_f32_16x16x32_bf16 v[50:53], v[166:169], v[190:193], v[50:53]
	v_mfma_f32_16x16x32_bf16 v[62:65], v[174:177], v[190:193], v[62:65]
	v_mfma_f32_16x16x32_bf16 v[46:49], v[174:177], v[198:201], v[46:49]
	v_mfma_f32_16x16x32_bf16 v[30:33], v[174:177], v[206:209], v[30:33]
	v_mfma_f32_16x16x32_bf16 v[10:13], v[174:177], v[214:217], v[10:13]
	v_mfma_f32_16x16x32_bf16 v[10:13], v[178:181], v[218:221], v[10:13]
	v_mfma_f32_16x16x32_bf16 v[30:33], v[178:181], v[210:213], v[30:33]
	v_mfma_f32_16x16x32_bf16 v[46:49], v[178:181], v[202:205], v[46:49]
	v_mfma_f32_16x16x32_bf16 v[62:65], v[178:181], v[194:197], v[62:65]
	v_mfma_f32_16x16x32_bf16 v[58:61], v[186:189], v[194:197], v[58:61]
	v_mfma_f32_16x16x32_bf16 v[42:45], v[186:189], v[202:205], v[42:45]
	v_mfma_f32_16x16x32_bf16 v[26:29], v[186:189], v[210:213], v[26:29]
	v_mfma_f32_16x16x32_bf16 v[14:17], v[186:189], v[218:221], v[14:17]
	v_mfma_f32_16x16x32_bf16 v[14:17], v[182:185], v[214:217], v[14:17]
	v_mfma_f32_16x16x32_bf16 v[26:29], v[182:185], v[206:209], v[26:29]
	v_mfma_f32_16x16x32_bf16 v[42:45], v[182:185], v[198:201], v[42:45]
	v_mfma_f32_16x16x32_bf16 v[58:61], v[182:185], v[190:193], v[58:61]
	s_barrier
	s_add_i32 s35, s35, 2
	s_add_u32 s22, s22, 0x100
	s_addc_u32 s23, s23, 0
	s_add_u32 s62, s62, 0x100
	s_addc_u32 s34, s34, 0
	s_cmp_gt_u32 s35, 61
	s_cbranch_scc0 .LBB0_673
	s_and_b64 vcc, exec, s[8:9]
	s_cbranch_vccz .LBB0_676
	s_barrier

; #define PG8_STAGE(bufoff, gbase, voff) do { _Pragma("unroll") for (int _i = 0; _i < 2; ++_i) \
;         __builtin_amdgcn_global_load_lds((const unsigned*)((const char*)(gbase) + (voff)[_i]), (PG8_LAS unsigned*)(lds + (bufoff) + ldsw + _i * 8192), 16, 0, 0); } while (0)
; #define PG8_LDA(dst, b, h) do { _Pragma("unroll") for (int m = 0; m < 4; ++m) _Pragma("unroll") for (int k = 0; k < 2; ++k) dst[m][k] = *(const PG8_LAS bf16x8*)(lds + PG8_SA(b, h) + aoff + m * 2048 + k * 1024); } while (0)
; #define PG8_LDB(dst, b, h) do { _Pragma("unroll") for (int n = 0; n < 2; ++n) _Pragma("unroll") for (int k = 0; k < 2; ++k) dst[n][k] = *(const PG8_LAS bf16x8*)(lds + PG8_SB(b, h) + boff + n * 2048 + k * 1024); } while (0)
; #define PG8_MMA(ai, bj, At, Bt) do { __builtin_amdgcn_s_setprio(1); _Pragma("unroll") for (int m = 0; m < 4; ++m) _Pragma("unroll") for (int n = 0; n < 2; ++n) _Pragma("unroll") for (int k = 0; k < 2; ++k) \
;         acc[ai][bj][m][n] = __builtin_amdgcn_mfma_f32_16x16x32_bf16(Bt[n][k], At[m][k], acc[ai][bj][m][n], 0, 0, 0); __builtin_amdgcn_s_setprio(0); } while (0)
; #define PG8_WAIT_V(n) asm volatile("s_waitcnt vmcnt(" #n ")" ::: "memory")
; #define PG8_WAIT_L(n) asm volatile("s_waitcnt lgkmcnt(" #n ")" ::: "memory")
; template <class Epi, class Sched, bool ALIGN_EPI = false, bool SP2 = false>
; __device__ __forceinline__ void gemm_phase(PG8_LAS unsigned char* lds, const Gemm g, const Sched& S, const Epi& E) {
;     ...
;             const bool last = (t == nt - 2);
;             const char* a1 = cA + (size_t)(t + 1) * kstep;
;             const char* a2 = last ? nA : cA + (size_t)(t + 2) * kstep; const char* b2 = last ? nB : cB + (size_t)(t + 2) * kstep;
;             const char* a3 = a2 + kstep; const char* b3 = b2 + kstep;
;             if (last && has_next) S.a_ready(nxt);
;             if constexpr (SP2) {
;             PG8_LDB(B0, 0, 0); PG8_LDB(B1, 0, 1); PG8_SCHED; PG8_LDA(At, 0, 0); PG8_STAGE(PG8_SA(1, 1), a1 + hstep, voffA);
;             PG8_WAIT_V(8); PG8_WAIT_L(0); PG8_BAR; PG8_MMA(0, 0, At, B0); PG8_MMA(0, 1, At, B1); PG8_BAR; PG8_SCHED;
;             PG8_LDA(At, 0, 1); PG8_STAGE(PG8_SB(0, 0), b2, voffB); PG8_STAGE(PG8_SB(0, 1), b2 + hstep, voffB); PG8_STAGE(PG8_SA(0, 0), a2, voffA);
;             PG8_WAIT_V(8); PG8_WAIT_L(0); PG8_BAR; PG8_MMA(1, 0, At, B0); PG8_MMA(1, 1, At, B1); PG8_BAR; PG8_SCHED;
.LBB0_1039:
	ds_read_b128 v[130:133], v241 offset:0
	ds_read_b128 v[134:137], v241 offset:1024
	ds_read_b128 v[138:141], v241 offset:2048
	ds_read_b128 v[142:145], v241 offset:3072
	ds_read_b128 v[146:149], v241 offset:16384
	ds_read_b128 v[150:153], v241 offset:17408
	ds_read_b128 v[172:175], v241 offset:18432
	ds_read_b128 v[176:179], v241 offset:19456
	s_add_u32 s24, s26, 0xfff00080
	s_addc_u32 s25, s27, -1
	s_cmp_eq_u32 s68, 60
	s_cselect_b32 s29, s15, s25
	s_cselect_b32 s28, s21, s24
	s_cselect_b32 s25, s13, s67
	s_cselect_b32 s24, s65, s66
	s_add_i32 m0, s23, 0xc000
	ds_read_b128 v[180:183], v185
	ds_read_b128 v[188:191], v185 offset:1024
	ds_read_b128 v[192:195], v185 offset:2048
	ds_read_b128 v[196:199], v185 offset:3072
	ds_read_b128 v[200:203], v185 offset:4096
	ds_read_b128 v[204:207], v185 offset:5120
	ds_read_b128 v[208:211], v185 offset:6144
	ds_read_b128 v[212:215], v185 offset:7168
	global_load_lds_dwordx4 v162, s[26:27]
	s_add_i32 m0, s23, 0xe000
	s_nop 0
	global_load_lds_dwordx4 v166, s[26:27]
	s_waitcnt vmcnt(8)
	s_waitcnt lgkmcnt(0)
	s_barrier
	s_waitcnt lgkmcnt(0)
	v_mfma_f32_16x16x32_bf16 v[114:117], v[130:133], v[180:183], v[114:117]
	v_mfma_f32_16x16x32_bf16 v[106:109], v[130:133], v[192:195], v[106:109]
	v_mfma_f32_16x16x32_bf16 v[90:93], v[130:133], v[200:203], v[90:93]
	v_mfma_f32_16x16x32_bf16 v[74:77], v[130:133], v[208:211], v[74:77]
	v_mfma_f32_16x16x32_bf16 v[74:77], v[134:137], v[212:215], v[74:77]
	v_mfma_f32_16x16x32_bf16 v[90:93], v[134:137], v[204:207], v[90:93]
	v_mfma_f32_16x16x32_bf16 v[106:109], v[134:137], v[196:199], v[106:109]
	v_mfma_f32_16x16x32_bf16 v[114:117], v[134:137], v[188:191], v[114:117]
	v_mfma_f32_16x16x32_bf16 v[118:121], v[142:145], v[188:191], v[118:121]
	v_mfma_f32_16x16x32_bf16 v[98:101], v[142:145], v[196:199], v[98:101]
	v_mfma_f32_16x16x32_bf16 v[82:85], v[142:145], v[204:207], v[82:85]
	v_mfma_f32_16x16x32_bf16 v[66:69], v[142:145], v[212:215], v[66:69]
	v_mfma_f32_16x16x32_bf16 v[66:69], v[138:141], v[208:211], v[66:69]
	v_mfma_f32_16x16x32_bf16 v[82:85], v[138:141], v[200:203], v[82:85]
	v_mfma_f32_16x16x32_bf16 v[98:101], v[138:141], v[192:195], v[98:101]
	v_mfma_f32_16x16x32_bf16 v[118:121], v[138:141], v[180:183], v[118:121]
	v_mfma_f32_16x16x32_bf16 v[122:125], v[146:149], v[180:183], v[122:125]
	v_mfma_f32_16x16x32_bf16 v[110:113], v[146:149], v[192:195], v[110:113]
	v_mfma_f32_16x16x32_bf16 v[94:97], v[146:149], v[200:203], v[94:97]
	v_mfma_f32_16x16x32_bf16 v[78:81], v[146:149], v[208:211], v[78:81]
	v_mfma_f32_16x16x32_bf16 v[78:81], v[150:153], v[212:215], v[78:81]
	v_mfma_f32_16x16x32_bf16 v[94:97], v[150:153], v[204:207], v[94:97]
	v_mfma_f32_16x16x32_bf16 v[110:113], v[150:153], v[196:199], v[110:113]
	v_mfma_f32_16x16x32_bf16 v[122:125], v[150:153], v[188:191], v[122:125]
	v_mfma_f32_16x16x32_bf16 v[126:129], v[176:179], v[188:191], v[126:129]
	v_mfma_f32_16x16x32_bf16 v[102:105], v[176:179], v[196:199], v[102:105]
	v_mfma_f32_16x16x32_bf16 v[86:89], v[176:179], v[204:207], v[86:89]
	v_mfma_f32_16x16x32_bf16 v[70:73], v[176:179], v[212:215], v[70:73]
	v_mfma_f32_16x16x32_bf16 v[70:73], v[172:175], v[208:211], v[70:73]
	v_mfma_f32_16x16x32_bf16 v[86:89], v[172:175], v[200:203], v[86:89]
	v_mfma_f32_16x16x32_bf16 v[102:105], v[172:175], v[192:195], v[102:105]
	v_mfma_f32_16x16x32_bf16 v[126:129], v[172:175], v[180:183], v[126:129]
	s_barrier
	s_add_i32 s33, s62, s36
	s_mov_b32 m0, s33
	ds_read_b128 v[180:183], v185 offset:16384
	ds_read_b128 v[188:191], v185 offset:17408
	ds_read_b128 v[192:195], v185 offset:18432
	ds_read_b128 v[196:199], v185 offset:19456
	ds_read_b128 v[200:203], v185 offset:20480
	ds_read_b128 v[204:207], v185 offset:21504
	ds_read_b128 v[208:211], v185 offset:22528
	ds_read_b128 v[212:215], v185 offset:23552
	global_load_lds_dwordx4 v156, s[24:25]
	s_add_i32 m0, s33, 0x2000
	s_add_u32 s72, s24, 0x100000
	s_addc_u32 s73, s25, 0
	s_add_i32 s33, s63, s36
	global_load_lds_dwordx4 v160, s[24:25]
	s_mov_b32 m0, s33
	s_add_u32 s100, s28, 0x80
	s_addc_u32 s101, s29, 0
	global_load_lds_dwordx4 v156, s[72:73]
	s_add_i32 m0, s33, 0x2000
	s_nop 0
	global_load_lds_dwordx4 v160, s[72:73]
	s_mov_b32 m0, s23
	s_nop 0
	global_load_lds_dwordx4 v154, s[28:29]
	s_mov_b32 m0, s37
	s_nop 0
	global_load_lds_dwordx4 v158, s[28:29]
	s_waitcnt vmcnt(8)
	s_waitcnt lgkmcnt(0)
	s_barrier
	s_waitcnt lgkmcnt(0)
	v_mfma_f32_16x16x32_bf16 v[58:61], v[130:133], v[180:183], v[58:61]
	v_mfma_f32_16x16x32_bf16 v[42:45], v[130:133], v[192:195], v[42:45]
	v_mfma_f32_16x16x32_bf16 v[26:29], v[130:133], v[200:203], v[26:29]
	v_mfma_f32_16x16x32_bf16 v[6:9], v[130:133], v[208:211], v[6:9]
	v_mfma_f32_16x16x32_bf16 v[6:9], v[134:137], v[212:215], v[6:9]
	v_mfma_f32_16x16x32_bf16 v[26:29], v[134:137], v[204:207], v[26:29]
	v_mfma_f32_16x16x32_bf16 v[42:45], v[134:137], v[196:199], v[42:45]
	v_mfma_f32_16x16x32_bf16 v[58:61], v[134:137], v[188:191], v[58:61]
	v_mfma_f32_16x16x32_bf16 v[54:57], v[142:145], v[188:191], v[54:57]
	v_mfma_f32_16x16x32_bf16 v[34:37], v[142:145], v[196:199], v[34:37]
	v_mfma_f32_16x16x32_bf16 v[18:21], v[142:145], v[204:207], v[18:21]
	v_mfma_f32_16x16x32_bf16 v[2:5], v[142:145], v[212:215], v[2:5]
	v_mfma_f32_16x16x32_bf16 v[2:5], v[138:141], v[208:211], v[2:5]
	v_mfma_f32_16x16x32_bf16 v[18:21], v[138:141], v[200:203], v[18:21]
	v_mfma_f32_16x16x32_bf16 v[34:37], v[138:141], v[192:195], v[34:37]
	v_mfma_f32_16x16x32_bf16 v[54:57], v[138:141], v[180:183], v[54:57]
	v_mfma_f32_16x16x32_bf16 v[62:65], v[146:149], v[180:183], v[62:65]
	v_mfma_f32_16x16x32_bf16 v[46:49], v[146:149], v[192:195], v[46:49]
	v_mfma_f32_16x16x32_bf16 v[30:33], v[146:149], v[200:203], v[30:33]
	v_mfma_f32_16x16x32_bf16 v[10:13], v[146:149], v[208:211], v[10:13]
	v_mfma_f32_16x16x32_bf16 v[10:13], v[150:153], v[212:215], v[10:13]
	v_mfma_f32_16x16x32_bf16 v[30:33], v[150:153], v[204:207], v[30:33]
	v_mfma_f32_16x16x32_bf16 v[46:49], v[150:153], v[196:199], v[46:49]
	v_mfma_f32_16x16x32_bf16 v[62:65], v[150:153], v[188:191], v[62:65]
	v_mfma_f32_16x16x32_bf16 v[50:53], v[176:179], v[188:191], v[50:53]
	v_mfma_f32_16x16x32_bf16 v[38:41], v[176:179], v[196:199], v[38:41]
	v_mfma_f32_16x16x32_bf16 v[22:25], v[176:179], v[204:207], v[22:25]
	v_mfma_f32_16x16x32_bf16 v[14:17], v[176:179], v[212:215], v[14:17]
	v_mfma_f32_16x16x32_bf16 v[14:17], v[172:175], v[208:211], v[14:17]
	v_mfma_f32_16x16x32_bf16 v[22:25], v[172:175], v[200:203], v[22:25]
	v_mfma_f32_16x16x32_bf16 v[38:41], v[172:175], v[192:195], v[38:41]
	v_mfma_f32_16x16x32_bf16 v[50:53], v[172:175], v[180:183], v[50:53]
	s_barrier
; #define PG8_STAGE(bufoff, gbase, voff) do { _Pragma("unroll") for (int _i = 0; _i < 2; ++_i) \
;         __builtin_amdgcn_global_load_lds((const unsigned*)((const char*)(gbase) + (voff)[_i]), (PG8_LAS unsigned*)(lds + (bufoff) + ldsw + _i * 8192), 16, 0, 0); } while (0)
; #define PG8_LDA(dst, b, h) do { _Pragma("unroll") for (int m = 0; m < 4; ++m) _Pragma("unroll") for (int k = 0; k < 2; ++k) dst[m][k] = *(const PG8_LAS bf16x8*)(lds + PG8_SA(b, h) + aoff + m * 2048 + k * 1024); } while (0)
; #define PG8_LDB(dst, b, h) do { _Pragma("unroll") for (int n = 0; n < 2; ++n) _Pragma("unroll") for (int k = 0; k < 2; ++k) dst[n][k] = *(const PG8_LAS bf16x8*)(lds + PG8_SB(b, h) + boff + n * 2048 + k * 1024); } while (0)
; #define PG8_MMA(ai, bj, At, Bt) do { __builtin_amdgcn_s_setprio(1); _Pragma("unroll") for (int m = 0; m < 4; ++m) _Pragma("unroll") for (int n = 0; n < 2; ++n) _Pragma("unroll") for (int k = 0; k < 2; ++k) \
;         acc[ai][bj][m][n] = __builtin_amdgcn_mfma_f32_16x16x32_bf16(Bt[n][k], At[m][k], acc[ai][bj][m][n], 0, 0, 0); __builtin_amdgcn_s_setprio(0); } while (0)
; #define PG8_WAIT_V(n) asm volatile("s_waitcnt vmcnt(" #n ")" ::: "memory")
; #define PG8_WAIT_L(n) asm volatile("s_waitcnt lgkmcnt(" #n ")" ::: "memory")
; #define PG8_BAR __builtin_amdgcn_s_barrier()
; template <class Epi, class Sched, bool ALIGN_EPI = false, bool SP2 = false>
; __device__ __forceinline__ void gemm_phase(PG8_LAS unsigned char* lds, const Gemm g, const Sched& S, const Epi& E) {
;     ...
;         for (int t = 0; t < nt; t += 2) {
;             const bool last = (t == nt - 2);
;             const char* a1 = cA + (size_t)(t + 1) * kstep;
;             const char* a2 = last ? nA : cA + (size_t)(t + 2) * kstep; const char* b2 = last ? nB : cB + (size_t)(t + 2) * kstep;
;             const char* a3 = a2 + kstep; const char* b3 = b2 + kstep;
;     ...
;             PG8_LDB(B0, 1, 0); PG8_LDB(B1, 1, 1); PG8_SCHED; PG8_LDA(At, 1, 0); PG8_STAGE(PG8_SA(0, 1), a2 + hstep, voffA);
;             PG8_WAIT_V(8); PG8_WAIT_L(0); PG8_BAR; PG8_MMA(0, 0, At, B0); PG8_MMA(0, 1, At, B1); PG8_BAR; PG8_SCHED;
;             PG8_LDA(At, 1, 1); PG8_STAGE(PG8_SB(1, 0), b3, voffB); PG8_STAGE(PG8_SB(1, 1), b3 + hstep, voffB); PG8_STAGE(PG8_SA(1, 0), a3, voffA);
;             PG8_WAIT_V(8); PG8_WAIT_L(0); PG8_BAR; PG8_MMA(1, 0, At, B0); PG8_MMA(1, 1, At, B1); PG8_BAR; PG8_SCHED;
	s_add_i32 s33, 0, 0x18000
	s_add_i32 s42, 0, 0x1c000
	ds_read_b128 v[130:133], v241 offset:32768
	ds_read_b128 v[134:137], v241 offset:33792
	ds_read_b128 v[138:141], v241 offset:34816
	ds_read_b128 v[142:145], v241 offset:35840
	ds_read_b128 v[146:149], v241 offset:49152
	ds_read_b128 v[150:153], v241 offset:50176
	ds_read_b128 v[172:175], v241 offset:51200
	ds_read_b128 v[176:179], v241 offset:52224
	s_add_u32 s28, s28, 0x100000
	s_addc_u32 s29, s29, 0
	s_mov_b32 m0, s40
	ds_read_b128 v[180:183], v185 offset:32768
	ds_read_b128 v[188:191], v185 offset:33792
	ds_read_b128 v[192:195], v185 offset:34816
	ds_read_b128 v[196:199], v185 offset:35840
	ds_read_b128 v[200:203], v185 offset:36864
	ds_read_b128 v[204:207], v185 offset:37888
	ds_read_b128 v[208:211], v185 offset:38912
	ds_read_b128 v[212:215], v185 offset:39936
	global_load_lds_dwordx4 v154, s[28:29]
	s_mov_b32 m0, s41
	s_nop 0
	global_load_lds_dwordx4 v158, s[28:29]
	s_waitcnt vmcnt(8)
	s_waitcnt lgkmcnt(0)
	s_barrier
	s_waitcnt lgkmcnt(0)
	v_mfma_f32_16x16x32_bf16 v[114:117], v[130:133], v[180:183], v[114:117]
	v_mfma_f32_16x16x32_bf16 v[106:109], v[130:133], v[192:195], v[106:109]
	v_mfma_f32_16x16x32_bf16 v[90:93], v[130:133], v[200:203], v[90:93]
	v_mfma_f32_16x16x32_bf16 v[74:77], v[130:133], v[208:211], v[74:77]
	v_mfma_f32_16x16x32_bf16 v[74:77], v[134:137], v[212:215], v[74:77]
	v_mfma_f32_16x16x32_bf16 v[90:93], v[134:137], v[204:207], v[90:93]
	v_mfma_f32_16x16x32_bf16 v[106:109], v[134:137], v[196:199], v[106:109]
	v_mfma_f32_16x16x32_bf16 v[114:117], v[134:137], v[188:191], v[114:117]
	v_mfma_f32_16x16x32_bf16 v[118:121], v[142:145], v[188:191], v[118:121]
	v_mfma_f32_16x16x32_bf16 v[98:101], v[142:145], v[196:199], v[98:101]
	v_mfma_f32_16x16x32_bf16 v[82:85], v[142:145], v[204:207], v[82:85]
	v_mfma_f32_16x16x32_bf16 v[66:69], v[142:145], v[212:215], v[66:69]
	v_mfma_f32_16x16x32_bf16 v[66:69], v[138:141], v[208:211], v[66:69]
	v_mfma_f32_16x16x32_bf16 v[82:85], v[138:141], v[200:203], v[82:85]
	v_mfma_f32_16x16x32_bf16 v[98:101], v[138:141], v[192:195], v[98:101]
	v_mfma_f32_16x16x32_bf16 v[118:121], v[138:141], v[180:183], v[118:121]
	v_mfma_f32_16x16x32_bf16 v[122:125], v[146:149], v[180:183], v[122:125]
	v_mfma_f32_16x16x32_bf16 v[110:113], v[146:149], v[192:195], v[110:113]
	v_mfma_f32_16x16x32_bf16 v[94:97], v[146:149], v[200:203], v[94:97]
	v_mfma_f32_16x16x32_bf16 v[78:81], v[146:149], v[208:211], v[78:81]
	v_mfma_f32_16x16x32_bf16 v[78:81], v[150:153], v[212:215], v[78:81]
	v_mfma_f32_16x16x32_bf16 v[94:97], v[150:153], v[204:207], v[94:97]
	v_mfma_f32_16x16x32_bf16 v[110:113], v[150:153], v[196:199], v[110:113]
	v_mfma_f32_16x16x32_bf16 v[122:125], v[150:153], v[188:191], v[122:125]
	v_mfma_f32_16x16x32_bf16 v[126:129], v[176:179], v[188:191], v[126:129]
	v_mfma_f32_16x16x32_bf16 v[102:105], v[176:179], v[196:199], v[102:105]
	v_mfma_f32_16x16x32_bf16 v[86:89], v[176:179], v[204:207], v[86:89]
	v_mfma_f32_16x16x32_bf16 v[70:73], v[176:179], v[212:215], v[70:73]
	v_mfma_f32_16x16x32_bf16 v[70:73], v[172:175], v[208:211], v[70:73]
	v_mfma_f32_16x16x32_bf16 v[86:89], v[172:175], v[200:203], v[86:89]
	v_mfma_f32_16x16x32_bf16 v[102:105], v[172:175], v[192:195], v[102:105]
	v_mfma_f32_16x16x32_bf16 v[126:129], v[172:175], v[180:183], v[126:129]
	s_barrier
	s_add_i32 s28, s33, s36
	s_add_i32 m0, s28, 0xffffff80
	ds_read_b128 v[180:183], v185 offset:49152
	ds_read_b128 v[188:191], v185 offset:50176
	ds_read_b128 v[192:195], v185 offset:51200
	ds_read_b128 v[196:199], v185 offset:52224
	ds_read_b128 v[200:203], v185 offset:53248
	ds_read_b128 v[204:207], v185 offset:54272
	ds_read_b128 v[208:211], v185 offset:55296
	ds_read_b128 v[212:215], v185 offset:56320
	global_load_lds_dwordx4 v156, s[24:25] offset:128
	s_add_i32 m0, s28, 0x1f80
	s_add_i32 s28, s42, s36
	global_load_lds_dwordx4 v160, s[24:25] offset:128
	s_add_u32 s24, s24, 0x100080
	s_addc_u32 s25, s25, 0
	s_mov_b32 m0, s28
	s_nop 0
	global_load_lds_dwordx4 v156, s[24:25]
	s_add_i32 m0, s28, 0x2000
	s_nop 0
	global_load_lds_dwordx4 v160, s[24:25]
	s_mov_b32 m0, s46
	s_nop 0
	global_load_lds_dwordx4 v154, s[100:101]
	s_mov_b32 m0, s47
	s_nop 0
	global_load_lds_dwordx4 v158, s[100:101]
	s_waitcnt vmcnt(8)
	s_waitcnt lgkmcnt(0)
	s_barrier
	s_waitcnt lgkmcnt(0)
	v_mfma_f32_16x16x32_bf16 v[58:61], v[130:133], v[180:183], v[58:61]
	v_mfma_f32_16x16x32_bf16 v[42:45], v[130:133], v[192:195], v[42:45]
	v_mfma_f32_16x16x32_bf16 v[26:29], v[130:133], v[200:203], v[26:29]
	v_mfma_f32_16x16x32_bf16 v[6:9], v[130:133], v[208:211], v[6:9]
	v_mfma_f32_16x16x32_bf16 v[6:9], v[134:137], v[212:215], v[6:9]
	v_mfma_f32_16x16x32_bf16 v[26:29], v[134:137], v[204:207], v[26:29]
	v_mfma_f32_16x16x32_bf16 v[42:45], v[134:137], v[196:199], v[42:45]
	v_mfma_f32_16x16x32_bf16 v[58:61], v[134:137], v[188:191], v[58:61]
	v_mfma_f32_16x16x32_bf16 v[54:57], v[142:145], v[188:191], v[54:57]
	v_mfma_f32_16x16x32_bf16 v[34:37], v[142:145], v[196:199], v[34:37]
	v_mfma_f32_16x16x32_bf16 v[18:21], v[142:145], v[204:207], v[18:21]
	v_mfma_f32_16x16x32_bf16 v[2:5], v[142:145], v[212:215], v[2:5]
	v_mfma_f32_16x16x32_bf16 v[2:5], v[138:141], v[208:211], v[2:5]
	v_mfma_f32_16x16x32_bf16 v[18:21], v[138:141], v[200:203], v[18:21]
	v_mfma_f32_16x16x32_bf16 v[34:37], v[138:141], v[192:195], v[34:37]
	v_mfma_f32_16x16x32_bf16 v[54:57], v[138:141], v[180:183], v[54:57]
	v_mfma_f32_16x16x32_bf16 v[62:65], v[146:149], v[180:183], v[62:65]
	v_mfma_f32_16x16x32_bf16 v[46:49], v[146:149], v[192:195], v[46:49]
	v_mfma_f32_16x16x32_bf16 v[30:33], v[146:149], v[200:203], v[30:33]
	v_mfma_f32_16x16x32_bf16 v[10:13], v[146:149], v[208:211], v[10:13]
	v_mfma_f32_16x16x32_bf16 v[10:13], v[150:153], v[212:215], v[10:13]
	v_mfma_f32_16x16x32_bf16 v[30:33], v[150:153], v[204:207], v[30:33]
	v_mfma_f32_16x16x32_bf16 v[46:49], v[150:153], v[196:199], v[46:49]
	v_mfma_f32_16x16x32_bf16 v[62:65], v[150:153], v[188:191], v[62:65]
	v_mfma_f32_16x16x32_bf16 v[50:53], v[176:179], v[188:191], v[50:53]
	v_mfma_f32_16x16x32_bf16 v[38:41], v[176:179], v[196:199], v[38:41]
	v_mfma_f32_16x16x32_bf16 v[22:25], v[176:179], v[204:207], v[22:25]
	v_mfma_f32_16x16x32_bf16 v[14:17], v[176:179], v[212:215], v[14:17]
	v_mfma_f32_16x16x32_bf16 v[14:17], v[172:175], v[208:211], v[14:17]
	v_mfma_f32_16x16x32_bf16 v[22:25], v[172:175], v[200:203], v[22:25]
	v_mfma_f32_16x16x32_bf16 v[38:41], v[172:175], v[192:195], v[38:41]
	v_mfma_f32_16x16x32_bf16 v[50:53], v[172:175], v[180:183], v[50:53]
	s_barrier
	s_add_i32 s68, s68, 2
	s_add_u32 s26, s26, 0x100
	s_addc_u32 s27, s27, 0
	s_add_u32 s66, s66, 0x100
	s_addc_u32 s67, s67, 0
	s_cmp_gt_u32 s68, 61
	s_cbranch_scc0 .LBB0_1039
	s_and_b64 vcc, exec, s[10:11]
	s_cbranch_vccz .LBB0_1042
	s_barrier

; #define PG8_STAGE(bufoff, gbase, voff) do { _Pragma("unroll") for (int _i = 0; _i < 2; ++_i) \
;         __builtin_amdgcn_global_load_lds((const unsigned*)((const char*)(gbase) + (voff)[_i]), (PG8_LAS unsigned*)(lds + (bufoff) + ldsw + _i * 8192), 16, 0, 0); } while (0)
; #define PG8_LDA(dst, b, h) do { _Pragma("unroll") for (int m = 0; m < 4; ++m) _Pragma("unroll") for (int k = 0; k < 2; ++k) dst[m][k] = *(const PG8_LAS bf16x8*)(lds + PG8_SA(b, h) + aoff + m * 2048 + k * 1024); } while (0)
; #define PG8_LDB(dst, b, h) do { _Pragma("unroll") for (int n = 0; n < 2; ++n) _Pragma("unroll") for (int k = 0; k < 2; ++k) dst[n][k] = *(const PG8_LAS bf16x8*)(lds + PG8_SB(b, h) + boff + n * 2048 + k * 1024); } while (0)
; #define PG8_MMA(ai, bj, At, Bt) do { __builtin_amdgcn_s_setprio(1); _Pragma("unroll") for (int m = 0; m < 4; ++m) _Pragma("unroll") for (int n = 0; n < 2; ++n) _Pragma("unroll") for (int k = 0; k < 2; ++k) \
;         acc[ai][bj][m][n] = __builtin_amdgcn_mfma_f32_16x16x32_bf16(Bt[n][k], At[m][k], acc[ai][bj][m][n], 0, 0, 0); __builtin_amdgcn_s_setprio(0); } while (0)
; #define PG8_WAIT_V(n) asm volatile("s_waitcnt vmcnt(" #n ")" ::: "memory")
; #define PG8_WAIT_L(n) asm volatile("s_waitcnt lgkmcnt(" #n ")" ::: "memory")
; template <class Epi, class Sched, bool ALIGN_EPI = false, bool SP2 = false>
; __device__ __forceinline__ void gemm_phase(PG8_LAS unsigned char* lds, const Gemm g, const Sched& S, const Epi& E) {
;     ...
;             const bool last = (t == nt - 2);
;             const char* a1 = cA + (size_t)(t + 1) * kstep;
;             const char* a2 = last ? nA : cA + (size_t)(t + 2) * kstep; const char* b2 = last ? nB : cB + (size_t)(t + 2) * kstep;
;             const char* a3 = a2 + kstep; const char* b3 = b2 + kstep;
;             if (last && has_next) S.a_ready(nxt);
;             if constexpr (SP2) {
;             PG8_LDB(B0, 0, 0); PG8_LDB(B1, 0, 1); PG8_SCHED; PG8_LDA(At, 0, 0); PG8_STAGE(PG8_SA(1, 1), a1 + hstep, voffA);
;             PG8_WAIT_V(8); PG8_WAIT_L(0); PG8_BAR; PG8_MMA(0, 0, At, B0); PG8_MMA(0, 1, At, B1); PG8_BAR; PG8_SCHED;
;             PG8_LDA(At, 0, 1); PG8_STAGE(PG8_SB(0, 0), b2, voffB); PG8_STAGE(PG8_SB(0, 1), b2 + hstep, voffB); PG8_STAGE(PG8_SA(0, 0), a2, voffA);
;             PG8_WAIT_V(8); PG8_WAIT_L(0); PG8_BAR; PG8_MMA(1, 0, At, B0); PG8_MMA(1, 1, At, B1); PG8_BAR; PG8_SCHED;
.LBB0_1126:
	ds_read_b128 v[160:163], v241 offset:0
	ds_read_b128 v[166:169], v241 offset:1024
	ds_read_b128 v[170:173], v241 offset:2048
	ds_read_b128 v[174:177], v241 offset:3072
	ds_read_b128 v[178:181], v241 offset:16384
	ds_read_b128 v[182:185], v241 offset:17408
	ds_read_b128 v[186:189], v241 offset:18432
	ds_read_b128 v[190:193], v241 offset:19456
	s_add_u32 s22, s24, 0xfff00080
	s_addc_u32 s23, s25, -1
	s_cmp_eq_u32 s68, 60
	s_cselect_b32 s27, s15, s23
	s_cselect_b32 s26, s64, s22
	s_cselect_b32 s23, s13, s67
	s_cselect_b32 s22, s65, s66
	s_add_i32 m0, s21, 0xc000
	ds_read_b128 v[194:197], v155
	ds_read_b128 v[198:201], v155 offset:1024
	ds_read_b128 v[202:205], v155 offset:2048
	ds_read_b128 v[206:209], v155 offset:3072
	ds_read_b128 v[210:213], v155 offset:4096
	ds_read_b128 v[214:217], v155 offset:5120
	ds_read_b128 v[218:221], v155 offset:6144
	ds_read_b128 v[222:225], v155 offset:7168
	global_load_lds_dwordx4 v138, s[24:25]
	s_add_i32 m0, s21, 0xe000
	s_nop 0
	global_load_lds_dwordx4 v140, s[24:25]
	s_waitcnt vmcnt(8)
	s_waitcnt lgkmcnt(0)
	s_barrier
	s_waitcnt lgkmcnt(0)
	v_mfma_f32_16x16x32_bf16 v[122:125], v[160:163], v[194:197], v[122:125]
	v_mfma_f32_16x16x32_bf16 v[106:109], v[160:163], v[202:205], v[106:109]
	v_mfma_f32_16x16x32_bf16 v[90:93], v[160:163], v[210:213], v[90:93]
	v_mfma_f32_16x16x32_bf16 v[74:77], v[160:163], v[218:221], v[74:77]
	v_mfma_f32_16x16x32_bf16 v[74:77], v[166:169], v[222:225], v[74:77]
	v_mfma_f32_16x16x32_bf16 v[90:93], v[166:169], v[214:217], v[90:93]
	v_mfma_f32_16x16x32_bf16 v[106:109], v[166:169], v[206:209], v[106:109]
	v_mfma_f32_16x16x32_bf16 v[122:125], v[166:169], v[198:201], v[122:125]
	v_mfma_f32_16x16x32_bf16 v[114:117], v[174:177], v[198:201], v[114:117]
	v_mfma_f32_16x16x32_bf16 v[98:101], v[174:177], v[206:209], v[98:101]
	v_mfma_f32_16x16x32_bf16 v[82:85], v[174:177], v[214:217], v[82:85]
	v_mfma_f32_16x16x32_bf16 v[62:65], v[174:177], v[222:225], v[62:65]
	v_mfma_f32_16x16x32_bf16 v[62:65], v[170:173], v[218:221], v[62:65]
	v_mfma_f32_16x16x32_bf16 v[82:85], v[170:173], v[210:213], v[82:85]
	v_mfma_f32_16x16x32_bf16 v[98:101], v[170:173], v[202:205], v[98:101]
	v_mfma_f32_16x16x32_bf16 v[114:117], v[170:173], v[194:197], v[114:117]
	v_mfma_f32_16x16x32_bf16 v[126:129], v[178:181], v[194:197], v[126:129]
	v_mfma_f32_16x16x32_bf16 v[110:113], v[178:181], v[202:205], v[110:113]
	v_mfma_f32_16x16x32_bf16 v[94:97], v[178:181], v[210:213], v[94:97]
	v_mfma_f32_16x16x32_bf16 v[78:81], v[178:181], v[218:221], v[78:81]
	v_mfma_f32_16x16x32_bf16 v[78:81], v[182:185], v[222:225], v[78:81]
	v_mfma_f32_16x16x32_bf16 v[94:97], v[182:185], v[214:217], v[94:97]
	v_mfma_f32_16x16x32_bf16 v[110:113], v[182:185], v[206:209], v[110:113]
	v_mfma_f32_16x16x32_bf16 v[126:129], v[182:185], v[198:201], v[126:129]
	v_mfma_f32_16x16x32_bf16 v[118:121], v[190:193], v[198:201], v[118:121]
	v_mfma_f32_16x16x32_bf16 v[102:105], v[190:193], v[206:209], v[102:105]
	v_mfma_f32_16x16x32_bf16 v[86:89], v[190:193], v[214:217], v[86:89]
	v_mfma_f32_16x16x32_bf16 v[70:73], v[190:193], v[222:225], v[70:73]
	v_mfma_f32_16x16x32_bf16 v[70:73], v[186:189], v[218:221], v[70:73]
	v_mfma_f32_16x16x32_bf16 v[86:89], v[186:189], v[210:213], v[86:89]
	v_mfma_f32_16x16x32_bf16 v[102:105], v[186:189], v[202:205], v[102:105]
	v_mfma_f32_16x16x32_bf16 v[118:121], v[186:189], v[194:197], v[118:121]
	s_barrier
	s_add_i32 s33, s52, s29
	s_mov_b32 m0, s33
	ds_read_b128 v[194:197], v155 offset:16384
	ds_read_b128 v[198:201], v155 offset:17408
	ds_read_b128 v[202:205], v155 offset:18432
	ds_read_b128 v[206:209], v155 offset:19456
	ds_read_b128 v[210:213], v155 offset:20480
	ds_read_b128 v[214:217], v155 offset:21504
	ds_read_b128 v[218:221], v155 offset:22528
	ds_read_b128 v[222:225], v155 offset:23552
	global_load_lds_dwordx4 v132, s[22:23]
	s_add_i32 m0, s33, 0x2000
	s_add_u32 s72, s22, 0x100000
	s_addc_u32 s73, s23, 0
	s_add_i32 s33, s53, s29
	global_load_lds_dwordx4 v136, s[22:23]
	s_mov_b32 m0, s33
	s_add_u32 s100, s26, 0x80
	s_addc_u32 s101, s27, 0
	global_load_lds_dwordx4 v132, s[72:73]
	s_add_i32 m0, s33, 0x2000
	s_nop 0
	global_load_lds_dwordx4 v136, s[72:73]
	s_mov_b32 m0, s21
	s_nop 0
	global_load_lds_dwordx4 v130, s[26:27]
	s_mov_b32 m0, s36
	s_nop 0
	global_load_lds_dwordx4 v134, s[26:27]
	s_waitcnt vmcnt(8)
	s_waitcnt lgkmcnt(0)
	s_barrier
	s_waitcnt lgkmcnt(0)
	v_mfma_f32_16x16x32_bf16 v[58:61], v[160:163], v[194:197], v[58:61]
	v_mfma_f32_16x16x32_bf16 v[42:45], v[160:163], v[202:205], v[42:45]
	v_mfma_f32_16x16x32_bf16 v[26:29], v[160:163], v[210:213], v[26:29]
	v_mfma_f32_16x16x32_bf16 v[10:13], v[160:163], v[218:221], v[10:13]
	v_mfma_f32_16x16x32_bf16 v[10:13], v[166:169], v[222:225], v[10:13]
	v_mfma_f32_16x16x32_bf16 v[26:29], v[166:169], v[214:217], v[26:29]
	v_mfma_f32_16x16x32_bf16 v[42:45], v[166:169], v[206:209], v[42:45]
	v_mfma_f32_16x16x32_bf16 v[58:61], v[166:169], v[198:201], v[58:61]
	v_mfma_f32_16x16x32_bf16 v[50:53], v[174:177], v[198:201], v[50:53]
	v_mfma_f32_16x16x32_bf16 v[34:37], v[174:177], v[206:209], v[34:37]
	v_mfma_f32_16x16x32_bf16 v[18:21], v[174:177], v[214:217], v[18:21]
	v_mfma_f32_16x16x32_bf16 v[2:5], v[174:177], v[222:225], v[2:5]
	v_mfma_f32_16x16x32_bf16 v[2:5], v[170:173], v[218:221], v[2:5]
	v_mfma_f32_16x16x32_bf16 v[18:21], v[170:173], v[210:213], v[18:21]
	v_mfma_f32_16x16x32_bf16 v[34:37], v[170:173], v[202:205], v[34:37]
	v_mfma_f32_16x16x32_bf16 v[50:53], v[170:173], v[194:197], v[50:53]
	v_mfma_f32_16x16x32_bf16 v[66:69], v[178:181], v[194:197], v[66:69]
	v_mfma_f32_16x16x32_bf16 v[46:49], v[178:181], v[202:205], v[46:49]
	v_mfma_f32_16x16x32_bf16 v[30:33], v[178:181], v[210:213], v[30:33]
	v_mfma_f32_16x16x32_bf16 v[14:17], v[178:181], v[218:221], v[14:17]
	v_mfma_f32_16x16x32_bf16 v[14:17], v[182:185], v[222:225], v[14:17]
	v_mfma_f32_16x16x32_bf16 v[30:33], v[182:185], v[214:217], v[30:33]
	v_mfma_f32_16x16x32_bf16 v[46:49], v[182:185], v[206:209], v[46:49]
	v_mfma_f32_16x16x32_bf16 v[66:69], v[182:185], v[198:201], v[66:69]
	v_mfma_f32_16x16x32_bf16 v[54:57], v[190:193], v[198:201], v[54:57]
	v_mfma_f32_16x16x32_bf16 v[38:41], v[190:193], v[206:209], v[38:41]
	v_mfma_f32_16x16x32_bf16 v[22:25], v[190:193], v[214:217], v[22:25]
	v_mfma_f32_16x16x32_bf16 v[6:9], v[190:193], v[222:225], v[6:9]
	v_mfma_f32_16x16x32_bf16 v[6:9], v[186:189], v[218:221], v[6:9]
	v_mfma_f32_16x16x32_bf16 v[22:25], v[186:189], v[210:213], v[22:25]
	v_mfma_f32_16x16x32_bf16 v[38:41], v[186:189], v[202:205], v[38:41]
	v_mfma_f32_16x16x32_bf16 v[54:57], v[186:189], v[194:197], v[54:57]
	s_barrier
; #define PG8_STAGE(bufoff, gbase, voff) do { _Pragma("unroll") for (int _i = 0; _i < 2; ++_i) \
;         __builtin_amdgcn_global_load_lds((const unsigned*)((const char*)(gbase) + (voff)[_i]), (PG8_LAS unsigned*)(lds + (bufoff) + ldsw + _i * 8192), 16, 0, 0); } while (0)
; #define PG8_LDA(dst, b, h) do { _Pragma("unroll") for (int m = 0; m < 4; ++m) _Pragma("unroll") for (int k = 0; k < 2; ++k) dst[m][k] = *(const PG8_LAS bf16x8*)(lds + PG8_SA(b, h) + aoff + m * 2048 + k * 1024); } while (0)
; #define PG8_LDB(dst, b, h) do { _Pragma("unroll") for (int n = 0; n < 2; ++n) _Pragma("unroll") for (int k = 0; k < 2; ++k) dst[n][k] = *(const PG8_LAS bf16x8*)(lds + PG8_SB(b, h) + boff + n * 2048 + k * 1024); } while (0)
; #define PG8_MMA(ai, bj, At, Bt) do { __builtin_amdgcn_s_setprio(1); _Pragma("unroll") for (int m = 0; m < 4; ++m) _Pragma("unroll") for (int n = 0; n < 2; ++n) _Pragma("unroll") for (int k = 0; k < 2; ++k) \
;         acc[ai][bj][m][n] = __builtin_amdgcn_mfma_f32_16x16x32_bf16(Bt[n][k], At[m][k], acc[ai][bj][m][n], 0, 0, 0); __builtin_amdgcn_s_setprio(0); } while (0)
; #define PG8_WAIT_V(n) asm volatile("s_waitcnt vmcnt(" #n ")" ::: "memory")
; #define PG8_WAIT_L(n) asm volatile("s_waitcnt lgkmcnt(" #n ")" ::: "memory")
; #define PG8_BAR __builtin_amdgcn_s_barrier()
; template <class Epi, class Sched, bool ALIGN_EPI = false, bool SP2 = false>
; __device__ __forceinline__ void gemm_phase(PG8_LAS unsigned char* lds, const Gemm g, const Sched& S, const Epi& E) {
;     ...
;         for (int t = 0; t < nt; t += 2) {
;             const bool last = (t == nt - 2);
;             const char* a1 = cA + (size_t)(t + 1) * kstep;
;             const char* a2 = last ? nA : cA + (size_t)(t + 2) * kstep; const char* b2 = last ? nB : cB + (size_t)(t + 2) * kstep;
;             const char* a3 = a2 + kstep; const char* b3 = b2 + kstep;
;     ...
;             PG8_LDB(B0, 1, 0); PG8_LDB(B1, 1, 1); PG8_SCHED; PG8_LDA(At, 1, 0); PG8_STAGE(PG8_SA(0, 1), a2 + hstep, voffA);
;             PG8_WAIT_V(8); PG8_WAIT_L(0); PG8_BAR; PG8_MMA(0, 0, At, B0); PG8_MMA(0, 1, At, B1); PG8_BAR; PG8_SCHED;
;             PG8_LDA(At, 1, 1); PG8_STAGE(PG8_SB(1, 0), b3, voffB); PG8_STAGE(PG8_SB(1, 1), b3 + hstep, voffB); PG8_STAGE(PG8_SA(1, 0), a3, voffA);
;             PG8_WAIT_V(8); PG8_WAIT_L(0); PG8_BAR; PG8_MMA(1, 0, At, B0); PG8_MMA(1, 1, At, B1); PG8_BAR; PG8_SCHED;
	s_add_i32 s33, 0, 0x18000
	s_add_i32 s42, 0, 0x1c000
	ds_read_b128 v[160:163], v241 offset:32768
	ds_read_b128 v[166:169], v241 offset:33792
	ds_read_b128 v[170:173], v241 offset:34816
	ds_read_b128 v[174:177], v241 offset:35840
	ds_read_b128 v[178:181], v241 offset:49152
	ds_read_b128 v[182:185], v241 offset:50176
	ds_read_b128 v[186:189], v241 offset:51200
	ds_read_b128 v[190:193], v241 offset:52224
	s_add_u32 s26, s26, 0x100000
	s_addc_u32 s27, s27, 0
	s_mov_b32 m0, s37
	ds_read_b128 v[194:197], v155 offset:32768
	ds_read_b128 v[198:201], v155 offset:33792
	ds_read_b128 v[202:205], v155 offset:34816
	ds_read_b128 v[206:209], v155 offset:35840
	ds_read_b128 v[210:213], v155 offset:36864
	ds_read_b128 v[214:217], v155 offset:37888
	ds_read_b128 v[218:221], v155 offset:38912
	ds_read_b128 v[222:225], v155 offset:39936
	global_load_lds_dwordx4 v130, s[26:27]
	s_mov_b32 m0, s40
	s_nop 0
	global_load_lds_dwordx4 v134, s[26:27]
	s_waitcnt vmcnt(8)
	s_waitcnt lgkmcnt(0)
	s_barrier
	s_waitcnt lgkmcnt(0)
	v_mfma_f32_16x16x32_bf16 v[122:125], v[160:163], v[194:197], v[122:125]
	v_mfma_f32_16x16x32_bf16 v[106:109], v[160:163], v[202:205], v[106:109]
	v_mfma_f32_16x16x32_bf16 v[90:93], v[160:163], v[210:213], v[90:93]
	v_mfma_f32_16x16x32_bf16 v[74:77], v[160:163], v[218:221], v[74:77]
	v_mfma_f32_16x16x32_bf16 v[74:77], v[166:169], v[222:225], v[74:77]
	v_mfma_f32_16x16x32_bf16 v[90:93], v[166:169], v[214:217], v[90:93]
	v_mfma_f32_16x16x32_bf16 v[106:109], v[166:169], v[206:209], v[106:109]
	v_mfma_f32_16x16x32_bf16 v[122:125], v[166:169], v[198:201], v[122:125]
	v_mfma_f32_16x16x32_bf16 v[114:117], v[174:177], v[198:201], v[114:117]
	v_mfma_f32_16x16x32_bf16 v[98:101], v[174:177], v[206:209], v[98:101]
	v_mfma_f32_16x16x32_bf16 v[82:85], v[174:177], v[214:217], v[82:85]
	v_mfma_f32_16x16x32_bf16 v[62:65], v[174:177], v[222:225], v[62:65]
	v_mfma_f32_16x16x32_bf16 v[62:65], v[170:173], v[218:221], v[62:65]
	v_mfma_f32_16x16x32_bf16 v[82:85], v[170:173], v[210:213], v[82:85]
	v_mfma_f32_16x16x32_bf16 v[98:101], v[170:173], v[202:205], v[98:101]
	v_mfma_f32_16x16x32_bf16 v[114:117], v[170:173], v[194:197], v[114:117]
	v_mfma_f32_16x16x32_bf16 v[126:129], v[178:181], v[194:197], v[126:129]
	v_mfma_f32_16x16x32_bf16 v[110:113], v[178:181], v[202:205], v[110:113]
	v_mfma_f32_16x16x32_bf16 v[94:97], v[178:181], v[210:213], v[94:97]
	v_mfma_f32_16x16x32_bf16 v[78:81], v[178:181], v[218:221], v[78:81]
	v_mfma_f32_16x16x32_bf16 v[78:81], v[182:185], v[222:225], v[78:81]
	v_mfma_f32_16x16x32_bf16 v[94:97], v[182:185], v[214:217], v[94:97]
	v_mfma_f32_16x16x32_bf16 v[110:113], v[182:185], v[206:209], v[110:113]
	v_mfma_f32_16x16x32_bf16 v[126:129], v[182:185], v[198:201], v[126:129]
	v_mfma_f32_16x16x32_bf16 v[118:121], v[190:193], v[198:201], v[118:121]
	v_mfma_f32_16x16x32_bf16 v[102:105], v[190:193], v[206:209], v[102:105]
	v_mfma_f32_16x16x32_bf16 v[86:89], v[190:193], v[214:217], v[86:89]
	v_mfma_f32_16x16x32_bf16 v[70:73], v[190:193], v[222:225], v[70:73]
	v_mfma_f32_16x16x32_bf16 v[70:73], v[186:189], v[218:221], v[70:73]
	v_mfma_f32_16x16x32_bf16 v[86:89], v[186:189], v[210:213], v[86:89]
	v_mfma_f32_16x16x32_bf16 v[102:105], v[186:189], v[202:205], v[102:105]
	v_mfma_f32_16x16x32_bf16 v[118:121], v[186:189], v[194:197], v[118:121]
	s_barrier
	s_add_i32 s26, s33, s29
	s_add_i32 m0, s26, 0xffffff80
	ds_read_b128 v[194:197], v155 offset:49152
	ds_read_b128 v[198:201], v155 offset:50176
	ds_read_b128 v[202:205], v155 offset:51200
	ds_read_b128 v[206:209], v155 offset:52224
	ds_read_b128 v[210:213], v155 offset:53248
	ds_read_b128 v[214:217], v155 offset:54272
	ds_read_b128 v[218:221], v155 offset:55296
	ds_read_b128 v[222:225], v155 offset:56320
	global_load_lds_dwordx4 v132, s[22:23] offset:128
	s_add_i32 m0, s26, 0x1f80
	s_add_i32 s26, s42, s29
	global_load_lds_dwordx4 v136, s[22:23] offset:128
	s_add_u32 s22, s22, 0x100080
	s_addc_u32 s23, s23, 0
	s_mov_b32 m0, s26
	s_nop 0
	global_load_lds_dwordx4 v132, s[22:23]
	s_add_i32 m0, s26, 0x2000
	s_nop 0
	global_load_lds_dwordx4 v136, s[22:23]
	s_mov_b32 m0, s46
	s_nop 0
	global_load_lds_dwordx4 v130, s[100:101]
	s_mov_b32 m0, s47
	s_nop 0
	global_load_lds_dwordx4 v134, s[100:101]
	s_waitcnt vmcnt(8)
	s_waitcnt lgkmcnt(0)
	s_barrier
	s_waitcnt lgkmcnt(0)
	v_mfma_f32_16x16x32_bf16 v[58:61], v[160:163], v[194:197], v[58:61]
	v_mfma_f32_16x16x32_bf16 v[42:45], v[160:163], v[202:205], v[42:45]
	v_mfma_f32_16x16x32_bf16 v[26:29], v[160:163], v[210:213], v[26:29]
	v_mfma_f32_16x16x32_bf16 v[10:13], v[160:163], v[218:221], v[10:13]
	v_mfma_f32_16x16x32_bf16 v[10:13], v[166:169], v[222:225], v[10:13]
	v_mfma_f32_16x16x32_bf16 v[26:29], v[166:169], v[214:217], v[26:29]
	v_mfma_f32_16x16x32_bf16 v[42:45], v[166:169], v[206:209], v[42:45]
	v_mfma_f32_16x16x32_bf16 v[58:61], v[166:169], v[198:201], v[58:61]
	v_mfma_f32_16x16x32_bf16 v[50:53], v[174:177], v[198:201], v[50:53]
	v_mfma_f32_16x16x32_bf16 v[34:37], v[174:177], v[206:209], v[34:37]
	v_mfma_f32_16x16x32_bf16 v[18:21], v[174:177], v[214:217], v[18:21]
	v_mfma_f32_16x16x32_bf16 v[2:5], v[174:177], v[222:225], v[2:5]
	v_mfma_f32_16x16x32_bf16 v[2:5], v[170:173], v[218:221], v[2:5]
	v_mfma_f32_16x16x32_bf16 v[18:21], v[170:173], v[210:213], v[18:21]
	v_mfma_f32_16x16x32_bf16 v[34:37], v[170:173], v[202:205], v[34:37]
	v_mfma_f32_16x16x32_bf16 v[50:53], v[170:173], v[194:197], v[50:53]
	v_mfma_f32_16x16x32_bf16 v[66:69], v[178:181], v[194:197], v[66:69]
	v_mfma_f32_16x16x32_bf16 v[46:49], v[178:181], v[202:205], v[46:49]
	v_mfma_f32_16x16x32_bf16 v[30:33], v[178:181], v[210:213], v[30:33]
	v_mfma_f32_16x16x32_bf16 v[14:17], v[178:181], v[218:221], v[14:17]
	v_mfma_f32_16x16x32_bf16 v[14:17], v[182:185], v[222:225], v[14:17]
	v_mfma_f32_16x16x32_bf16 v[30:33], v[182:185], v[214:217], v[30:33]
	v_mfma_f32_16x16x32_bf16 v[46:49], v[182:185], v[206:209], v[46:49]
	v_mfma_f32_16x16x32_bf16 v[66:69], v[182:185], v[198:201], v[66:69]
	v_mfma_f32_16x16x32_bf16 v[54:57], v[190:193], v[198:201], v[54:57]
	v_mfma_f32_16x16x32_bf16 v[38:41], v[190:193], v[206:209], v[38:41]
	v_mfma_f32_16x16x32_bf16 v[22:25], v[190:193], v[214:217], v[22:25]
	v_mfma_f32_16x16x32_bf16 v[6:9], v[190:193], v[222:225], v[6:9]
	v_mfma_f32_16x16x32_bf16 v[6:9], v[186:189], v[218:221], v[6:9]
	v_mfma_f32_16x16x32_bf16 v[22:25], v[186:189], v[210:213], v[22:25]
	v_mfma_f32_16x16x32_bf16 v[38:41], v[186:189], v[202:205], v[38:41]
	v_mfma_f32_16x16x32_bf16 v[54:57], v[186:189], v[194:197], v[54:57]
	s_barrier
	s_add_i32 s68, s68, 2
	s_add_u32 s24, s24, 0x100
	s_addc_u32 s25, s25, 0
	s_add_u32 s66, s66, 0x100
	s_addc_u32 s67, s67, 0
	s_cmp_gt_u32 s68, 61
	s_cbranch_scc0 .LBB0_1126
	s_and_b64 vcc, exec, s[8:9]
	s_cbranch_vccz .LBB0_1129
	s_barrier

; #define PG8_STAGE(bufoff, gbase, voff) do { _Pragma("unroll") for (int _i = 0; _i < 2; ++_i) \
;         __builtin_amdgcn_global_load_lds((const unsigned*)((const char*)(gbase) + (voff)[_i]), (PG8_LAS unsigned*)(lds + (bufoff) + ldsw + _i * 8192), 16, 0, 0); } while (0)
; #define PG8_LDA(dst, b, h) do { _Pragma("unroll") for (int m = 0; m < 4; ++m) _Pragma("unroll") for (int k = 0; k < 2; ++k) dst[m][k] = *(const PG8_LAS bf16x8*)(lds + PG8_SA(b, h) + aoff + m * 2048 + k * 1024); } while (0)
; #define PG8_LDB(dst, b, h) do { _Pragma("unroll") for (int n = 0; n < 2; ++n) _Pragma("unroll") for (int k = 0; k < 2; ++k) dst[n][k] = *(const PG8_LAS bf16x8*)(lds + PG8_SB(b, h) + boff + n * 2048 + k * 1024); } while (0)
; #define PG8_MMA(ai, bj, At, Bt) do { __builtin_amdgcn_s_setprio(1); _Pragma("unroll") for (int m = 0; m < 4; ++m) _Pragma("unroll") for (int n = 0; n < 2; ++n) _Pragma("unroll") for (int k = 0; k < 2; ++k) \
;         acc[ai][bj][m][n] = __builtin_amdgcn_mfma_f32_16x16x32_bf16(Bt[n][k], At[m][k], acc[ai][bj][m][n], 0, 0, 0); __builtin_amdgcn_s_setprio(0); } while (0)
; #define PG8_WAIT_V(n) asm volatile("s_waitcnt vmcnt(" #n ")" ::: "memory")
; #define PG8_WAIT_L(n) asm volatile("s_waitcnt lgkmcnt(" #n ")" ::: "memory")
; template <class Epi, class Sched, bool ALIGN_EPI = false, bool SP2 = false>
; __device__ __forceinline__ void gemm_phase(PG8_LAS unsigned char* lds, const Gemm g, const Sched& S, const Epi& E) {
;     ...
;             const bool last = (t == nt - 2);
;             const char* a1 = cA + (size_t)(t + 1) * kstep;
;             const char* a2 = last ? nA : cA + (size_t)(t + 2) * kstep; const char* b2 = last ? nB : cB + (size_t)(t + 2) * kstep;
;             const char* a3 = a2 + kstep; const char* b3 = b2 + kstep;
;             if (last && has_next) S.a_ready(nxt);
;             if constexpr (SP2) {
;             PG8_LDB(B0, 0, 0); PG8_LDB(B1, 0, 1); PG8_SCHED; PG8_LDA(At, 0, 0); PG8_STAGE(PG8_SA(1, 1), a1 + hstep, voffA);
;             PG8_WAIT_V(8); PG8_WAIT_L(0); PG8_BAR; PG8_MMA(0, 0, At, B0); PG8_MMA(0, 1, At, B1); PG8_BAR; PG8_SCHED;
;             PG8_LDA(At, 0, 1); PG8_STAGE(PG8_SB(0, 0), b2, voffB); PG8_STAGE(PG8_SB(0, 1), b2 + hstep, voffB); PG8_STAGE(PG8_SA(0, 0), a2, voffA);
;             PG8_WAIT_V(8); PG8_WAIT_L(0); PG8_BAR; PG8_MMA(1, 0, At, B0); PG8_MMA(1, 1, At, B1); PG8_BAR; PG8_SCHED;
.LBB0_1245:
	ds_read_b128 v[130:133], v241 offset:0
	ds_read_b128 v[134:137], v241 offset:1024
	ds_read_b128 v[138:141], v241 offset:2048
	ds_read_b128 v[142:145], v241 offset:3072
	ds_read_b128 v[146:149], v241 offset:16384
	ds_read_b128 v[150:153], v241 offset:17408
	ds_read_b128 v[172:175], v241 offset:18432
	ds_read_b128 v[176:179], v241 offset:19456
	s_add_u32 s16, s18, 0xffd50080
	s_addc_u32 s17, s19, -1
	s_cmpk_eq_i32 s64, 0xa8
	s_cselect_b32 s21, s5, s17
	s_cselect_b32 s20, s4, s16
	s_cselect_b32 s17, s15, s63
	s_cselect_b32 s16, s14, s62
	s_add_i32 m0, s25, 0xc000
	ds_read_b128 v[180:183], v185
	ds_read_b128 v[188:191], v185 offset:1024
	ds_read_b128 v[192:195], v185 offset:2048
	ds_read_b128 v[196:199], v185 offset:3072
	ds_read_b128 v[200:203], v185 offset:4096
	ds_read_b128 v[204:207], v185 offset:5120
	ds_read_b128 v[208:211], v185 offset:6144
	ds_read_b128 v[212:215], v185 offset:7168
	global_load_lds_dwordx4 v162, s[18:19]
	s_add_i32 m0, s25, 0xe000
	s_nop 0
	global_load_lds_dwordx4 v166, s[18:19]
	s_waitcnt vmcnt(8)
	s_waitcnt lgkmcnt(0)
	s_barrier
	s_waitcnt lgkmcnt(0)
	v_mfma_f32_16x16x32_bf16 v[114:117], v[130:133], v[180:183], v[114:117]
	v_mfma_f32_16x16x32_bf16 v[106:109], v[130:133], v[192:195], v[106:109]
	v_mfma_f32_16x16x32_bf16 v[90:93], v[130:133], v[200:203], v[90:93]
	v_mfma_f32_16x16x32_bf16 v[74:77], v[130:133], v[208:211], v[74:77]
	v_mfma_f32_16x16x32_bf16 v[74:77], v[134:137], v[212:215], v[74:77]
	v_mfma_f32_16x16x32_bf16 v[90:93], v[134:137], v[204:207], v[90:93]
	v_mfma_f32_16x16x32_bf16 v[106:109], v[134:137], v[196:199], v[106:109]
	v_mfma_f32_16x16x32_bf16 v[114:117], v[134:137], v[188:191], v[114:117]
	v_mfma_f32_16x16x32_bf16 v[118:121], v[142:145], v[188:191], v[118:121]
	v_mfma_f32_16x16x32_bf16 v[98:101], v[142:145], v[196:199], v[98:101]
	v_mfma_f32_16x16x32_bf16 v[82:85], v[142:145], v[204:207], v[82:85]
	v_mfma_f32_16x16x32_bf16 v[66:69], v[142:145], v[212:215], v[66:69]
	v_mfma_f32_16x16x32_bf16 v[66:69], v[138:141], v[208:211], v[66:69]
	v_mfma_f32_16x16x32_bf16 v[82:85], v[138:141], v[200:203], v[82:85]
	v_mfma_f32_16x16x32_bf16 v[98:101], v[138:141], v[192:195], v[98:101]
	v_mfma_f32_16x16x32_bf16 v[118:121], v[138:141], v[180:183], v[118:121]
	v_mfma_f32_16x16x32_bf16 v[122:125], v[146:149], v[180:183], v[122:125]
	v_mfma_f32_16x16x32_bf16 v[110:113], v[146:149], v[192:195], v[110:113]
	v_mfma_f32_16x16x32_bf16 v[94:97], v[146:149], v[200:203], v[94:97]
	v_mfma_f32_16x16x32_bf16 v[78:81], v[146:149], v[208:211], v[78:81]
	v_mfma_f32_16x16x32_bf16 v[78:81], v[150:153], v[212:215], v[78:81]
	v_mfma_f32_16x16x32_bf16 v[94:97], v[150:153], v[204:207], v[94:97]
	v_mfma_f32_16x16x32_bf16 v[110:113], v[150:153], v[196:199], v[110:113]
	v_mfma_f32_16x16x32_bf16 v[122:125], v[150:153], v[188:191], v[122:125]
	v_mfma_f32_16x16x32_bf16 v[126:129], v[176:179], v[188:191], v[126:129]
	v_mfma_f32_16x16x32_bf16 v[102:105], v[176:179], v[196:199], v[102:105]
	v_mfma_f32_16x16x32_bf16 v[86:89], v[176:179], v[204:207], v[86:89]
	v_mfma_f32_16x16x32_bf16 v[70:73], v[176:179], v[212:215], v[70:73]
	v_mfma_f32_16x16x32_bf16 v[70:73], v[172:175], v[208:211], v[70:73]
	v_mfma_f32_16x16x32_bf16 v[86:89], v[172:175], v[200:203], v[86:89]
	v_mfma_f32_16x16x32_bf16 v[102:105], v[172:175], v[192:195], v[102:105]
	v_mfma_f32_16x16x32_bf16 v[126:129], v[172:175], v[180:183], v[126:129]
	s_barrier
	s_add_i32 s33, s40, s24
	s_mov_b32 m0, s33
	ds_read_b128 v[180:183], v185 offset:16384
	ds_read_b128 v[188:191], v185 offset:17408
	ds_read_b128 v[192:195], v185 offset:18432
	ds_read_b128 v[196:199], v185 offset:19456
	ds_read_b128 v[200:203], v185 offset:20480
	ds_read_b128 v[204:207], v185 offset:21504
	ds_read_b128 v[208:211], v185 offset:22528
	ds_read_b128 v[212:215], v185 offset:23552
	global_load_lds_dwordx4 v156, s[16:17]
	s_add_i32 m0, s33, 0x2000
	s_add_u32 s66, s16, 0x2b0000
	s_addc_u32 s67, s17, 0
	s_add_i32 s33, s41, s24
	global_load_lds_dwordx4 v160, s[16:17]
	s_mov_b32 m0, s33
	s_add_u32 s100, s20, 0x80
	s_addc_u32 s101, s21, 0
	global_load_lds_dwordx4 v156, s[66:67]
	s_add_i32 m0, s33, 0x2000
	s_nop 0
	global_load_lds_dwordx4 v160, s[66:67]
	s_mov_b32 m0, s25
	s_nop 0
	global_load_lds_dwordx4 v154, s[20:21]
	s_mov_b32 m0, s26
	s_nop 0
	global_load_lds_dwordx4 v158, s[20:21]
	s_waitcnt vmcnt(8)
	s_waitcnt lgkmcnt(0)
	s_barrier
	s_waitcnt lgkmcnt(0)
	v_mfma_f32_16x16x32_bf16 v[58:61], v[130:133], v[180:183], v[58:61]
	v_mfma_f32_16x16x32_bf16 v[42:45], v[130:133], v[192:195], v[42:45]
	v_mfma_f32_16x16x32_bf16 v[26:29], v[130:133], v[200:203], v[26:29]
	v_mfma_f32_16x16x32_bf16 v[6:9], v[130:133], v[208:211], v[6:9]
	v_mfma_f32_16x16x32_bf16 v[6:9], v[134:137], v[212:215], v[6:9]
	v_mfma_f32_16x16x32_bf16 v[26:29], v[134:137], v[204:207], v[26:29]
	v_mfma_f32_16x16x32_bf16 v[42:45], v[134:137], v[196:199], v[42:45]
	v_mfma_f32_16x16x32_bf16 v[58:61], v[134:137], v[188:191], v[58:61]
	v_mfma_f32_16x16x32_bf16 v[54:57], v[142:145], v[188:191], v[54:57]
	v_mfma_f32_16x16x32_bf16 v[34:37], v[142:145], v[196:199], v[34:37]
	v_mfma_f32_16x16x32_bf16 v[18:21], v[142:145], v[204:207], v[18:21]
	v_mfma_f32_16x16x32_bf16 v[2:5], v[142:145], v[212:215], v[2:5]
	v_mfma_f32_16x16x32_bf16 v[2:5], v[138:141], v[208:211], v[2:5]
	v_mfma_f32_16x16x32_bf16 v[18:21], v[138:141], v[200:203], v[18:21]
	v_mfma_f32_16x16x32_bf16 v[34:37], v[138:141], v[192:195], v[34:37]
	v_mfma_f32_16x16x32_bf16 v[54:57], v[138:141], v[180:183], v[54:57]
	v_mfma_f32_16x16x32_bf16 v[62:65], v[146:149], v[180:183], v[62:65]
	v_mfma_f32_16x16x32_bf16 v[46:49], v[146:149], v[192:195], v[46:49]
	v_mfma_f32_16x16x32_bf16 v[30:33], v[146:149], v[200:203], v[30:33]
	v_mfma_f32_16x16x32_bf16 v[10:13], v[146:149], v[208:211], v[10:13]
	v_mfma_f32_16x16x32_bf16 v[10:13], v[150:153], v[212:215], v[10:13]
	v_mfma_f32_16x16x32_bf16 v[30:33], v[150:153], v[204:207], v[30:33]
	v_mfma_f32_16x16x32_bf16 v[46:49], v[150:153], v[196:199], v[46:49]
	v_mfma_f32_16x16x32_bf16 v[62:65], v[150:153], v[188:191], v[62:65]
	v_mfma_f32_16x16x32_bf16 v[50:53], v[176:179], v[188:191], v[50:53]
	v_mfma_f32_16x16x32_bf16 v[38:41], v[176:179], v[196:199], v[38:41]
	v_mfma_f32_16x16x32_bf16 v[22:25], v[176:179], v[204:207], v[22:25]
	v_mfma_f32_16x16x32_bf16 v[14:17], v[176:179], v[212:215], v[14:17]
	v_mfma_f32_16x16x32_bf16 v[14:17], v[172:175], v[208:211], v[14:17]
	v_mfma_f32_16x16x32_bf16 v[22:25], v[172:175], v[200:203], v[22:25]
	v_mfma_f32_16x16x32_bf16 v[38:41], v[172:175], v[192:195], v[38:41]
	v_mfma_f32_16x16x32_bf16 v[50:53], v[172:175], v[180:183], v[50:53]
	s_barrier
; #define PG8_STAGE(bufoff, gbase, voff) do { _Pragma("unroll") for (int _i = 0; _i < 2; ++_i) \
;         __builtin_amdgcn_global_load_lds((const unsigned*)((const char*)(gbase) + (voff)[_i]), (PG8_LAS unsigned*)(lds + (bufoff) + ldsw + _i * 8192), 16, 0, 0); } while (0)
; #define PG8_LDA(dst, b, h) do { _Pragma("unroll") for (int m = 0; m < 4; ++m) _Pragma("unroll") for (int k = 0; k < 2; ++k) dst[m][k] = *(const PG8_LAS bf16x8*)(lds + PG8_SA(b, h) + aoff + m * 2048 + k * 1024); } while (0)
; #define PG8_LDB(dst, b, h) do { _Pragma("unroll") for (int n = 0; n < 2; ++n) _Pragma("unroll") for (int k = 0; k < 2; ++k) dst[n][k] = *(const PG8_LAS bf16x8*)(lds + PG8_SB(b, h) + boff + n * 2048 + k * 1024); } while (0)
; #define PG8_MMA(ai, bj, At, Bt) do { __builtin_amdgcn_s_setprio(1); _Pragma("unroll") for (int m = 0; m < 4; ++m) _Pragma("unroll") for (int n = 0; n < 2; ++n) _Pragma("unroll") for (int k = 0; k < 2; ++k) \
;         acc[ai][bj][m][n] = __builtin_amdgcn_mfma_f32_16x16x32_bf16(Bt[n][k], At[m][k], acc[ai][bj][m][n], 0, 0, 0); __builtin_amdgcn_s_setprio(0); } while (0)
; #define PG8_WAIT_V(n) asm volatile("s_waitcnt vmcnt(" #n ")" ::: "memory")
; #define PG8_WAIT_L(n) asm volatile("s_waitcnt lgkmcnt(" #n ")" ::: "memory")
; #define PG8_BAR __builtin_amdgcn_s_barrier()
; template <class Epi, class Sched, bool ALIGN_EPI = false, bool SP2 = false>
; __device__ __forceinline__ void gemm_phase(PG8_LAS unsigned char* lds, const Gemm g, const Sched& S, const Epi& E) {
;     ...
;         for (int t = 0; t < nt; t += 2) {
;             const bool last = (t == nt - 2);
;             const char* a1 = cA + (size_t)(t + 1) * kstep;
;             const char* a2 = last ? nA : cA + (size_t)(t + 2) * kstep; const char* b2 = last ? nB : cB + (size_t)(t + 2) * kstep;
;             const char* a3 = a2 + kstep; const char* b3 = b2 + kstep;
;     ...
;             PG8_LDB(B0, 1, 0); PG8_LDB(B1, 1, 1); PG8_SCHED; PG8_LDA(At, 1, 0); PG8_STAGE(PG8_SA(0, 1), a2 + hstep, voffA);
;             PG8_WAIT_V(8); PG8_WAIT_L(0); PG8_BAR; PG8_MMA(0, 0, At, B0); PG8_MMA(0, 1, At, B1); PG8_BAR; PG8_SCHED;
;             PG8_LDA(At, 1, 1); PG8_STAGE(PG8_SB(1, 0), b3, voffB); PG8_STAGE(PG8_SB(1, 1), b3 + hstep, voffB); PG8_STAGE(PG8_SA(1, 0), a3, voffA);
;             PG8_WAIT_V(8); PG8_WAIT_L(0); PG8_BAR; PG8_MMA(1, 0, At, B0); PG8_MMA(1, 1, At, B1); PG8_BAR; PG8_SCHED;
	s_add_i32 s33, 0, 0x18000
	s_add_i32 s42, 0, 0x1c000
	ds_read_b128 v[130:133], v241 offset:32768
	ds_read_b128 v[134:137], v241 offset:33792
	ds_read_b128 v[138:141], v241 offset:34816
	ds_read_b128 v[142:145], v241 offset:35840
	ds_read_b128 v[146:149], v241 offset:49152
	ds_read_b128 v[150:153], v241 offset:50176
	ds_read_b128 v[172:175], v241 offset:51200
	ds_read_b128 v[176:179], v241 offset:52224
	s_add_u32 s20, s20, 0x2b0000
	s_addc_u32 s21, s21, 0
	s_mov_b32 m0, s27
	ds_read_b128 v[180:183], v185 offset:32768
	ds_read_b128 v[188:191], v185 offset:33792
	ds_read_b128 v[192:195], v185 offset:34816
	ds_read_b128 v[196:199], v185 offset:35840
	ds_read_b128 v[200:203], v185 offset:36864
	ds_read_b128 v[204:207], v185 offset:37888
	ds_read_b128 v[208:211], v185 offset:38912
	ds_read_b128 v[212:215], v185 offset:39936
	global_load_lds_dwordx4 v154, s[20:21]
	s_mov_b32 m0, s28
	s_nop 0
	global_load_lds_dwordx4 v158, s[20:21]
	s_waitcnt vmcnt(8)
	s_waitcnt lgkmcnt(0)
	s_barrier
	s_waitcnt lgkmcnt(0)
	v_mfma_f32_16x16x32_bf16 v[114:117], v[130:133], v[180:183], v[114:117]
	v_mfma_f32_16x16x32_bf16 v[106:109], v[130:133], v[192:195], v[106:109]
	v_mfma_f32_16x16x32_bf16 v[90:93], v[130:133], v[200:203], v[90:93]
	v_mfma_f32_16x16x32_bf16 v[74:77], v[130:133], v[208:211], v[74:77]
	v_mfma_f32_16x16x32_bf16 v[74:77], v[134:137], v[212:215], v[74:77]
	v_mfma_f32_16x16x32_bf16 v[90:93], v[134:137], v[204:207], v[90:93]
	v_mfma_f32_16x16x32_bf16 v[106:109], v[134:137], v[196:199], v[106:109]
	v_mfma_f32_16x16x32_bf16 v[114:117], v[134:137], v[188:191], v[114:117]
	v_mfma_f32_16x16x32_bf16 v[118:121], v[142:145], v[188:191], v[118:121]
	v_mfma_f32_16x16x32_bf16 v[98:101], v[142:145], v[196:199], v[98:101]
	v_mfma_f32_16x16x32_bf16 v[82:85], v[142:145], v[204:207], v[82:85]
	v_mfma_f32_16x16x32_bf16 v[66:69], v[142:145], v[212:215], v[66:69]
	v_mfma_f32_16x16x32_bf16 v[66:69], v[138:141], v[208:211], v[66:69]
	v_mfma_f32_16x16x32_bf16 v[82:85], v[138:141], v[200:203], v[82:85]
	v_mfma_f32_16x16x32_bf16 v[98:101], v[138:141], v[192:195], v[98:101]
	v_mfma_f32_16x16x32_bf16 v[118:121], v[138:141], v[180:183], v[118:121]
	v_mfma_f32_16x16x32_bf16 v[122:125], v[146:149], v[180:183], v[122:125]
	v_mfma_f32_16x16x32_bf16 v[110:113], v[146:149], v[192:195], v[110:113]
	v_mfma_f32_16x16x32_bf16 v[94:97], v[146:149], v[200:203], v[94:97]
	v_mfma_f32_16x16x32_bf16 v[78:81], v[146:149], v[208:211], v[78:81]
	v_mfma_f32_16x16x32_bf16 v[78:81], v[150:153], v[212:215], v[78:81]
	v_mfma_f32_16x16x32_bf16 v[94:97], v[150:153], v[204:207], v[94:97]
	v_mfma_f32_16x16x32_bf16 v[110:113], v[150:153], v[196:199], v[110:113]
	v_mfma_f32_16x16x32_bf16 v[122:125], v[150:153], v[188:191], v[122:125]
	v_mfma_f32_16x16x32_bf16 v[126:129], v[176:179], v[188:191], v[126:129]
	v_mfma_f32_16x16x32_bf16 v[102:105], v[176:179], v[196:199], v[102:105]
	v_mfma_f32_16x16x32_bf16 v[86:89], v[176:179], v[204:207], v[86:89]
	v_mfma_f32_16x16x32_bf16 v[70:73], v[176:179], v[212:215], v[70:73]
	v_mfma_f32_16x16x32_bf16 v[70:73], v[172:175], v[208:211], v[70:73]
	v_mfma_f32_16x16x32_bf16 v[86:89], v[172:175], v[200:203], v[86:89]
	v_mfma_f32_16x16x32_bf16 v[102:105], v[172:175], v[192:195], v[102:105]
	v_mfma_f32_16x16x32_bf16 v[126:129], v[172:175], v[180:183], v[126:129]
	s_barrier
	s_add_i32 s20, s33, s24
	s_add_i32 m0, s20, 0xffffff80
	ds_read_b128 v[180:183], v185 offset:49152
	ds_read_b128 v[188:191], v185 offset:50176
	ds_read_b128 v[192:195], v185 offset:51200
	ds_read_b128 v[196:199], v185 offset:52224
	ds_read_b128 v[200:203], v185 offset:53248
	ds_read_b128 v[204:207], v185 offset:54272
	ds_read_b128 v[208:211], v185 offset:55296
	ds_read_b128 v[212:215], v185 offset:56320
	global_load_lds_dwordx4 v156, s[16:17] offset:128
	s_add_i32 m0, s20, 0x1f80
	s_add_i32 s20, s42, s24
	global_load_lds_dwordx4 v160, s[16:17] offset:128
	s_add_u32 s16, s16, 0x2b0080
	s_addc_u32 s17, s17, 0
	s_mov_b32 m0, s20
	s_nop 0
	global_load_lds_dwordx4 v156, s[16:17]
	s_add_i32 m0, s20, 0x2000
	s_nop 0
	global_load_lds_dwordx4 v160, s[16:17]
	s_mov_b32 m0, s34
	s_nop 0
	global_load_lds_dwordx4 v154, s[100:101]
	s_mov_b32 m0, s35
	s_nop 0
	global_load_lds_dwordx4 v158, s[100:101]
	s_waitcnt vmcnt(8)
	s_waitcnt lgkmcnt(0)
	s_barrier
	s_waitcnt lgkmcnt(0)
	v_mfma_f32_16x16x32_bf16 v[58:61], v[130:133], v[180:183], v[58:61]
	v_mfma_f32_16x16x32_bf16 v[42:45], v[130:133], v[192:195], v[42:45]
	v_mfma_f32_16x16x32_bf16 v[26:29], v[130:133], v[200:203], v[26:29]
	v_mfma_f32_16x16x32_bf16 v[6:9], v[130:133], v[208:211], v[6:9]
	v_mfma_f32_16x16x32_bf16 v[6:9], v[134:137], v[212:215], v[6:9]
	v_mfma_f32_16x16x32_bf16 v[26:29], v[134:137], v[204:207], v[26:29]
	v_mfma_f32_16x16x32_bf16 v[42:45], v[134:137], v[196:199], v[42:45]
	v_mfma_f32_16x16x32_bf16 v[58:61], v[134:137], v[188:191], v[58:61]
	v_mfma_f32_16x16x32_bf16 v[54:57], v[142:145], v[188:191], v[54:57]
	v_mfma_f32_16x16x32_bf16 v[34:37], v[142:145], v[196:199], v[34:37]
	v_mfma_f32_16x16x32_bf16 v[18:21], v[142:145], v[204:207], v[18:21]
	v_mfma_f32_16x16x32_bf16 v[2:5], v[142:145], v[212:215], v[2:5]
	v_mfma_f32_16x16x32_bf16 v[2:5], v[138:141], v[208:211], v[2:5]
	v_mfma_f32_16x16x32_bf16 v[18:21], v[138:141], v[200:203], v[18:21]
	v_mfma_f32_16x16x32_bf16 v[34:37], v[138:141], v[192:195], v[34:37]
	v_mfma_f32_16x16x32_bf16 v[54:57], v[138:141], v[180:183], v[54:57]
	v_mfma_f32_16x16x32_bf16 v[62:65], v[146:149], v[180:183], v[62:65]
	v_mfma_f32_16x16x32_bf16 v[46:49], v[146:149], v[192:195], v[46:49]
	v_mfma_f32_16x16x32_bf16 v[30:33], v[146:149], v[200:203], v[30:33]
	v_mfma_f32_16x16x32_bf16 v[10:13], v[146:149], v[208:211], v[10:13]
	v_mfma_f32_16x16x32_bf16 v[10:13], v[150:153], v[212:215], v[10:13]
	v_mfma_f32_16x16x32_bf16 v[30:33], v[150:153], v[204:207], v[30:33]
	v_mfma_f32_16x16x32_bf16 v[46:49], v[150:153], v[196:199], v[46:49]
	v_mfma_f32_16x16x32_bf16 v[62:65], v[150:153], v[188:191], v[62:65]
	v_mfma_f32_16x16x32_bf16 v[50:53], v[176:179], v[188:191], v[50:53]
	v_mfma_f32_16x16x32_bf16 v[38:41], v[176:179], v[196:199], v[38:41]
	v_mfma_f32_16x16x32_bf16 v[22:25], v[176:179], v[204:207], v[22:25]
	v_mfma_f32_16x16x32_bf16 v[14:17], v[176:179], v[212:215], v[14:17]
	v_mfma_f32_16x16x32_bf16 v[14:17], v[172:175], v[208:211], v[14:17]
	v_mfma_f32_16x16x32_bf16 v[22:25], v[172:175], v[200:203], v[22:25]
	v_mfma_f32_16x16x32_bf16 v[38:41], v[172:175], v[192:195], v[38:41]
	v_mfma_f32_16x16x32_bf16 v[50:53], v[172:175], v[180:183], v[50:53]
	s_barrier
	s_add_i32 s64, s64, 2
	s_add_u32 s18, s18, 0x100
	s_addc_u32 s19, s19, 0
	s_add_u32 s62, s62, 0x100
	s_addc_u32 s63, s63, 0
	s_cmpk_gt_u32 s64, 0xa9
	s_cbranch_scc0 .LBB0_1245
	s_and_b64 vcc, exec, s[12:13]
	s_cbranch_vccz .LBB0_1248
	s_barrier

; #define PG8_STAGE(bufoff, gbase, voff) do { _Pragma("unroll") for (int _i = 0; _i < 2; ++_i) \
;         __builtin_amdgcn_global_load_lds((const unsigned*)((const char*)(gbase) + (voff)[_i]), (PG8_LAS unsigned*)(lds + (bufoff) + ldsw + _i * 8192), 16, 0, 0); } while (0)
; #define PG8_LDA(dst, b, h) do { _Pragma("unroll") for (int m = 0; m < 4; ++m) _Pragma("unroll") for (int k = 0; k < 2; ++k) dst[m][k] = *(const PG8_LAS bf16x8*)(lds + PG8_SA(b, h) + aoff + m * 2048 + k * 1024); } while (0)
; #define PG8_LDB(dst, b, h) do { _Pragma("unroll") for (int n = 0; n < 2; ++n) _Pragma("unroll") for (int k = 0; k < 2; ++k) dst[n][k] = *(const PG8_LAS bf16x8*)(lds + PG8_SB(b, h) + boff + n * 2048 + k * 1024); } while (0)
; #define PG8_MMA(ai, bj, At, Bt) do { __builtin_amdgcn_s_setprio(1); _Pragma("unroll") for (int m = 0; m < 4; ++m) _Pragma("unroll") for (int n = 0; n < 2; ++n) _Pragma("unroll") for (int k = 0; k < 2; ++k) \
;         acc[ai][bj][m][n] = __builtin_amdgcn_mfma_f32_16x16x32_bf16(Bt[n][k], At[m][k], acc[ai][bj][m][n], 0, 0, 0); __builtin_amdgcn_s_setprio(0); } while (0)
; #define PG8_WAIT_V(n) asm volatile("s_waitcnt vmcnt(" #n ")" ::: "memory")
; #define PG8_WAIT_L(n) asm volatile("s_waitcnt lgkmcnt(" #n ")" ::: "memory")
; template <class Epi, class Sched, bool ALIGN_EPI = false, bool SP2 = false>
; __device__ __forceinline__ void gemm_phase(PG8_LAS unsigned char* lds, const Gemm g, const Sched& S, const Epi& E) {
;     ...
;             const bool last = (t == nt - 2);
;             const char* a1 = cA + (size_t)(t + 1) * kstep;
;             const char* a2 = last ? nA : cA + (size_t)(t + 2) * kstep; const char* b2 = last ? nB : cB + (size_t)(t + 2) * kstep;
;             const char* a3 = a2 + kstep; const char* b3 = b2 + kstep;
;             if (last && has_next) S.a_ready(nxt);
;             if constexpr (SP2) {
;             PG8_LDB(B0, 0, 0); PG8_LDB(B1, 0, 1); PG8_SCHED; PG8_LDA(At, 0, 0); PG8_STAGE(PG8_SA(1, 1), a1 + hstep, voffA);
;             PG8_WAIT_V(8); PG8_WAIT_L(0); PG8_BAR; PG8_MMA(0, 0, At, B0); PG8_MMA(0, 1, At, B1); PG8_BAR; PG8_SCHED;
;             PG8_LDA(At, 0, 1); PG8_STAGE(PG8_SB(0, 0), b2, voffB); PG8_STAGE(PG8_SB(0, 1), b2 + hstep, voffB); PG8_STAGE(PG8_SA(0, 0), a2, voffA);
;             PG8_WAIT_V(8); PG8_WAIT_L(0); PG8_BAR; PG8_MMA(1, 0, At, B0); PG8_MMA(1, 1, At, B1); PG8_BAR; PG8_SCHED;
.LBB0_1332:
	ds_read_b128 v[148:151], v241 offset:0
	ds_read_b128 v[156:159], v241 offset:1024
	ds_read_b128 v[166:169], v241 offset:2048
	ds_read_b128 v[170:173], v241 offset:3072
	ds_read_b128 v[174:177], v241 offset:16384
	ds_read_b128 v[178:181], v241 offset:17408
	ds_read_b128 v[182:185], v241 offset:18432
	ds_read_b128 v[186:189], v241 offset:19456
	s_add_u32 s20, s22, 0xfff00080
	s_addc_u32 s21, s23, -1
	s_cmp_eq_u32 s67, 60
	s_cselect_b32 s25, s13, s21
	s_cselect_b32 s24, s63, s20
	s_cselect_b32 s21, s11, s66
	s_cselect_b32 s20, s64, s65
	s_add_i32 m0, s19, 0xc000
	ds_read_b128 v[190:193], v155
	ds_read_b128 v[194:197], v155 offset:1024
	ds_read_b128 v[198:201], v155 offset:2048
	ds_read_b128 v[202:205], v155 offset:3072
	ds_read_b128 v[206:209], v155 offset:4096
	ds_read_b128 v[210:213], v155 offset:5120
	ds_read_b128 v[214:217], v155 offset:6144
	ds_read_b128 v[218:221], v155 offset:7168
	global_load_lds_dwordx4 v138, s[22:23]
	s_add_i32 m0, s19, 0xe000
	s_nop 0
	global_load_lds_dwordx4 v140, s[22:23]
	s_waitcnt vmcnt(8)
	s_waitcnt lgkmcnt(0)
	s_barrier
	s_waitcnt lgkmcnt(0)
	v_mfma_f32_16x16x32_bf16 v[118:121], v[148:151], v[190:193], v[118:121]
	v_mfma_f32_16x16x32_bf16 v[102:105], v[148:151], v[198:201], v[102:105]
	v_mfma_f32_16x16x32_bf16 v[86:89], v[148:151], v[206:209], v[86:89]
	v_mfma_f32_16x16x32_bf16 v[70:73], v[148:151], v[214:217], v[70:73]
	v_mfma_f32_16x16x32_bf16 v[70:73], v[156:159], v[218:221], v[70:73]
	v_mfma_f32_16x16x32_bf16 v[86:89], v[156:159], v[210:213], v[86:89]
	v_mfma_f32_16x16x32_bf16 v[102:105], v[156:159], v[202:205], v[102:105]
	v_mfma_f32_16x16x32_bf16 v[118:121], v[156:159], v[194:197], v[118:121]
	v_mfma_f32_16x16x32_bf16 v[114:117], v[170:173], v[194:197], v[114:117]
	v_mfma_f32_16x16x32_bf16 v[98:101], v[170:173], v[202:205], v[98:101]
	v_mfma_f32_16x16x32_bf16 v[82:85], v[170:173], v[210:213], v[82:85]
	v_mfma_f32_16x16x32_bf16 v[66:69], v[170:173], v[218:221], v[66:69]
	v_mfma_f32_16x16x32_bf16 v[66:69], v[166:169], v[214:217], v[66:69]
	v_mfma_f32_16x16x32_bf16 v[82:85], v[166:169], v[206:209], v[82:85]
	v_mfma_f32_16x16x32_bf16 v[98:101], v[166:169], v[198:201], v[98:101]
	v_mfma_f32_16x16x32_bf16 v[114:117], v[166:169], v[190:193], v[114:117]
	v_mfma_f32_16x16x32_bf16 v[126:129], v[174:177], v[190:193], v[126:129]
	v_mfma_f32_16x16x32_bf16 v[110:113], v[174:177], v[198:201], v[110:113]
	v_mfma_f32_16x16x32_bf16 v[94:97], v[174:177], v[206:209], v[94:97]
	v_mfma_f32_16x16x32_bf16 v[78:81], v[174:177], v[214:217], v[78:81]
	v_mfma_f32_16x16x32_bf16 v[78:81], v[178:181], v[218:221], v[78:81]
	v_mfma_f32_16x16x32_bf16 v[94:97], v[178:181], v[210:213], v[94:97]
	v_mfma_f32_16x16x32_bf16 v[110:113], v[178:181], v[202:205], v[110:113]
	v_mfma_f32_16x16x32_bf16 v[126:129], v[178:181], v[194:197], v[126:129]
	v_mfma_f32_16x16x32_bf16 v[122:125], v[186:189], v[194:197], v[122:125]
	v_mfma_f32_16x16x32_bf16 v[106:109], v[186:189], v[202:205], v[106:109]
	v_mfma_f32_16x16x32_bf16 v[90:93], v[186:189], v[210:213], v[90:93]
	v_mfma_f32_16x16x32_bf16 v[74:77], v[186:189], v[218:221], v[74:77]
	v_mfma_f32_16x16x32_bf16 v[74:77], v[182:185], v[214:217], v[74:77]
	v_mfma_f32_16x16x32_bf16 v[90:93], v[182:185], v[206:209], v[90:93]
	v_mfma_f32_16x16x32_bf16 v[106:109], v[182:185], v[198:201], v[106:109]
	v_mfma_f32_16x16x32_bf16 v[122:125], v[182:185], v[190:193], v[122:125]
	s_barrier
	s_add_i32 s33, s47, s28
	s_mov_b32 m0, s33
	ds_read_b128 v[190:193], v155 offset:16384
	ds_read_b128 v[194:197], v155 offset:17408
	ds_read_b128 v[198:201], v155 offset:18432
	ds_read_b128 v[202:205], v155 offset:19456
	ds_read_b128 v[206:209], v155 offset:20480
	ds_read_b128 v[210:213], v155 offset:21504
	ds_read_b128 v[214:217], v155 offset:22528
	ds_read_b128 v[218:221], v155 offset:23552
	global_load_lds_dwordx4 v132, s[20:21]
	s_add_i32 m0, s33, 0x2000
	s_add_u32 s68, s20, 0x100000
	s_addc_u32 s69, s21, 0
	s_add_i32 s33, s52, s28
	global_load_lds_dwordx4 v136, s[20:21]
	s_mov_b32 m0, s33
	s_add_u32 s100, s24, 0x80
	s_addc_u32 s101, s25, 0
	global_load_lds_dwordx4 v132, s[68:69]
	s_add_i32 m0, s33, 0x2000
	s_nop 0
	global_load_lds_dwordx4 v136, s[68:69]
	s_mov_b32 m0, s19
	s_nop 0
	global_load_lds_dwordx4 v130, s[24:25]
	s_mov_b32 m0, s35
	s_nop 0
	global_load_lds_dwordx4 v134, s[24:25]
	s_waitcnt vmcnt(8)
	s_waitcnt lgkmcnt(0)
	s_barrier
	s_waitcnt lgkmcnt(0)
	v_mfma_f32_16x16x32_bf16 v[54:57], v[148:151], v[190:193], v[54:57]
	v_mfma_f32_16x16x32_bf16 v[38:41], v[148:151], v[198:201], v[38:41]
	v_mfma_f32_16x16x32_bf16 v[22:25], v[148:151], v[206:209], v[22:25]
	v_mfma_f32_16x16x32_bf16 v[6:9], v[148:151], v[214:217], v[6:9]
	v_mfma_f32_16x16x32_bf16 v[6:9], v[156:159], v[218:221], v[6:9]
	v_mfma_f32_16x16x32_bf16 v[22:25], v[156:159], v[210:213], v[22:25]
	v_mfma_f32_16x16x32_bf16 v[38:41], v[156:159], v[202:205], v[38:41]
	v_mfma_f32_16x16x32_bf16 v[54:57], v[156:159], v[194:197], v[54:57]
	v_mfma_f32_16x16x32_bf16 v[50:53], v[170:173], v[194:197], v[50:53]
	v_mfma_f32_16x16x32_bf16 v[34:37], v[170:173], v[202:205], v[34:37]
	v_mfma_f32_16x16x32_bf16 v[18:21], v[170:173], v[210:213], v[18:21]
	v_mfma_f32_16x16x32_bf16 v[2:5], v[170:173], v[218:221], v[2:5]
	v_mfma_f32_16x16x32_bf16 v[2:5], v[166:169], v[214:217], v[2:5]
	v_mfma_f32_16x16x32_bf16 v[18:21], v[166:169], v[206:209], v[18:21]
	v_mfma_f32_16x16x32_bf16 v[34:37], v[166:169], v[198:201], v[34:37]
	v_mfma_f32_16x16x32_bf16 v[50:53], v[166:169], v[190:193], v[50:53]
	v_mfma_f32_16x16x32_bf16 v[62:65], v[174:177], v[190:193], v[62:65]
	v_mfma_f32_16x16x32_bf16 v[46:49], v[174:177], v[198:201], v[46:49]
	v_mfma_f32_16x16x32_bf16 v[30:33], v[174:177], v[206:209], v[30:33]
	v_mfma_f32_16x16x32_bf16 v[10:13], v[174:177], v[214:217], v[10:13]
	v_mfma_f32_16x16x32_bf16 v[10:13], v[178:181], v[218:221], v[10:13]
	v_mfma_f32_16x16x32_bf16 v[30:33], v[178:181], v[210:213], v[30:33]
	v_mfma_f32_16x16x32_bf16 v[46:49], v[178:181], v[202:205], v[46:49]
	v_mfma_f32_16x16x32_bf16 v[62:65], v[178:181], v[194:197], v[62:65]
	v_mfma_f32_16x16x32_bf16 v[58:61], v[186:189], v[194:197], v[58:61]
	v_mfma_f32_16x16x32_bf16 v[42:45], v[186:189], v[202:205], v[42:45]
	v_mfma_f32_16x16x32_bf16 v[26:29], v[186:189], v[210:213], v[26:29]
	v_mfma_f32_16x16x32_bf16 v[14:17], v[186:189], v[218:221], v[14:17]
	v_mfma_f32_16x16x32_bf16 v[14:17], v[182:185], v[214:217], v[14:17]
	v_mfma_f32_16x16x32_bf16 v[26:29], v[182:185], v[206:209], v[26:29]
	v_mfma_f32_16x16x32_bf16 v[42:45], v[182:185], v[198:201], v[42:45]
	v_mfma_f32_16x16x32_bf16 v[58:61], v[182:185], v[190:193], v[58:61]
	s_barrier
; #define PG8_STAGE(bufoff, gbase, voff) do { _Pragma("unroll") for (int _i = 0; _i < 2; ++_i) \
;         __builtin_amdgcn_global_load_lds((const unsigned*)((const char*)(gbase) + (voff)[_i]), (PG8_LAS unsigned*)(lds + (bufoff) + ldsw + _i * 8192), 16, 0, 0); } while (0)
; #define PG8_LDA(dst, b, h) do { _Pragma("unroll") for (int m = 0; m < 4; ++m) _Pragma("unroll") for (int k = 0; k < 2; ++k) dst[m][k] = *(const PG8_LAS bf16x8*)(lds + PG8_SA(b, h) + aoff + m * 2048 + k * 1024); } while (0)
; #define PG8_LDB(dst, b, h) do { _Pragma("unroll") for (int n = 0; n < 2; ++n) _Pragma("unroll") for (int k = 0; k < 2; ++k) dst[n][k] = *(const PG8_LAS bf16x8*)(lds + PG8_SB(b, h) + boff + n * 2048 + k * 1024); } while (0)
; #define PG8_MMA(ai, bj, At, Bt) do { __builtin_amdgcn_s_setprio(1); _Pragma("unroll") for (int m = 0; m < 4; ++m) _Pragma("unroll") for (int n = 0; n < 2; ++n) _Pragma("unroll") for (int k = 0; k < 2; ++k) \
;         acc[ai][bj][m][n] = __builtin_amdgcn_mfma_f32_16x16x32_bf16(Bt[n][k], At[m][k], acc[ai][bj][m][n], 0, 0, 0); __builtin_amdgcn_s_setprio(0); } while (0)
; #define PG8_WAIT_V(n) asm volatile("s_waitcnt vmcnt(" #n ")" ::: "memory")
; #define PG8_WAIT_L(n) asm volatile("s_waitcnt lgkmcnt(" #n ")" ::: "memory")
; #define PG8_BAR __builtin_amdgcn_s_barrier()
; #define PG8_SCHED __builtin_amdgcn_sched_barrier(0)
; template <class Epi, class Sched, bool ALIGN_EPI = false, bool SP2 = false>
; __device__ __forceinline__ void gemm_phase(PG8_LAS unsigned char* lds, const Gemm g, const Sched& S, const Epi& E) {
;     ...
;             PG8_LDB(B0, 1, 0); PG8_LDB(B1, 1, 1); PG8_SCHED; PG8_LDA(At, 1, 0); PG8_STAGE(PG8_SA(0, 1), a2 + hstep, voffA);
;             PG8_WAIT_V(8); PG8_WAIT_L(0); PG8_BAR; PG8_MMA(0, 0, At, B0); PG8_MMA(0, 1, At, B1); PG8_BAR; PG8_SCHED;
;             PG8_LDA(At, 1, 1); PG8_STAGE(PG8_SB(1, 0), b3, voffB); PG8_STAGE(PG8_SB(1, 1), b3 + hstep, voffB); PG8_STAGE(PG8_SA(1, 0), a3, voffA);
;             PG8_WAIT_V(8); PG8_WAIT_L(0); PG8_BAR; PG8_MMA(1, 0, At, B0); PG8_MMA(1, 1, At, B1); PG8_BAR; PG8_SCHED;
	s_add_i32 s33, 0, 0x18000
	s_add_i32 s42, 0, 0x1c000
	ds_read_b128 v[148:151], v241 offset:32768
	ds_read_b128 v[156:159], v241 offset:33792
	ds_read_b128 v[166:169], v241 offset:34816
	ds_read_b128 v[170:173], v241 offset:35840
	ds_read_b128 v[174:177], v241 offset:49152
	ds_read_b128 v[178:181], v241 offset:50176
	ds_read_b128 v[182:185], v241 offset:51200
	ds_read_b128 v[186:189], v241 offset:52224
	s_add_u32 s24, s24, 0x100000
	s_addc_u32 s25, s25, 0
	s_mov_b32 m0, s36
	ds_read_b128 v[190:193], v155 offset:32768
	ds_read_b128 v[194:197], v155 offset:33792
	ds_read_b128 v[198:201], v155 offset:34816
	ds_read_b128 v[202:205], v155 offset:35840
	ds_read_b128 v[206:209], v155 offset:36864
	ds_read_b128 v[210:213], v155 offset:37888
	ds_read_b128 v[214:217], v155 offset:38912
	ds_read_b128 v[218:221], v155 offset:39936
	global_load_lds_dwordx4 v130, s[24:25]
	s_mov_b32 m0, s37
	s_nop 0
	global_load_lds_dwordx4 v134, s[24:25]
	s_waitcnt vmcnt(8)
	s_waitcnt lgkmcnt(0)
	s_barrier
	s_waitcnt lgkmcnt(0)
	v_mfma_f32_16x16x32_bf16 v[118:121], v[148:151], v[190:193], v[118:121]
	v_mfma_f32_16x16x32_bf16 v[102:105], v[148:151], v[198:201], v[102:105]
	v_mfma_f32_16x16x32_bf16 v[86:89], v[148:151], v[206:209], v[86:89]
	v_mfma_f32_16x16x32_bf16 v[70:73], v[148:151], v[214:217], v[70:73]
	v_mfma_f32_16x16x32_bf16 v[70:73], v[156:159], v[218:221], v[70:73]
	v_mfma_f32_16x16x32_bf16 v[86:89], v[156:159], v[210:213], v[86:89]
	v_mfma_f32_16x16x32_bf16 v[102:105], v[156:159], v[202:205], v[102:105]
	v_mfma_f32_16x16x32_bf16 v[118:121], v[156:159], v[194:197], v[118:121]
	v_mfma_f32_16x16x32_bf16 v[114:117], v[170:173], v[194:197], v[114:117]
	v_mfma_f32_16x16x32_bf16 v[98:101], v[170:173], v[202:205], v[98:101]
	v_mfma_f32_16x16x32_bf16 v[82:85], v[170:173], v[210:213], v[82:85]
	v_mfma_f32_16x16x32_bf16 v[66:69], v[170:173], v[218:221], v[66:69]
	v_mfma_f32_16x16x32_bf16 v[66:69], v[166:169], v[214:217], v[66:69]
	v_mfma_f32_16x16x32_bf16 v[82:85], v[166:169], v[206:209], v[82:85]
	v_mfma_f32_16x16x32_bf16 v[98:101], v[166:169], v[198:201], v[98:101]
	v_mfma_f32_16x16x32_bf16 v[114:117], v[166:169], v[190:193], v[114:117]
	v_mfma_f32_16x16x32_bf16 v[126:129], v[174:177], v[190:193], v[126:129]
	v_mfma_f32_16x16x32_bf16 v[110:113], v[174:177], v[198:201], v[110:113]
	v_mfma_f32_16x16x32_bf16 v[94:97], v[174:177], v[206:209], v[94:97]
	v_mfma_f32_16x16x32_bf16 v[78:81], v[174:177], v[214:217], v[78:81]
	v_mfma_f32_16x16x32_bf16 v[78:81], v[178:181], v[218:221], v[78:81]
	v_mfma_f32_16x16x32_bf16 v[94:97], v[178:181], v[210:213], v[94:97]
	v_mfma_f32_16x16x32_bf16 v[110:113], v[178:181], v[202:205], v[110:113]
	v_mfma_f32_16x16x32_bf16 v[126:129], v[178:181], v[194:197], v[126:129]
	v_mfma_f32_16x16x32_bf16 v[122:125], v[186:189], v[194:197], v[122:125]
	v_mfma_f32_16x16x32_bf16 v[106:109], v[186:189], v[202:205], v[106:109]
	v_mfma_f32_16x16x32_bf16 v[90:93], v[186:189], v[210:213], v[90:93]
	v_mfma_f32_16x16x32_bf16 v[74:77], v[186:189], v[218:221], v[74:77]
	v_mfma_f32_16x16x32_bf16 v[74:77], v[182:185], v[214:217], v[74:77]
	v_mfma_f32_16x16x32_bf16 v[90:93], v[182:185], v[206:209], v[90:93]
	v_mfma_f32_16x16x32_bf16 v[106:109], v[182:185], v[198:201], v[106:109]
	v_mfma_f32_16x16x32_bf16 v[122:125], v[182:185], v[190:193], v[122:125]
	s_barrier
	s_add_i32 s24, s33, s28
	s_add_i32 m0, s24, 0xffffff80
	ds_read_b128 v[190:193], v155 offset:49152
	ds_read_b128 v[194:197], v155 offset:50176
	ds_read_b128 v[198:201], v155 offset:51200
	ds_read_b128 v[202:205], v155 offset:52224
	ds_read_b128 v[206:209], v155 offset:53248
	ds_read_b128 v[210:213], v155 offset:54272
	ds_read_b128 v[214:217], v155 offset:55296
	ds_read_b128 v[218:221], v155 offset:56320
	global_load_lds_dwordx4 v132, s[20:21] offset:128
	s_add_i32 m0, s24, 0x1f80
	s_add_i32 s24, s42, s28
	global_load_lds_dwordx4 v136, s[20:21] offset:128
	s_add_u32 s20, s20, 0x100080
	s_addc_u32 s21, s21, 0
	s_mov_b32 m0, s24
	s_nop 0
	global_load_lds_dwordx4 v132, s[20:21]
	s_add_i32 m0, s24, 0x2000
	s_nop 0
	global_load_lds_dwordx4 v136, s[20:21]
	s_mov_b32 m0, s43
	s_nop 0
	global_load_lds_dwordx4 v130, s[100:101]
	s_mov_b32 m0, s46
	s_nop 0
	global_load_lds_dwordx4 v134, s[100:101]
	s_waitcnt vmcnt(8)
	s_waitcnt lgkmcnt(0)
	s_barrier
	s_waitcnt lgkmcnt(0)
	v_mfma_f32_16x16x32_bf16 v[54:57], v[148:151], v[190:193], v[54:57]
	v_mfma_f32_16x16x32_bf16 v[38:41], v[148:151], v[198:201], v[38:41]
	v_mfma_f32_16x16x32_bf16 v[22:25], v[148:151], v[206:209], v[22:25]
	v_mfma_f32_16x16x32_bf16 v[6:9], v[148:151], v[214:217], v[6:9]
	v_mfma_f32_16x16x32_bf16 v[6:9], v[156:159], v[218:221], v[6:9]
	v_mfma_f32_16x16x32_bf16 v[22:25], v[156:159], v[210:213], v[22:25]
	v_mfma_f32_16x16x32_bf16 v[38:41], v[156:159], v[202:205], v[38:41]
	v_mfma_f32_16x16x32_bf16 v[54:57], v[156:159], v[194:197], v[54:57]
	v_mfma_f32_16x16x32_bf16 v[50:53], v[170:173], v[194:197], v[50:53]
	v_mfma_f32_16x16x32_bf16 v[34:37], v[170:173], v[202:205], v[34:37]
	v_mfma_f32_16x16x32_bf16 v[18:21], v[170:173], v[210:213], v[18:21]
	v_mfma_f32_16x16x32_bf16 v[2:5], v[170:173], v[218:221], v[2:5]
	v_mfma_f32_16x16x32_bf16 v[2:5], v[166:169], v[214:217], v[2:5]
	v_mfma_f32_16x16x32_bf16 v[18:21], v[166:169], v[206:209], v[18:21]
	v_mfma_f32_16x16x32_bf16 v[34:37], v[166:169], v[198:201], v[34:37]
	v_mfma_f32_16x16x32_bf16 v[50:53], v[166:169], v[190:193], v[50:53]
	v_mfma_f32_16x16x32_bf16 v[62:65], v[174:177], v[190:193], v[62:65]
	v_mfma_f32_16x16x32_bf16 v[46:49], v[174:177], v[198:201], v[46:49]
	v_mfma_f32_16x16x32_bf16 v[30:33], v[174:177], v[206:209], v[30:33]
	v_mfma_f32_16x16x32_bf16 v[10:13], v[174:177], v[214:217], v[10:13]
	v_mfma_f32_16x16x32_bf16 v[10:13], v[178:181], v[218:221], v[10:13]
	v_mfma_f32_16x16x32_bf16 v[30:33], v[178:181], v[210:213], v[30:33]
	v_mfma_f32_16x16x32_bf16 v[46:49], v[178:181], v[202:205], v[46:49]
	v_mfma_f32_16x16x32_bf16 v[62:65], v[178:181], v[194:197], v[62:65]
	v_mfma_f32_16x16x32_bf16 v[58:61], v[186:189], v[194:197], v[58:61]
	v_mfma_f32_16x16x32_bf16 v[42:45], v[186:189], v[202:205], v[42:45]
	v_mfma_f32_16x16x32_bf16 v[26:29], v[186:189], v[210:213], v[26:29]
	v_mfma_f32_16x16x32_bf16 v[14:17], v[186:189], v[218:221], v[14:17]
	v_mfma_f32_16x16x32_bf16 v[14:17], v[182:185], v[214:217], v[14:17]
	v_mfma_f32_16x16x32_bf16 v[26:29], v[182:185], v[206:209], v[26:29]
	v_mfma_f32_16x16x32_bf16 v[42:45], v[182:185], v[198:201], v[42:45]
	v_mfma_f32_16x16x32_bf16 v[58:61], v[182:185], v[190:193], v[58:61]
	s_barrier
	s_add_i32 s67, s67, 2
	s_add_u32 s22, s22, 0x100
	s_addc_u32 s23, s23, 0
	s_add_u32 s65, s65, 0x100
	s_addc_u32 s66, s66, 0
	s_cmp_gt_u32 s67, 61
	s_cbranch_scc0 .LBB0_1332
	s_and_b64 vcc, exec, s[8:9]
	s_cbranch_vccz .LBB0_1335
	s_barrier

; #define PG8_STAGE(bufoff, gbase, voff) do { _Pragma("unroll") for (int _i = 0; _i < 2; ++_i) \
;         __builtin_amdgcn_global_load_lds((const unsigned*)((const char*)(gbase) + (voff)[_i]), (PG8_LAS unsigned*)(lds + (bufoff) + ldsw + _i * 8192), 16, 0, 0); } while (0)
; #define PG8_LDA(dst, b, h) do { _Pragma("unroll") for (int m = 0; m < 4; ++m) _Pragma("unroll") for (int k = 0; k < 2; ++k) dst[m][k] = *(const PG8_LAS bf16x8*)(lds + PG8_SA(b, h) + aoff + m * 2048 + k * 1024); } while (0)
; #define PG8_LDB(dst, b, h) do { _Pragma("unroll") for (int n = 0; n < 2; ++n) _Pragma("unroll") for (int k = 0; k < 2; ++k) dst[n][k] = *(const PG8_LAS bf16x8*)(lds + PG8_SB(b, h) + boff + n * 2048 + k * 1024); } while (0)
; #define PG8_MMA(ai, bj, At, Bt) do { __builtin_amdgcn_s_setprio(1); _Pragma("unroll") for (int m = 0; m < 4; ++m) _Pragma("unroll") for (int n = 0; n < 2; ++n) _Pragma("unroll") for (int k = 0; k < 2; ++k) \
;         acc[ai][bj][m][n] = __builtin_amdgcn_mfma_f32_16x16x32_bf16(Bt[n][k], At[m][k], acc[ai][bj][m][n], 0, 0, 0); __builtin_amdgcn_s_setprio(0); } while (0)
; #define PG8_WAIT_V(n) asm volatile("s_waitcnt vmcnt(" #n ")" ::: "memory")
; #define PG8_WAIT_L(n) asm volatile("s_waitcnt lgkmcnt(" #n ")" ::: "memory")
; template <class Epi, class Sched, bool ALIGN_EPI = false, bool SP2 = false>
; __device__ __forceinline__ void gemm_phase(PG8_LAS unsigned char* lds, const Gemm g, const Sched& S, const Epi& E) {
;     ...
;             const bool last = (t == nt - 2);
;             const char* a1 = cA + (size_t)(t + 1) * kstep;
;             const char* a2 = last ? nA : cA + (size_t)(t + 2) * kstep; const char* b2 = last ? nB : cB + (size_t)(t + 2) * kstep;
;             const char* a3 = a2 + kstep; const char* b3 = b2 + kstep;
;             if (last && has_next) S.a_ready(nxt);
;             if constexpr (SP2) {
;             PG8_LDB(B0, 0, 0); PG8_LDB(B1, 0, 1); PG8_SCHED; PG8_LDA(At, 0, 0); PG8_STAGE(PG8_SA(1, 1), a1 + hstep, voffA);
;             PG8_WAIT_V(8); PG8_WAIT_L(0); PG8_BAR; PG8_MMA(0, 0, At, B0); PG8_MMA(0, 1, At, B1); PG8_BAR; PG8_SCHED;
;             PG8_LDA(At, 0, 1); PG8_STAGE(PG8_SB(0, 0), b2, voffB); PG8_STAGE(PG8_SB(0, 1), b2 + hstep, voffB); PG8_STAGE(PG8_SA(0, 0), a2, voffA);
;             PG8_WAIT_V(8); PG8_WAIT_L(0); PG8_BAR; PG8_MMA(1, 0, At, B0); PG8_MMA(1, 1, At, B1); PG8_BAR; PG8_SCHED;
.LBB0_1595:
	ds_read_b128 v[130:133], v241 offset:0
	ds_read_b128 v[134:137], v241 offset:1024
	ds_read_b128 v[138:141], v241 offset:2048
	ds_read_b128 v[142:145], v241 offset:3072
	ds_read_b128 v[146:149], v241 offset:16384
	ds_read_b128 v[150:153], v241 offset:17408
	ds_read_b128 v[172:175], v241 offset:18432
	ds_read_b128 v[176:179], v241 offset:19456
	s_add_u32 s24, s26, 0xfff00080
	s_addc_u32 s25, s27, -1
	s_cmp_eq_u32 s62, 60
	s_cselect_b32 s29, s15, s25
	s_cselect_b32 s28, s21, s24
	s_cselect_b32 s25, s13, s53
	s_cselect_b32 s24, s51, s52
	s_add_i32 m0, s23, 0xc000
	ds_read_b128 v[180:183], v185
	ds_read_b128 v[188:191], v185 offset:1024
	ds_read_b128 v[192:195], v185 offset:2048
	ds_read_b128 v[196:199], v185 offset:3072
	ds_read_b128 v[200:203], v185 offset:4096
	ds_read_b128 v[204:207], v185 offset:5120
	ds_read_b128 v[208:211], v185 offset:6144
	ds_read_b128 v[212:215], v185 offset:7168
	global_load_lds_dwordx4 v162, s[26:27]
	s_add_i32 m0, s23, 0xe000
	s_nop 0
	global_load_lds_dwordx4 v166, s[26:27]
	s_waitcnt vmcnt(8)
	s_waitcnt lgkmcnt(0)
	s_barrier
	s_waitcnt lgkmcnt(0)
	v_mfma_f32_16x16x32_bf16 v[114:117], v[130:133], v[180:183], v[114:117]
	v_mfma_f32_16x16x32_bf16 v[106:109], v[130:133], v[192:195], v[106:109]
	v_mfma_f32_16x16x32_bf16 v[90:93], v[130:133], v[200:203], v[90:93]
	v_mfma_f32_16x16x32_bf16 v[74:77], v[130:133], v[208:211], v[74:77]
	v_mfma_f32_16x16x32_bf16 v[74:77], v[134:137], v[212:215], v[74:77]
	v_mfma_f32_16x16x32_bf16 v[90:93], v[134:137], v[204:207], v[90:93]
	v_mfma_f32_16x16x32_bf16 v[106:109], v[134:137], v[196:199], v[106:109]
	v_mfma_f32_16x16x32_bf16 v[114:117], v[134:137], v[188:191], v[114:117]
	v_mfma_f32_16x16x32_bf16 v[118:121], v[142:145], v[188:191], v[118:121]
	v_mfma_f32_16x16x32_bf16 v[98:101], v[142:145], v[196:199], v[98:101]
	v_mfma_f32_16x16x32_bf16 v[82:85], v[142:145], v[204:207], v[82:85]
	v_mfma_f32_16x16x32_bf16 v[66:69], v[142:145], v[212:215], v[66:69]
	v_mfma_f32_16x16x32_bf16 v[66:69], v[138:141], v[208:211], v[66:69]
	v_mfma_f32_16x16x32_bf16 v[82:85], v[138:141], v[200:203], v[82:85]
	v_mfma_f32_16x16x32_bf16 v[98:101], v[138:141], v[192:195], v[98:101]
	v_mfma_f32_16x16x32_bf16 v[118:121], v[138:141], v[180:183], v[118:121]
	v_mfma_f32_16x16x32_bf16 v[122:125], v[146:149], v[180:183], v[122:125]
	v_mfma_f32_16x16x32_bf16 v[110:113], v[146:149], v[192:195], v[110:113]
	v_mfma_f32_16x16x32_bf16 v[94:97], v[146:149], v[200:203], v[94:97]
	v_mfma_f32_16x16x32_bf16 v[78:81], v[146:149], v[208:211], v[78:81]
	v_mfma_f32_16x16x32_bf16 v[78:81], v[150:153], v[212:215], v[78:81]
	v_mfma_f32_16x16x32_bf16 v[94:97], v[150:153], v[204:207], v[94:97]
	v_mfma_f32_16x16x32_bf16 v[110:113], v[150:153], v[196:199], v[110:113]
	v_mfma_f32_16x16x32_bf16 v[122:125], v[150:153], v[188:191], v[122:125]
	v_mfma_f32_16x16x32_bf16 v[126:129], v[176:179], v[188:191], v[126:129]
	v_mfma_f32_16x16x32_bf16 v[102:105], v[176:179], v[196:199], v[102:105]
	v_mfma_f32_16x16x32_bf16 v[86:89], v[176:179], v[204:207], v[86:89]
	v_mfma_f32_16x16x32_bf16 v[70:73], v[176:179], v[212:215], v[70:73]
	v_mfma_f32_16x16x32_bf16 v[70:73], v[172:175], v[208:211], v[70:73]
	v_mfma_f32_16x16x32_bf16 v[86:89], v[172:175], v[200:203], v[86:89]
	v_mfma_f32_16x16x32_bf16 v[102:105], v[172:175], v[192:195], v[102:105]
	v_mfma_f32_16x16x32_bf16 v[126:129], v[172:175], v[180:183], v[126:129]
	s_barrier
	s_add_i32 s33, s48, s36
	s_mov_b32 m0, s33
	ds_read_b128 v[180:183], v185 offset:16384
	ds_read_b128 v[188:191], v185 offset:17408
	ds_read_b128 v[192:195], v185 offset:18432
	ds_read_b128 v[196:199], v185 offset:19456
	ds_read_b128 v[200:203], v185 offset:20480
	ds_read_b128 v[204:207], v185 offset:21504
	ds_read_b128 v[208:211], v185 offset:22528
	ds_read_b128 v[212:215], v185 offset:23552
	global_load_lds_dwordx4 v156, s[24:25]
	s_add_i32 m0, s33, 0x2000
	s_add_u32 s64, s24, 0x100000
	s_addc_u32 s65, s25, 0
	s_add_i32 s33, s49, s36
	global_load_lds_dwordx4 v160, s[24:25]
	s_mov_b32 m0, s33
	s_add_u32 s100, s28, 0x80
	s_addc_u32 s101, s29, 0
	global_load_lds_dwordx4 v156, s[64:65]
	s_add_i32 m0, s33, 0x2000
	s_nop 0
	global_load_lds_dwordx4 v160, s[64:65]
	s_mov_b32 m0, s23
	s_nop 0
	global_load_lds_dwordx4 v154, s[28:29]
	s_mov_b32 m0, s37
	s_nop 0
	global_load_lds_dwordx4 v158, s[28:29]
	s_waitcnt vmcnt(8)
	s_waitcnt lgkmcnt(0)
	s_barrier
	s_waitcnt lgkmcnt(0)
	v_mfma_f32_16x16x32_bf16 v[58:61], v[130:133], v[180:183], v[58:61]
	v_mfma_f32_16x16x32_bf16 v[42:45], v[130:133], v[192:195], v[42:45]
	v_mfma_f32_16x16x32_bf16 v[26:29], v[130:133], v[200:203], v[26:29]
	v_mfma_f32_16x16x32_bf16 v[6:9], v[130:133], v[208:211], v[6:9]
	v_mfma_f32_16x16x32_bf16 v[6:9], v[134:137], v[212:215], v[6:9]
	v_mfma_f32_16x16x32_bf16 v[26:29], v[134:137], v[204:207], v[26:29]
	v_mfma_f32_16x16x32_bf16 v[42:45], v[134:137], v[196:199], v[42:45]
	v_mfma_f32_16x16x32_bf16 v[58:61], v[134:137], v[188:191], v[58:61]
	v_mfma_f32_16x16x32_bf16 v[54:57], v[142:145], v[188:191], v[54:57]
	v_mfma_f32_16x16x32_bf16 v[34:37], v[142:145], v[196:199], v[34:37]
	v_mfma_f32_16x16x32_bf16 v[18:21], v[142:145], v[204:207], v[18:21]
	v_mfma_f32_16x16x32_bf16 v[2:5], v[142:145], v[212:215], v[2:5]
	v_mfma_f32_16x16x32_bf16 v[2:5], v[138:141], v[208:211], v[2:5]
	v_mfma_f32_16x16x32_bf16 v[18:21], v[138:141], v[200:203], v[18:21]
	v_mfma_f32_16x16x32_bf16 v[34:37], v[138:141], v[192:195], v[34:37]
	v_mfma_f32_16x16x32_bf16 v[54:57], v[138:141], v[180:183], v[54:57]
	v_mfma_f32_16x16x32_bf16 v[62:65], v[146:149], v[180:183], v[62:65]
	v_mfma_f32_16x16x32_bf16 v[46:49], v[146:149], v[192:195], v[46:49]
	v_mfma_f32_16x16x32_bf16 v[30:33], v[146:149], v[200:203], v[30:33]
	v_mfma_f32_16x16x32_bf16 v[10:13], v[146:149], v[208:211], v[10:13]
	v_mfma_f32_16x16x32_bf16 v[10:13], v[150:153], v[212:215], v[10:13]
	v_mfma_f32_16x16x32_bf16 v[30:33], v[150:153], v[204:207], v[30:33]
	v_mfma_f32_16x16x32_bf16 v[46:49], v[150:153], v[196:199], v[46:49]
	v_mfma_f32_16x16x32_bf16 v[62:65], v[150:153], v[188:191], v[62:65]
	v_mfma_f32_16x16x32_bf16 v[50:53], v[176:179], v[188:191], v[50:53]
	v_mfma_f32_16x16x32_bf16 v[38:41], v[176:179], v[196:199], v[38:41]
	v_mfma_f32_16x16x32_bf16 v[22:25], v[176:179], v[204:207], v[22:25]
	v_mfma_f32_16x16x32_bf16 v[14:17], v[176:179], v[212:215], v[14:17]
	v_mfma_f32_16x16x32_bf16 v[14:17], v[172:175], v[208:211], v[14:17]
	v_mfma_f32_16x16x32_bf16 v[22:25], v[172:175], v[200:203], v[22:25]
	v_mfma_f32_16x16x32_bf16 v[38:41], v[172:175], v[192:195], v[38:41]
	v_mfma_f32_16x16x32_bf16 v[50:53], v[172:175], v[180:183], v[50:53]
	s_barrier
; #define PG8_STAGE(bufoff, gbase, voff) do { _Pragma("unroll") for (int _i = 0; _i < 2; ++_i) \
;         __builtin_amdgcn_global_load_lds((const unsigned*)((const char*)(gbase) + (voff)[_i]), (PG8_LAS unsigned*)(lds + (bufoff) + ldsw + _i * 8192), 16, 0, 0); } while (0)
; #define PG8_LDA(dst, b, h) do { _Pragma("unroll") for (int m = 0; m < 4; ++m) _Pragma("unroll") for (int k = 0; k < 2; ++k) dst[m][k] = *(const PG8_LAS bf16x8*)(lds + PG8_SA(b, h) + aoff + m * 2048 + k * 1024); } while (0)
; #define PG8_LDB(dst, b, h) do { _Pragma("unroll") for (int n = 0; n < 2; ++n) _Pragma("unroll") for (int k = 0; k < 2; ++k) dst[n][k] = *(const PG8_LAS bf16x8*)(lds + PG8_SB(b, h) + boff + n * 2048 + k * 1024); } while (0)
; #define PG8_MMA(ai, bj, At, Bt) do { __builtin_amdgcn_s_setprio(1); _Pragma("unroll") for (int m = 0; m < 4; ++m) _Pragma("unroll") for (int n = 0; n < 2; ++n) _Pragma("unroll") for (int k = 0; k < 2; ++k) \
;         acc[ai][bj][m][n] = __builtin_amdgcn_mfma_f32_16x16x32_bf16(Bt[n][k], At[m][k], acc[ai][bj][m][n], 0, 0, 0); __builtin_amdgcn_s_setprio(0); } while (0)
; #define PG8_WAIT_V(n) asm volatile("s_waitcnt vmcnt(" #n ")" ::: "memory")
; #define PG8_WAIT_L(n) asm volatile("s_waitcnt lgkmcnt(" #n ")" ::: "memory")
; #define PG8_BAR __builtin_amdgcn_s_barrier()
; #define PG8_SCHED __builtin_amdgcn_sched_barrier(0)
; template <class Epi, class Sched, bool ALIGN_EPI = false, bool SP2 = false>
; __device__ __forceinline__ void gemm_phase(PG8_LAS unsigned char* lds, const Gemm g, const Sched& S, const Epi& E) {
;     ...
;             PG8_LDB(B0, 1, 0); PG8_LDB(B1, 1, 1); PG8_SCHED; PG8_LDA(At, 1, 0); PG8_STAGE(PG8_SA(0, 1), a2 + hstep, voffA);
;             PG8_WAIT_V(8); PG8_WAIT_L(0); PG8_BAR; PG8_MMA(0, 0, At, B0); PG8_MMA(0, 1, At, B1); PG8_BAR; PG8_SCHED;
;             PG8_LDA(At, 1, 1); PG8_STAGE(PG8_SB(1, 0), b3, voffB); PG8_STAGE(PG8_SB(1, 1), b3 + hstep, voffB); PG8_STAGE(PG8_SA(1, 0), a3, voffA);
;             PG8_WAIT_V(8); PG8_WAIT_L(0); PG8_BAR; PG8_MMA(1, 0, At, B0); PG8_MMA(1, 1, At, B1); PG8_BAR; PG8_SCHED;
	s_add_i32 s33, 0, 0x18000
	s_add_i32 s42, 0, 0x1c000
	ds_read_b128 v[130:133], v241 offset:32768
	ds_read_b128 v[134:137], v241 offset:33792
	ds_read_b128 v[138:141], v241 offset:34816
	ds_read_b128 v[142:145], v241 offset:35840
	ds_read_b128 v[146:149], v241 offset:49152
	ds_read_b128 v[150:153], v241 offset:50176
	ds_read_b128 v[172:175], v241 offset:51200
	ds_read_b128 v[176:179], v241 offset:52224
	s_add_u32 s28, s28, 0x100000
	s_addc_u32 s29, s29, 0
	s_mov_b32 m0, s40
	ds_read_b128 v[180:183], v185 offset:32768
	ds_read_b128 v[188:191], v185 offset:33792
	ds_read_b128 v[192:195], v185 offset:34816
	ds_read_b128 v[196:199], v185 offset:35840
	ds_read_b128 v[200:203], v185 offset:36864
	ds_read_b128 v[204:207], v185 offset:37888
	ds_read_b128 v[208:211], v185 offset:38912
	ds_read_b128 v[212:215], v185 offset:39936
	global_load_lds_dwordx4 v154, s[28:29]
	s_mov_b32 m0, s41
	s_nop 0
	global_load_lds_dwordx4 v158, s[28:29]
	s_waitcnt vmcnt(8)
	s_waitcnt lgkmcnt(0)
	s_barrier
	s_waitcnt lgkmcnt(0)
	v_mfma_f32_16x16x32_bf16 v[114:117], v[130:133], v[180:183], v[114:117]
	v_mfma_f32_16x16x32_bf16 v[106:109], v[130:133], v[192:195], v[106:109]
	v_mfma_f32_16x16x32_bf16 v[90:93], v[130:133], v[200:203], v[90:93]
	v_mfma_f32_16x16x32_bf16 v[74:77], v[130:133], v[208:211], v[74:77]
	v_mfma_f32_16x16x32_bf16 v[74:77], v[134:137], v[212:215], v[74:77]
	v_mfma_f32_16x16x32_bf16 v[90:93], v[134:137], v[204:207], v[90:93]
	v_mfma_f32_16x16x32_bf16 v[106:109], v[134:137], v[196:199], v[106:109]
	v_mfma_f32_16x16x32_bf16 v[114:117], v[134:137], v[188:191], v[114:117]
	v_mfma_f32_16x16x32_bf16 v[118:121], v[142:145], v[188:191], v[118:121]
	v_mfma_f32_16x16x32_bf16 v[98:101], v[142:145], v[196:199], v[98:101]
	v_mfma_f32_16x16x32_bf16 v[82:85], v[142:145], v[204:207], v[82:85]
	v_mfma_f32_16x16x32_bf16 v[66:69], v[142:145], v[212:215], v[66:69]
	v_mfma_f32_16x16x32_bf16 v[66:69], v[138:141], v[208:211], v[66:69]
	v_mfma_f32_16x16x32_bf16 v[82:85], v[138:141], v[200:203], v[82:85]
	v_mfma_f32_16x16x32_bf16 v[98:101], v[138:141], v[192:195], v[98:101]
	v_mfma_f32_16x16x32_bf16 v[118:121], v[138:141], v[180:183], v[118:121]
	v_mfma_f32_16x16x32_bf16 v[122:125], v[146:149], v[180:183], v[122:125]
	v_mfma_f32_16x16x32_bf16 v[110:113], v[146:149], v[192:195], v[110:113]
	v_mfma_f32_16x16x32_bf16 v[94:97], v[146:149], v[200:203], v[94:97]
	v_mfma_f32_16x16x32_bf16 v[78:81], v[146:149], v[208:211], v[78:81]
	v_mfma_f32_16x16x32_bf16 v[78:81], v[150:153], v[212:215], v[78:81]
	v_mfma_f32_16x16x32_bf16 v[94:97], v[150:153], v[204:207], v[94:97]
	v_mfma_f32_16x16x32_bf16 v[110:113], v[150:153], v[196:199], v[110:113]
	v_mfma_f32_16x16x32_bf16 v[122:125], v[150:153], v[188:191], v[122:125]
	v_mfma_f32_16x16x32_bf16 v[126:129], v[176:179], v[188:191], v[126:129]
	v_mfma_f32_16x16x32_bf16 v[102:105], v[176:179], v[196:199], v[102:105]
	v_mfma_f32_16x16x32_bf16 v[86:89], v[176:179], v[204:207], v[86:89]
	v_mfma_f32_16x16x32_bf16 v[70:73], v[176:179], v[212:215], v[70:73]
	v_mfma_f32_16x16x32_bf16 v[70:73], v[172:175], v[208:211], v[70:73]
	v_mfma_f32_16x16x32_bf16 v[86:89], v[172:175], v[200:203], v[86:89]
	v_mfma_f32_16x16x32_bf16 v[102:105], v[172:175], v[192:195], v[102:105]
	v_mfma_f32_16x16x32_bf16 v[126:129], v[172:175], v[180:183], v[126:129]
	s_barrier
	s_add_i32 s28, s33, s36
	s_add_i32 m0, s28, 0xffffff80
	ds_read_b128 v[180:183], v185 offset:49152
	ds_read_b128 v[188:191], v185 offset:50176
	ds_read_b128 v[192:195], v185 offset:51200
	ds_read_b128 v[196:199], v185 offset:52224
	ds_read_b128 v[200:203], v185 offset:53248
	ds_read_b128 v[204:207], v185 offset:54272
	ds_read_b128 v[208:211], v185 offset:55296
	ds_read_b128 v[212:215], v185 offset:56320
	global_load_lds_dwordx4 v156, s[24:25] offset:128
	s_add_i32 m0, s28, 0x1f80
	s_add_i32 s28, s42, s36
	global_load_lds_dwordx4 v160, s[24:25] offset:128
	s_add_u32 s24, s24, 0x100080
	s_addc_u32 s25, s25, 0
	s_mov_b32 m0, s28
	s_nop 0
	global_load_lds_dwordx4 v156, s[24:25]
	s_add_i32 m0, s28, 0x2000
	s_nop 0
	global_load_lds_dwordx4 v160, s[24:25]
	s_mov_b32 m0, s44
	s_nop 0
	global_load_lds_dwordx4 v154, s[100:101]
	s_mov_b32 m0, s45
	s_nop 0
	global_load_lds_dwordx4 v158, s[100:101]
	s_waitcnt vmcnt(8)
	s_waitcnt lgkmcnt(0)
	s_barrier
	s_waitcnt lgkmcnt(0)
	v_mfma_f32_16x16x32_bf16 v[58:61], v[130:133], v[180:183], v[58:61]
	v_mfma_f32_16x16x32_bf16 v[42:45], v[130:133], v[192:195], v[42:45]
	v_mfma_f32_16x16x32_bf16 v[26:29], v[130:133], v[200:203], v[26:29]
	v_mfma_f32_16x16x32_bf16 v[6:9], v[130:133], v[208:211], v[6:9]
	v_mfma_f32_16x16x32_bf16 v[6:9], v[134:137], v[212:215], v[6:9]
	v_mfma_f32_16x16x32_bf16 v[26:29], v[134:137], v[204:207], v[26:29]
	v_mfma_f32_16x16x32_bf16 v[42:45], v[134:137], v[196:199], v[42:45]
	v_mfma_f32_16x16x32_bf16 v[58:61], v[134:137], v[188:191], v[58:61]
	v_mfma_f32_16x16x32_bf16 v[54:57], v[142:145], v[188:191], v[54:57]
	v_mfma_f32_16x16x32_bf16 v[34:37], v[142:145], v[196:199], v[34:37]
	v_mfma_f32_16x16x32_bf16 v[18:21], v[142:145], v[204:207], v[18:21]
	v_mfma_f32_16x16x32_bf16 v[2:5], v[142:145], v[212:215], v[2:5]
	v_mfma_f32_16x16x32_bf16 v[2:5], v[138:141], v[208:211], v[2:5]
	v_mfma_f32_16x16x32_bf16 v[18:21], v[138:141], v[200:203], v[18:21]
	v_mfma_f32_16x16x32_bf16 v[34:37], v[138:141], v[192:195], v[34:37]
	v_mfma_f32_16x16x32_bf16 v[54:57], v[138:141], v[180:183], v[54:57]
	v_mfma_f32_16x16x32_bf16 v[62:65], v[146:149], v[180:183], v[62:65]
	v_mfma_f32_16x16x32_bf16 v[46:49], v[146:149], v[192:195], v[46:49]
	v_mfma_f32_16x16x32_bf16 v[30:33], v[146:149], v[200:203], v[30:33]
	v_mfma_f32_16x16x32_bf16 v[10:13], v[146:149], v[208:211], v[10:13]
	v_mfma_f32_16x16x32_bf16 v[10:13], v[150:153], v[212:215], v[10:13]
	v_mfma_f32_16x16x32_bf16 v[30:33], v[150:153], v[204:207], v[30:33]
	v_mfma_f32_16x16x32_bf16 v[46:49], v[150:153], v[196:199], v[46:49]
	v_mfma_f32_16x16x32_bf16 v[62:65], v[150:153], v[188:191], v[62:65]
	v_mfma_f32_16x16x32_bf16 v[50:53], v[176:179], v[188:191], v[50:53]
	v_mfma_f32_16x16x32_bf16 v[38:41], v[176:179], v[196:199], v[38:41]
	v_mfma_f32_16x16x32_bf16 v[22:25], v[176:179], v[204:207], v[22:25]
	v_mfma_f32_16x16x32_bf16 v[14:17], v[176:179], v[212:215], v[14:17]
	v_mfma_f32_16x16x32_bf16 v[14:17], v[172:175], v[208:211], v[14:17]
	v_mfma_f32_16x16x32_bf16 v[22:25], v[172:175], v[200:203], v[22:25]
	v_mfma_f32_16x16x32_bf16 v[38:41], v[172:175], v[192:195], v[38:41]
	v_mfma_f32_16x16x32_bf16 v[50:53], v[172:175], v[180:183], v[50:53]
	s_barrier
	s_add_i32 s62, s62, 2
	s_add_u32 s26, s26, 0x100
	s_addc_u32 s27, s27, 0
	s_add_u32 s52, s52, 0x100
	s_addc_u32 s53, s53, 0
	s_cmp_gt_u32 s62, 61
	s_cbranch_scc0 .LBB0_1595
	s_and_b64 vcc, exec, s[10:11]
	s_cbranch_vccz .LBB0_1598
	s_barrier

; #define PG8_STAGE(bufoff, gbase, voff) do { _Pragma("unroll") for (int _i = 0; _i < 2; ++_i) \
;         __builtin_amdgcn_global_load_lds((const unsigned*)((const char*)(gbase) + (voff)[_i]), (PG8_LAS unsigned*)(lds + (bufoff) + ldsw + _i * 8192), 16, 0, 0); } while (0)
; #define PG8_LDA(dst, b, h) do { _Pragma("unroll") for (int m = 0; m < 4; ++m) _Pragma("unroll") for (int k = 0; k < 2; ++k) dst[m][k] = *(const PG8_LAS bf16x8*)(lds + PG8_SA(b, h) + aoff + m * 2048 + k * 1024); } while (0)
; #define PG8_LDB(dst, b, h) do { _Pragma("unroll") for (int n = 0; n < 2; ++n) _Pragma("unroll") for (int k = 0; k < 2; ++k) dst[n][k] = *(const PG8_LAS bf16x8*)(lds + PG8_SB(b, h) + boff + n * 2048 + k * 1024); } while (0)
; #define PG8_MMA(ai, bj, At, Bt) do { __builtin_amdgcn_s_setprio(1); _Pragma("unroll") for (int m = 0; m < 4; ++m) _Pragma("unroll") for (int n = 0; n < 2; ++n) _Pragma("unroll") for (int k = 0; k < 2; ++k) \
;         acc[ai][bj][m][n] = __builtin_amdgcn_mfma_f32_16x16x32_bf16(Bt[n][k], At[m][k], acc[ai][bj][m][n], 0, 0, 0); __builtin_amdgcn_s_setprio(0); } while (0)
; #define PG8_WAIT_V(n) asm volatile("s_waitcnt vmcnt(" #n ")" ::: "memory")
; #define PG8_WAIT_L(n) asm volatile("s_waitcnt lgkmcnt(" #n ")" ::: "memory")
; template <class Epi, class Sched, bool ALIGN_EPI = false, bool SP2 = false>
; __device__ __forceinline__ void gemm_phase(PG8_LAS unsigned char* lds, const Gemm g, const Sched& S, const Epi& E) {
;     ...
;             const bool last = (t == nt - 2);
;             const char* a1 = cA + (size_t)(t + 1) * kstep;
;             const char* a2 = last ? nA : cA + (size_t)(t + 2) * kstep; const char* b2 = last ? nB : cB + (size_t)(t + 2) * kstep;
;             const char* a3 = a2 + kstep; const char* b3 = b2 + kstep;
;             if (last && has_next) S.a_ready(nxt);
;             if constexpr (SP2) {
;             PG8_LDB(B0, 0, 0); PG8_LDB(B1, 0, 1); PG8_SCHED; PG8_LDA(At, 0, 0); PG8_STAGE(PG8_SA(1, 1), a1 + hstep, voffA);
;             PG8_WAIT_V(8); PG8_WAIT_L(0); PG8_BAR; PG8_MMA(0, 0, At, B0); PG8_MMA(0, 1, At, B1); PG8_BAR; PG8_SCHED;
;             PG8_LDA(At, 0, 1); PG8_STAGE(PG8_SB(0, 0), b2, voffB); PG8_STAGE(PG8_SB(0, 1), b2 + hstep, voffB); PG8_STAGE(PG8_SA(0, 0), a2, voffA);
;             PG8_WAIT_V(8); PG8_WAIT_L(0); PG8_BAR; PG8_MMA(1, 0, At, B0); PG8_MMA(1, 1, At, B1); PG8_BAR; PG8_SCHED;
.LBB0_1681:
	ds_read_b128 v[160:163], v241 offset:0
	ds_read_b128 v[166:169], v241 offset:1024
	ds_read_b128 v[170:173], v241 offset:2048
	ds_read_b128 v[174:177], v241 offset:3072
	ds_read_b128 v[178:181], v241 offset:16384
	ds_read_b128 v[182:185], v241 offset:17408
	ds_read_b128 v[186:189], v241 offset:18432
	ds_read_b128 v[190:193], v241 offset:19456
	s_add_u32 s22, s24, 0xfff00080
	s_addc_u32 s23, s25, -1
	s_cmp_eq_u32 s52, 60
	s_cselect_b32 s27, s15, s23
	s_cselect_b32 s26, s48, s22
	s_cselect_b32 s23, s13, s51
	s_cselect_b32 s22, s49, s50
	s_add_i32 m0, s21, 0xc000
	ds_read_b128 v[194:197], v155
	ds_read_b128 v[198:201], v155 offset:1024
	ds_read_b128 v[202:205], v155 offset:2048
	ds_read_b128 v[206:209], v155 offset:3072
	ds_read_b128 v[210:213], v155 offset:4096
	ds_read_b128 v[214:217], v155 offset:5120
	ds_read_b128 v[218:221], v155 offset:6144
	ds_read_b128 v[222:225], v155 offset:7168
	global_load_lds_dwordx4 v138, s[24:25]
	s_add_i32 m0, s21, 0xe000
	s_nop 0
	global_load_lds_dwordx4 v140, s[24:25]
	s_waitcnt vmcnt(8)
	s_waitcnt lgkmcnt(0)
	s_barrier
	s_waitcnt lgkmcnt(0)
	v_mfma_f32_16x16x32_bf16 v[122:125], v[160:163], v[194:197], v[122:125]
	v_mfma_f32_16x16x32_bf16 v[106:109], v[160:163], v[202:205], v[106:109]
	v_mfma_f32_16x16x32_bf16 v[90:93], v[160:163], v[210:213], v[90:93]
	v_mfma_f32_16x16x32_bf16 v[74:77], v[160:163], v[218:221], v[74:77]
	v_mfma_f32_16x16x32_bf16 v[74:77], v[166:169], v[222:225], v[74:77]
	v_mfma_f32_16x16x32_bf16 v[90:93], v[166:169], v[214:217], v[90:93]
	v_mfma_f32_16x16x32_bf16 v[106:109], v[166:169], v[206:209], v[106:109]
	v_mfma_f32_16x16x32_bf16 v[122:125], v[166:169], v[198:201], v[122:125]
	v_mfma_f32_16x16x32_bf16 v[114:117], v[174:177], v[198:201], v[114:117]
	v_mfma_f32_16x16x32_bf16 v[98:101], v[174:177], v[206:209], v[98:101]
	v_mfma_f32_16x16x32_bf16 v[82:85], v[174:177], v[214:217], v[82:85]
	v_mfma_f32_16x16x32_bf16 v[62:65], v[174:177], v[222:225], v[62:65]
	v_mfma_f32_16x16x32_bf16 v[62:65], v[170:173], v[218:221], v[62:65]
	v_mfma_f32_16x16x32_bf16 v[82:85], v[170:173], v[210:213], v[82:85]
	v_mfma_f32_16x16x32_bf16 v[98:101], v[170:173], v[202:205], v[98:101]
	v_mfma_f32_16x16x32_bf16 v[114:117], v[170:173], v[194:197], v[114:117]
	v_mfma_f32_16x16x32_bf16 v[126:129], v[178:181], v[194:197], v[126:129]
	v_mfma_f32_16x16x32_bf16 v[110:113], v[178:181], v[202:205], v[110:113]
	v_mfma_f32_16x16x32_bf16 v[94:97], v[178:181], v[210:213], v[94:97]
	v_mfma_f32_16x16x32_bf16 v[78:81], v[178:181], v[218:221], v[78:81]
	v_mfma_f32_16x16x32_bf16 v[78:81], v[182:185], v[222:225], v[78:81]
	v_mfma_f32_16x16x32_bf16 v[94:97], v[182:185], v[214:217], v[94:97]
	v_mfma_f32_16x16x32_bf16 v[110:113], v[182:185], v[206:209], v[110:113]
	v_mfma_f32_16x16x32_bf16 v[126:129], v[182:185], v[198:201], v[126:129]
	v_mfma_f32_16x16x32_bf16 v[118:121], v[190:193], v[198:201], v[118:121]
	v_mfma_f32_16x16x32_bf16 v[102:105], v[190:193], v[206:209], v[102:105]
	v_mfma_f32_16x16x32_bf16 v[86:89], v[190:193], v[214:217], v[86:89]
	v_mfma_f32_16x16x32_bf16 v[70:73], v[190:193], v[222:225], v[70:73]
	v_mfma_f32_16x16x32_bf16 v[70:73], v[186:189], v[218:221], v[70:73]
	v_mfma_f32_16x16x32_bf16 v[86:89], v[186:189], v[210:213], v[86:89]
	v_mfma_f32_16x16x32_bf16 v[102:105], v[186:189], v[202:205], v[102:105]
	v_mfma_f32_16x16x32_bf16 v[118:121], v[186:189], v[194:197], v[118:121]
	s_barrier
	s_add_i32 s33, s44, s29
	s_mov_b32 m0, s33
	ds_read_b128 v[194:197], v155 offset:16384
	ds_read_b128 v[198:201], v155 offset:17408
	ds_read_b128 v[202:205], v155 offset:18432
	ds_read_b128 v[206:209], v155 offset:19456
	ds_read_b128 v[210:213], v155 offset:20480
	ds_read_b128 v[214:217], v155 offset:21504
	ds_read_b128 v[218:221], v155 offset:22528
	ds_read_b128 v[222:225], v155 offset:23552
	global_load_lds_dwordx4 v132, s[22:23]
	s_add_i32 m0, s33, 0x2000
	s_add_u32 s62, s22, 0x100000
	s_addc_u32 s63, s23, 0
	s_add_i32 s33, s45, s29
	global_load_lds_dwordx4 v136, s[22:23]
	s_mov_b32 m0, s33
	s_add_u32 s100, s26, 0x80
	s_addc_u32 s101, s27, 0
	global_load_lds_dwordx4 v132, s[62:63]
	s_add_i32 m0, s33, 0x2000
	s_nop 0
	global_load_lds_dwordx4 v136, s[62:63]
	s_mov_b32 m0, s21
	s_nop 0
	global_load_lds_dwordx4 v130, s[26:27]
	s_mov_b32 m0, s34
	s_nop 0
	global_load_lds_dwordx4 v134, s[26:27]
	s_waitcnt vmcnt(8)
	s_waitcnt lgkmcnt(0)
	s_barrier
	s_waitcnt lgkmcnt(0)
	v_mfma_f32_16x16x32_bf16 v[58:61], v[160:163], v[194:197], v[58:61]
	v_mfma_f32_16x16x32_bf16 v[42:45], v[160:163], v[202:205], v[42:45]
	v_mfma_f32_16x16x32_bf16 v[26:29], v[160:163], v[210:213], v[26:29]
	v_mfma_f32_16x16x32_bf16 v[10:13], v[160:163], v[218:221], v[10:13]
	v_mfma_f32_16x16x32_bf16 v[10:13], v[166:169], v[222:225], v[10:13]
	v_mfma_f32_16x16x32_bf16 v[26:29], v[166:169], v[214:217], v[26:29]
	v_mfma_f32_16x16x32_bf16 v[42:45], v[166:169], v[206:209], v[42:45]
	v_mfma_f32_16x16x32_bf16 v[58:61], v[166:169], v[198:201], v[58:61]
	v_mfma_f32_16x16x32_bf16 v[50:53], v[174:177], v[198:201], v[50:53]
	v_mfma_f32_16x16x32_bf16 v[34:37], v[174:177], v[206:209], v[34:37]
	v_mfma_f32_16x16x32_bf16 v[18:21], v[174:177], v[214:217], v[18:21]
	v_mfma_f32_16x16x32_bf16 v[2:5], v[174:177], v[222:225], v[2:5]
	v_mfma_f32_16x16x32_bf16 v[2:5], v[170:173], v[218:221], v[2:5]
	v_mfma_f32_16x16x32_bf16 v[18:21], v[170:173], v[210:213], v[18:21]
	v_mfma_f32_16x16x32_bf16 v[34:37], v[170:173], v[202:205], v[34:37]
	v_mfma_f32_16x16x32_bf16 v[50:53], v[170:173], v[194:197], v[50:53]
	v_mfma_f32_16x16x32_bf16 v[66:69], v[178:181], v[194:197], v[66:69]
	v_mfma_f32_16x16x32_bf16 v[46:49], v[178:181], v[202:205], v[46:49]
	v_mfma_f32_16x16x32_bf16 v[30:33], v[178:181], v[210:213], v[30:33]
	v_mfma_f32_16x16x32_bf16 v[14:17], v[178:181], v[218:221], v[14:17]
	v_mfma_f32_16x16x32_bf16 v[14:17], v[182:185], v[222:225], v[14:17]
	v_mfma_f32_16x16x32_bf16 v[30:33], v[182:185], v[214:217], v[30:33]
	v_mfma_f32_16x16x32_bf16 v[46:49], v[182:185], v[206:209], v[46:49]
	v_mfma_f32_16x16x32_bf16 v[66:69], v[182:185], v[198:201], v[66:69]
	v_mfma_f32_16x16x32_bf16 v[54:57], v[190:193], v[198:201], v[54:57]
	v_mfma_f32_16x16x32_bf16 v[38:41], v[190:193], v[206:209], v[38:41]
	v_mfma_f32_16x16x32_bf16 v[22:25], v[190:193], v[214:217], v[22:25]
	v_mfma_f32_16x16x32_bf16 v[6:9], v[190:193], v[222:225], v[6:9]
	v_mfma_f32_16x16x32_bf16 v[6:9], v[186:189], v[218:221], v[6:9]
	v_mfma_f32_16x16x32_bf16 v[22:25], v[186:189], v[210:213], v[22:25]
	v_mfma_f32_16x16x32_bf16 v[38:41], v[186:189], v[202:205], v[38:41]
	v_mfma_f32_16x16x32_bf16 v[54:57], v[186:189], v[194:197], v[54:57]
	s_barrier
; #define PG8_STAGE(bufoff, gbase, voff) do { _Pragma("unroll") for (int _i = 0; _i < 2; ++_i) \
;         __builtin_amdgcn_global_load_lds((const unsigned*)((const char*)(gbase) + (voff)[_i]), (PG8_LAS unsigned*)(lds + (bufoff) + ldsw + _i * 8192), 16, 0, 0); } while (0)
; #define PG8_LDA(dst, b, h) do { _Pragma("unroll") for (int m = 0; m < 4; ++m) _Pragma("unroll") for (int k = 0; k < 2; ++k) dst[m][k] = *(const PG8_LAS bf16x8*)(lds + PG8_SA(b, h) + aoff + m * 2048 + k * 1024); } while (0)
; #define PG8_LDB(dst, b, h) do { _Pragma("unroll") for (int n = 0; n < 2; ++n) _Pragma("unroll") for (int k = 0; k < 2; ++k) dst[n][k] = *(const PG8_LAS bf16x8*)(lds + PG8_SB(b, h) + boff + n * 2048 + k * 1024); } while (0)
; #define PG8_MMA(ai, bj, At, Bt) do { __builtin_amdgcn_s_setprio(1); _Pragma("unroll") for (int m = 0; m < 4; ++m) _Pragma("unroll") for (int n = 0; n < 2; ++n) _Pragma("unroll") for (int k = 0; k < 2; ++k) \
;         acc[ai][bj][m][n] = __builtin_amdgcn_mfma_f32_16x16x32_bf16(Bt[n][k], At[m][k], acc[ai][bj][m][n], 0, 0, 0); __builtin_amdgcn_s_setprio(0); } while (0)
; #define PG8_WAIT_V(n) asm volatile("s_waitcnt vmcnt(" #n ")" ::: "memory")
; #define PG8_WAIT_L(n) asm volatile("s_waitcnt lgkmcnt(" #n ")" ::: "memory")
; #define PG8_BAR __builtin_amdgcn_s_barrier()
; #define PG8_SCHED __builtin_amdgcn_sched_barrier(0)
; template <class Epi, class Sched, bool ALIGN_EPI = false, bool SP2 = false>
; __device__ __forceinline__ void gemm_phase(PG8_LAS unsigned char* lds, const Gemm g, const Sched& S, const Epi& E) {
;     ...
;             PG8_LDB(B0, 1, 0); PG8_LDB(B1, 1, 1); PG8_SCHED; PG8_LDA(At, 1, 0); PG8_STAGE(PG8_SA(0, 1), a2 + hstep, voffA);
;             PG8_WAIT_V(8); PG8_WAIT_L(0); PG8_BAR; PG8_MMA(0, 0, At, B0); PG8_MMA(0, 1, At, B1); PG8_BAR; PG8_SCHED;
;             PG8_LDA(At, 1, 1); PG8_STAGE(PG8_SB(1, 0), b3, voffB); PG8_STAGE(PG8_SB(1, 1), b3 + hstep, voffB); PG8_STAGE(PG8_SA(1, 0), a3, voffA);
;             PG8_WAIT_V(8); PG8_WAIT_L(0); PG8_BAR; PG8_MMA(1, 0, At, B0); PG8_MMA(1, 1, At, B1); PG8_BAR; PG8_SCHED;
	s_add_i32 s33, 0, 0x18000
	s_add_i32 s42, 0, 0x1c000
	ds_read_b128 v[160:163], v241 offset:32768
	ds_read_b128 v[166:169], v241 offset:33792
	ds_read_b128 v[170:173], v241 offset:34816
	ds_read_b128 v[174:177], v241 offset:35840
	ds_read_b128 v[178:181], v241 offset:49152
	ds_read_b128 v[182:185], v241 offset:50176
	ds_read_b128 v[186:189], v241 offset:51200
	ds_read_b128 v[190:193], v241 offset:52224
	s_add_u32 s26, s26, 0x100000
	s_addc_u32 s27, s27, 0
	s_mov_b32 m0, s35
	ds_read_b128 v[194:197], v155 offset:32768
	ds_read_b128 v[198:201], v155 offset:33792
	ds_read_b128 v[202:205], v155 offset:34816
	ds_read_b128 v[206:209], v155 offset:35840
	ds_read_b128 v[210:213], v155 offset:36864
	ds_read_b128 v[214:217], v155 offset:37888
	ds_read_b128 v[218:221], v155 offset:38912
	ds_read_b128 v[222:225], v155 offset:39936
	global_load_lds_dwordx4 v130, s[26:27]
	s_mov_b32 m0, s36
	s_nop 0
	global_load_lds_dwordx4 v134, s[26:27]
	s_waitcnt vmcnt(8)
	s_waitcnt lgkmcnt(0)
	s_barrier
	s_waitcnt lgkmcnt(0)
	v_mfma_f32_16x16x32_bf16 v[122:125], v[160:163], v[194:197], v[122:125]
	v_mfma_f32_16x16x32_bf16 v[106:109], v[160:163], v[202:205], v[106:109]
	v_mfma_f32_16x16x32_bf16 v[90:93], v[160:163], v[210:213], v[90:93]
	v_mfma_f32_16x16x32_bf16 v[74:77], v[160:163], v[218:221], v[74:77]
	v_mfma_f32_16x16x32_bf16 v[74:77], v[166:169], v[222:225], v[74:77]
	v_mfma_f32_16x16x32_bf16 v[90:93], v[166:169], v[214:217], v[90:93]
	v_mfma_f32_16x16x32_bf16 v[106:109], v[166:169], v[206:209], v[106:109]
	v_mfma_f32_16x16x32_bf16 v[122:125], v[166:169], v[198:201], v[122:125]
	v_mfma_f32_16x16x32_bf16 v[114:117], v[174:177], v[198:201], v[114:117]
	v_mfma_f32_16x16x32_bf16 v[98:101], v[174:177], v[206:209], v[98:101]
	v_mfma_f32_16x16x32_bf16 v[82:85], v[174:177], v[214:217], v[82:85]
	v_mfma_f32_16x16x32_bf16 v[62:65], v[174:177], v[222:225], v[62:65]
	v_mfma_f32_16x16x32_bf16 v[62:65], v[170:173], v[218:221], v[62:65]
	v_mfma_f32_16x16x32_bf16 v[82:85], v[170:173], v[210:213], v[82:85]
	v_mfma_f32_16x16x32_bf16 v[98:101], v[170:173], v[202:205], v[98:101]
	v_mfma_f32_16x16x32_bf16 v[114:117], v[170:173], v[194:197], v[114:117]
	v_mfma_f32_16x16x32_bf16 v[126:129], v[178:181], v[194:197], v[126:129]
	v_mfma_f32_16x16x32_bf16 v[110:113], v[178:181], v[202:205], v[110:113]
	v_mfma_f32_16x16x32_bf16 v[94:97], v[178:181], v[210:213], v[94:97]
	v_mfma_f32_16x16x32_bf16 v[78:81], v[178:181], v[218:221], v[78:81]
	v_mfma_f32_16x16x32_bf16 v[78:81], v[182:185], v[222:225], v[78:81]
	v_mfma_f32_16x16x32_bf16 v[94:97], v[182:185], v[214:217], v[94:97]
	v_mfma_f32_16x16x32_bf16 v[110:113], v[182:185], v[206:209], v[110:113]
	v_mfma_f32_16x16x32_bf16 v[126:129], v[182:185], v[198:201], v[126:129]
	v_mfma_f32_16x16x32_bf16 v[118:121], v[190:193], v[198:201], v[118:121]
	v_mfma_f32_16x16x32_bf16 v[102:105], v[190:193], v[206:209], v[102:105]
	v_mfma_f32_16x16x32_bf16 v[86:89], v[190:193], v[214:217], v[86:89]
	v_mfma_f32_16x16x32_bf16 v[70:73], v[190:193], v[222:225], v[70:73]
	v_mfma_f32_16x16x32_bf16 v[70:73], v[186:189], v[218:221], v[70:73]
	v_mfma_f32_16x16x32_bf16 v[86:89], v[186:189], v[210:213], v[86:89]
	v_mfma_f32_16x16x32_bf16 v[102:105], v[186:189], v[202:205], v[102:105]
	v_mfma_f32_16x16x32_bf16 v[118:121], v[186:189], v[194:197], v[118:121]
	s_barrier
	s_add_i32 s26, s33, s29
	s_add_i32 m0, s26, 0xffffff80
	ds_read_b128 v[194:197], v155 offset:49152
	ds_read_b128 v[198:201], v155 offset:50176
	ds_read_b128 v[202:205], v155 offset:51200
	ds_read_b128 v[206:209], v155 offset:52224
	ds_read_b128 v[210:213], v155 offset:53248
	ds_read_b128 v[214:217], v155 offset:54272
	ds_read_b128 v[218:221], v155 offset:55296
	ds_read_b128 v[222:225], v155 offset:56320
	global_load_lds_dwordx4 v132, s[22:23] offset:128
	s_add_i32 m0, s26, 0x1f80
	s_add_i32 s26, s42, s29
	global_load_lds_dwordx4 v136, s[22:23] offset:128
	s_add_u32 s22, s22, 0x100080
	s_addc_u32 s23, s23, 0
	s_mov_b32 m0, s26
	s_nop 0
	global_load_lds_dwordx4 v132, s[22:23]
	s_add_i32 m0, s26, 0x2000
	s_nop 0
	global_load_lds_dwordx4 v136, s[22:23]
	s_mov_b32 m0, s41
	s_nop 0
	global_load_lds_dwordx4 v130, s[100:101]
	s_mov_b32 m0, s43
	s_nop 0
	global_load_lds_dwordx4 v134, s[100:101]
	s_waitcnt vmcnt(8)
	s_waitcnt lgkmcnt(0)
	s_barrier
	s_waitcnt lgkmcnt(0)
	v_mfma_f32_16x16x32_bf16 v[58:61], v[160:163], v[194:197], v[58:61]
	v_mfma_f32_16x16x32_bf16 v[42:45], v[160:163], v[202:205], v[42:45]
	v_mfma_f32_16x16x32_bf16 v[26:29], v[160:163], v[210:213], v[26:29]
	v_mfma_f32_16x16x32_bf16 v[10:13], v[160:163], v[218:221], v[10:13]
	v_mfma_f32_16x16x32_bf16 v[10:13], v[166:169], v[222:225], v[10:13]
	v_mfma_f32_16x16x32_bf16 v[26:29], v[166:169], v[214:217], v[26:29]
	v_mfma_f32_16x16x32_bf16 v[42:45], v[166:169], v[206:209], v[42:45]
	v_mfma_f32_16x16x32_bf16 v[58:61], v[166:169], v[198:201], v[58:61]
	v_mfma_f32_16x16x32_bf16 v[50:53], v[174:177], v[198:201], v[50:53]
	v_mfma_f32_16x16x32_bf16 v[34:37], v[174:177], v[206:209], v[34:37]
	v_mfma_f32_16x16x32_bf16 v[18:21], v[174:177], v[214:217], v[18:21]
	v_mfma_f32_16x16x32_bf16 v[2:5], v[174:177], v[222:225], v[2:5]
	v_mfma_f32_16x16x32_bf16 v[2:5], v[170:173], v[218:221], v[2:5]
	v_mfma_f32_16x16x32_bf16 v[18:21], v[170:173], v[210:213], v[18:21]
	v_mfma_f32_16x16x32_bf16 v[34:37], v[170:173], v[202:205], v[34:37]
	v_mfma_f32_16x16x32_bf16 v[50:53], v[170:173], v[194:197], v[50:53]
	v_mfma_f32_16x16x32_bf16 v[66:69], v[178:181], v[194:197], v[66:69]
	v_mfma_f32_16x16x32_bf16 v[46:49], v[178:181], v[202:205], v[46:49]
	v_mfma_f32_16x16x32_bf16 v[30:33], v[178:181], v[210:213], v[30:33]
	v_mfma_f32_16x16x32_bf16 v[14:17], v[178:181], v[218:221], v[14:17]
	v_mfma_f32_16x16x32_bf16 v[14:17], v[182:185], v[222:225], v[14:17]
	v_mfma_f32_16x16x32_bf16 v[30:33], v[182:185], v[214:217], v[30:33]
	v_mfma_f32_16x16x32_bf16 v[46:49], v[182:185], v[206:209], v[46:49]
	v_mfma_f32_16x16x32_bf16 v[66:69], v[182:185], v[198:201], v[66:69]
	v_mfma_f32_16x16x32_bf16 v[54:57], v[190:193], v[198:201], v[54:57]
	v_mfma_f32_16x16x32_bf16 v[38:41], v[190:193], v[206:209], v[38:41]
	v_mfma_f32_16x16x32_bf16 v[22:25], v[190:193], v[214:217], v[22:25]
	v_mfma_f32_16x16x32_bf16 v[6:9], v[190:193], v[222:225], v[6:9]
	v_mfma_f32_16x16x32_bf16 v[6:9], v[186:189], v[218:221], v[6:9]
	v_mfma_f32_16x16x32_bf16 v[22:25], v[186:189], v[210:213], v[22:25]
	v_mfma_f32_16x16x32_bf16 v[38:41], v[186:189], v[202:205], v[38:41]
	v_mfma_f32_16x16x32_bf16 v[54:57], v[186:189], v[194:197], v[54:57]
	s_barrier
	s_add_i32 s52, s52, 2
	s_add_u32 s24, s24, 0x100
	s_addc_u32 s25, s25, 0
	s_add_u32 s50, s50, 0x100
	s_addc_u32 s51, s51, 0
	s_cmp_gt_u32 s52, 61
	s_cbranch_scc0 .LBB0_1681
	s_and_b64 vcc, exec, s[8:9]
	s_cbranch_vccz .LBB0_1684
	s_barrier

; #define PG8_STAGE(bufoff, gbase, voff) do { _Pragma("unroll") for (int _i = 0; _i < 2; ++_i) \
;         __builtin_amdgcn_global_load_lds((const unsigned*)((const char*)(gbase) + (voff)[_i]), (PG8_LAS unsigned*)(lds + (bufoff) + ldsw + _i * 8192), 16, 0, 0); } while (0)
; #define PG8_LDA(dst, b, h) do { _Pragma("unroll") for (int m = 0; m < 4; ++m) _Pragma("unroll") for (int k = 0; k < 2; ++k) dst[m][k] = *(const PG8_LAS bf16x8*)(lds + PG8_SA(b, h) + aoff + m * 2048 + k * 1024); } while (0)
; #define PG8_LDB(dst, b, h) do { _Pragma("unroll") for (int n = 0; n < 2; ++n) _Pragma("unroll") for (int k = 0; k < 2; ++k) dst[n][k] = *(const PG8_LAS bf16x8*)(lds + PG8_SB(b, h) + boff + n * 2048 + k * 1024); } while (0)
; #define PG8_MMA(ai, bj, At, Bt) do { __builtin_amdgcn_s_setprio(1); _Pragma("unroll") for (int m = 0; m < 4; ++m) _Pragma("unroll") for (int n = 0; n < 2; ++n) _Pragma("unroll") for (int k = 0; k < 2; ++k) \
;         acc[ai][bj][m][n] = __builtin_amdgcn_mfma_f32_16x16x32_bf16(Bt[n][k], At[m][k], acc[ai][bj][m][n], 0, 0, 0); __builtin_amdgcn_s_setprio(0); } while (0)
; #define PG8_WAIT_V(n) asm volatile("s_waitcnt vmcnt(" #n ")" ::: "memory")
; #define PG8_WAIT_L(n) asm volatile("s_waitcnt lgkmcnt(" #n ")" ::: "memory")
; template <class Epi, class Sched, bool ALIGN_EPI = false, bool SP2 = false>
; __device__ __forceinline__ void gemm_phase(PG8_LAS unsigned char* lds, const Gemm g, const Sched& S, const Epi& E) {
;     ...
;             const bool last = (t == nt - 2);
;             const char* a1 = cA + (size_t)(t + 1) * kstep;
;             const char* a2 = last ? nA : cA + (size_t)(t + 2) * kstep; const char* b2 = last ? nB : cB + (size_t)(t + 2) * kstep;
;             const char* a3 = a2 + kstep; const char* b3 = b2 + kstep;
;             if (last && has_next) S.a_ready(nxt);
;             if constexpr (SP2) {
;             PG8_LDB(B0, 0, 0); PG8_LDB(B1, 0, 1); PG8_SCHED; PG8_LDA(At, 0, 0); PG8_STAGE(PG8_SA(1, 1), a1 + hstep, voffA);
;             PG8_WAIT_V(8); PG8_WAIT_L(0); PG8_BAR; PG8_MMA(0, 0, At, B0); PG8_MMA(0, 1, At, B1); PG8_BAR; PG8_SCHED;
;             PG8_LDA(At, 0, 1); PG8_STAGE(PG8_SB(0, 0), b2, voffB); PG8_STAGE(PG8_SB(0, 1), b2 + hstep, voffB); PG8_STAGE(PG8_SA(0, 0), a2, voffA);
;             PG8_WAIT_V(8); PG8_WAIT_L(0); PG8_BAR; PG8_MMA(1, 0, At, B0); PG8_MMA(1, 1, At, B1); PG8_BAR; PG8_SCHED;
.LBB0_1801:
	ds_read_b128 v[130:133], v241 offset:0
	ds_read_b128 v[134:137], v241 offset:1024
	ds_read_b128 v[138:141], v241 offset:2048
	ds_read_b128 v[142:145], v241 offset:3072
	ds_read_b128 v[146:149], v241 offset:16384
	ds_read_b128 v[150:153], v241 offset:17408
	ds_read_b128 v[170:173], v241 offset:18432
	ds_read_b128 v[174:177], v241 offset:19456
	s_add_u32 s16, s18, 0xffd50080
	s_addc_u32 s17, s19, -1
	s_cmpk_eq_i32 s48, 0xa8
	s_cselect_b32 s21, s5, s17
	s_cselect_b32 s20, s4, s16
	s_cselect_b32 s17, s15, s47
	s_cselect_b32 s16, s14, s46
	s_add_i32 m0, s25, 0xc000
	ds_read_b128 v[178:181], v184
	ds_read_b128 v[186:189], v184 offset:1024
	ds_read_b128 v[190:193], v184 offset:2048
	ds_read_b128 v[194:197], v184 offset:3072
	ds_read_b128 v[198:201], v184 offset:4096
	ds_read_b128 v[202:205], v184 offset:5120
	ds_read_b128 v[206:209], v184 offset:6144
	ds_read_b128 v[210:213], v184 offset:7168
	global_load_lds_dwordx4 v0, s[18:19]
	s_add_i32 m0, s25, 0xe000
	s_nop 0
	global_load_lds_dwordx4 v162, s[18:19]
	s_waitcnt vmcnt(8)
	s_waitcnt lgkmcnt(0)
	s_barrier
	s_waitcnt lgkmcnt(0)
	v_mfma_f32_16x16x32_bf16 v[114:117], v[130:133], v[178:181], v[114:117]
	v_mfma_f32_16x16x32_bf16 v[106:109], v[130:133], v[190:193], v[106:109]
	v_mfma_f32_16x16x32_bf16 v[90:93], v[130:133], v[198:201], v[90:93]
	v_mfma_f32_16x16x32_bf16 v[74:77], v[130:133], v[206:209], v[74:77]
	v_mfma_f32_16x16x32_bf16 v[74:77], v[134:137], v[210:213], v[74:77]
	v_mfma_f32_16x16x32_bf16 v[90:93], v[134:137], v[202:205], v[90:93]
	v_mfma_f32_16x16x32_bf16 v[106:109], v[134:137], v[194:197], v[106:109]
	v_mfma_f32_16x16x32_bf16 v[114:117], v[134:137], v[186:189], v[114:117]
	v_mfma_f32_16x16x32_bf16 v[118:121], v[142:145], v[186:189], v[118:121]
	v_mfma_f32_16x16x32_bf16 v[98:101], v[142:145], v[194:197], v[98:101]
	v_mfma_f32_16x16x32_bf16 v[82:85], v[142:145], v[202:205], v[82:85]
	v_mfma_f32_16x16x32_bf16 v[66:69], v[142:145], v[210:213], v[66:69]
	v_mfma_f32_16x16x32_bf16 v[66:69], v[138:141], v[206:209], v[66:69]
	v_mfma_f32_16x16x32_bf16 v[82:85], v[138:141], v[198:201], v[82:85]
	v_mfma_f32_16x16x32_bf16 v[98:101], v[138:141], v[190:193], v[98:101]
	v_mfma_f32_16x16x32_bf16 v[118:121], v[138:141], v[178:181], v[118:121]
	v_mfma_f32_16x16x32_bf16 v[122:125], v[146:149], v[178:181], v[122:125]
	v_mfma_f32_16x16x32_bf16 v[110:113], v[146:149], v[190:193], v[110:113]
	v_mfma_f32_16x16x32_bf16 v[94:97], v[146:149], v[198:201], v[94:97]
	v_mfma_f32_16x16x32_bf16 v[78:81], v[146:149], v[206:209], v[78:81]
	v_mfma_f32_16x16x32_bf16 v[78:81], v[150:153], v[210:213], v[78:81]
	v_mfma_f32_16x16x32_bf16 v[94:97], v[150:153], v[202:205], v[94:97]
	v_mfma_f32_16x16x32_bf16 v[110:113], v[150:153], v[194:197], v[110:113]
	v_mfma_f32_16x16x32_bf16 v[122:125], v[150:153], v[186:189], v[122:125]
	v_mfma_f32_16x16x32_bf16 v[126:129], v[174:177], v[186:189], v[126:129]
	v_mfma_f32_16x16x32_bf16 v[102:105], v[174:177], v[194:197], v[102:105]
	v_mfma_f32_16x16x32_bf16 v[86:89], v[174:177], v[202:205], v[86:89]
	v_mfma_f32_16x16x32_bf16 v[70:73], v[174:177], v[210:213], v[70:73]
	v_mfma_f32_16x16x32_bf16 v[70:73], v[170:173], v[206:209], v[70:73]
	v_mfma_f32_16x16x32_bf16 v[86:89], v[170:173], v[198:201], v[86:89]
	v_mfma_f32_16x16x32_bf16 v[102:105], v[170:173], v[190:193], v[102:105]
	v_mfma_f32_16x16x32_bf16 v[126:129], v[170:173], v[178:181], v[126:129]
	s_barrier
	s_add_i32 s33, s36, s24
	s_mov_b32 m0, s33
	ds_read_b128 v[178:181], v184 offset:16384
	ds_read_b128 v[186:189], v184 offset:17408
	ds_read_b128 v[190:193], v184 offset:18432
	ds_read_b128 v[194:197], v184 offset:19456
	ds_read_b128 v[198:201], v184 offset:20480
	ds_read_b128 v[202:205], v184 offset:21504
	ds_read_b128 v[206:209], v184 offset:22528
	ds_read_b128 v[210:213], v184 offset:23552
	global_load_lds_dwordx4 v156, s[16:17]
	s_add_i32 m0, s33, 0x2000
	s_add_u32 s50, s16, 0x2b0000
	s_addc_u32 s51, s17, 0
	s_add_i32 s33, s37, s24
	global_load_lds_dwordx4 v160, s[16:17]
	s_mov_b32 m0, s33
	s_add_u32 s100, s20, 0x80
	s_addc_u32 s101, s21, 0
	global_load_lds_dwordx4 v156, s[50:51]
	s_add_i32 m0, s33, 0x2000
	s_nop 0
	global_load_lds_dwordx4 v160, s[50:51]
	s_mov_b32 m0, s25
	s_nop 0
	global_load_lds_dwordx4 v154, s[20:21]
	s_mov_b32 m0, s26
	s_nop 0
	global_load_lds_dwordx4 v158, s[20:21]
	s_waitcnt vmcnt(8)
	s_waitcnt lgkmcnt(0)
	s_barrier
	s_waitcnt lgkmcnt(0)
	v_mfma_f32_16x16x32_bf16 v[58:61], v[130:133], v[178:181], v[58:61]
	v_mfma_f32_16x16x32_bf16 v[42:45], v[130:133], v[190:193], v[42:45]
	v_mfma_f32_16x16x32_bf16 v[26:29], v[130:133], v[198:201], v[26:29]
	v_mfma_f32_16x16x32_bf16 v[6:9], v[130:133], v[206:209], v[6:9]
	v_mfma_f32_16x16x32_bf16 v[6:9], v[134:137], v[210:213], v[6:9]
	v_mfma_f32_16x16x32_bf16 v[26:29], v[134:137], v[202:205], v[26:29]
	v_mfma_f32_16x16x32_bf16 v[42:45], v[134:137], v[194:197], v[42:45]
	v_mfma_f32_16x16x32_bf16 v[58:61], v[134:137], v[186:189], v[58:61]
	v_mfma_f32_16x16x32_bf16 v[54:57], v[142:145], v[186:189], v[54:57]
	v_mfma_f32_16x16x32_bf16 v[34:37], v[142:145], v[194:197], v[34:37]
	v_mfma_f32_16x16x32_bf16 v[18:21], v[142:145], v[202:205], v[18:21]
	v_mfma_f32_16x16x32_bf16 v[2:5], v[142:145], v[210:213], v[2:5]
	v_mfma_f32_16x16x32_bf16 v[2:5], v[138:141], v[206:209], v[2:5]
	v_mfma_f32_16x16x32_bf16 v[18:21], v[138:141], v[198:201], v[18:21]
	v_mfma_f32_16x16x32_bf16 v[34:37], v[138:141], v[190:193], v[34:37]
	v_mfma_f32_16x16x32_bf16 v[54:57], v[138:141], v[178:181], v[54:57]
	v_mfma_f32_16x16x32_bf16 v[62:65], v[146:149], v[178:181], v[62:65]
	v_mfma_f32_16x16x32_bf16 v[46:49], v[146:149], v[190:193], v[46:49]
	v_mfma_f32_16x16x32_bf16 v[30:33], v[146:149], v[198:201], v[30:33]
	v_mfma_f32_16x16x32_bf16 v[10:13], v[146:149], v[206:209], v[10:13]
	v_mfma_f32_16x16x32_bf16 v[10:13], v[150:153], v[210:213], v[10:13]
	v_mfma_f32_16x16x32_bf16 v[30:33], v[150:153], v[202:205], v[30:33]
	v_mfma_f32_16x16x32_bf16 v[46:49], v[150:153], v[194:197], v[46:49]
	v_mfma_f32_16x16x32_bf16 v[62:65], v[150:153], v[186:189], v[62:65]
	v_mfma_f32_16x16x32_bf16 v[50:53], v[174:177], v[186:189], v[50:53]
	v_mfma_f32_16x16x32_bf16 v[38:41], v[174:177], v[194:197], v[38:41]
	v_mfma_f32_16x16x32_bf16 v[22:25], v[174:177], v[202:205], v[22:25]
	v_mfma_f32_16x16x32_bf16 v[14:17], v[174:177], v[210:213], v[14:17]
	v_mfma_f32_16x16x32_bf16 v[14:17], v[170:173], v[206:209], v[14:17]
	v_mfma_f32_16x16x32_bf16 v[22:25], v[170:173], v[198:201], v[22:25]
	v_mfma_f32_16x16x32_bf16 v[38:41], v[170:173], v[190:193], v[38:41]
	v_mfma_f32_16x16x32_bf16 v[50:53], v[170:173], v[178:181], v[50:53]
	s_barrier
; #define PG8_STAGE(bufoff, gbase, voff) do { _Pragma("unroll") for (int _i = 0; _i < 2; ++_i) \
;         __builtin_amdgcn_global_load_lds((const unsigned*)((const char*)(gbase) + (voff)[_i]), (PG8_LAS unsigned*)(lds + (bufoff) + ldsw + _i * 8192), 16, 0, 0); } while (0)
; #define PG8_LDA(dst, b, h) do { _Pragma("unroll") for (int m = 0; m < 4; ++m) _Pragma("unroll") for (int k = 0; k < 2; ++k) dst[m][k] = *(const PG8_LAS bf16x8*)(lds + PG8_SA(b, h) + aoff + m * 2048 + k * 1024); } while (0)
; #define PG8_LDB(dst, b, h) do { _Pragma("unroll") for (int n = 0; n < 2; ++n) _Pragma("unroll") for (int k = 0; k < 2; ++k) dst[n][k] = *(const PG8_LAS bf16x8*)(lds + PG8_SB(b, h) + boff + n * 2048 + k * 1024); } while (0)
; #define PG8_MMA(ai, bj, At, Bt) do { __builtin_amdgcn_s_setprio(1); _Pragma("unroll") for (int m = 0; m < 4; ++m) _Pragma("unroll") for (int n = 0; n < 2; ++n) _Pragma("unroll") for (int k = 0; k < 2; ++k) \
;         acc[ai][bj][m][n] = __builtin_amdgcn_mfma_f32_16x16x32_bf16(Bt[n][k], At[m][k], acc[ai][bj][m][n], 0, 0, 0); __builtin_amdgcn_s_setprio(0); } while (0)
; #define PG8_WAIT_V(n) asm volatile("s_waitcnt vmcnt(" #n ")" ::: "memory")
; #define PG8_WAIT_L(n) asm volatile("s_waitcnt lgkmcnt(" #n ")" ::: "memory")
; #define PG8_BAR __builtin_amdgcn_s_barrier()
; #define PG8_SCHED __builtin_amdgcn_sched_barrier(0)
; template <class Epi, class Sched, bool ALIGN_EPI = false, bool SP2 = false>
; __device__ __forceinline__ void gemm_phase(PG8_LAS unsigned char* lds, const Gemm g, const Sched& S, const Epi& E) {
;     ...
;             PG8_LDB(B0, 1, 0); PG8_LDB(B1, 1, 1); PG8_SCHED; PG8_LDA(At, 1, 0); PG8_STAGE(PG8_SA(0, 1), a2 + hstep, voffA);
;             PG8_WAIT_V(8); PG8_WAIT_L(0); PG8_BAR; PG8_MMA(0, 0, At, B0); PG8_MMA(0, 1, At, B1); PG8_BAR; PG8_SCHED;
;             PG8_LDA(At, 1, 1); PG8_STAGE(PG8_SB(1, 0), b3, voffB); PG8_STAGE(PG8_SB(1, 1), b3 + hstep, voffB); PG8_STAGE(PG8_SA(1, 0), a3, voffA);
;             PG8_WAIT_V(8); PG8_WAIT_L(0); PG8_BAR; PG8_MMA(1, 0, At, B0); PG8_MMA(1, 1, At, B1); PG8_BAR; PG8_SCHED;
	s_add_i32 s33, 0, 0x18000
	s_add_i32 s42, 0, 0x1c000
	ds_read_b128 v[130:133], v241 offset:32768
	ds_read_b128 v[134:137], v241 offset:33792
	ds_read_b128 v[138:141], v241 offset:34816
	ds_read_b128 v[142:145], v241 offset:35840
	ds_read_b128 v[146:149], v241 offset:49152
	ds_read_b128 v[150:153], v241 offset:50176
	ds_read_b128 v[170:173], v241 offset:51200
	ds_read_b128 v[174:177], v241 offset:52224
	s_add_u32 s20, s20, 0x2b0000
	s_addc_u32 s21, s21, 0
	s_mov_b32 m0, s27
	ds_read_b128 v[178:181], v184 offset:32768
	ds_read_b128 v[186:189], v184 offset:33792
	ds_read_b128 v[190:193], v184 offset:34816
	ds_read_b128 v[194:197], v184 offset:35840
	ds_read_b128 v[198:201], v184 offset:36864
	ds_read_b128 v[202:205], v184 offset:37888
	ds_read_b128 v[206:209], v184 offset:38912
	ds_read_b128 v[210:213], v184 offset:39936
	global_load_lds_dwordx4 v154, s[20:21]
	s_mov_b32 m0, s28
	s_nop 0
	global_load_lds_dwordx4 v158, s[20:21]
	s_waitcnt vmcnt(8)
	s_waitcnt lgkmcnt(0)
	s_barrier
	s_waitcnt lgkmcnt(0)
	v_mfma_f32_16x16x32_bf16 v[114:117], v[130:133], v[178:181], v[114:117]
	v_mfma_f32_16x16x32_bf16 v[106:109], v[130:133], v[190:193], v[106:109]
	v_mfma_f32_16x16x32_bf16 v[90:93], v[130:133], v[198:201], v[90:93]
	v_mfma_f32_16x16x32_bf16 v[74:77], v[130:133], v[206:209], v[74:77]
	v_mfma_f32_16x16x32_bf16 v[74:77], v[134:137], v[210:213], v[74:77]
	v_mfma_f32_16x16x32_bf16 v[90:93], v[134:137], v[202:205], v[90:93]
	v_mfma_f32_16x16x32_bf16 v[106:109], v[134:137], v[194:197], v[106:109]
	v_mfma_f32_16x16x32_bf16 v[114:117], v[134:137], v[186:189], v[114:117]
	v_mfma_f32_16x16x32_bf16 v[118:121], v[142:145], v[186:189], v[118:121]
	v_mfma_f32_16x16x32_bf16 v[98:101], v[142:145], v[194:197], v[98:101]
	v_mfma_f32_16x16x32_bf16 v[82:85], v[142:145], v[202:205], v[82:85]
	v_mfma_f32_16x16x32_bf16 v[66:69], v[142:145], v[210:213], v[66:69]
	v_mfma_f32_16x16x32_bf16 v[66:69], v[138:141], v[206:209], v[66:69]
	v_mfma_f32_16x16x32_bf16 v[82:85], v[138:141], v[198:201], v[82:85]
	v_mfma_f32_16x16x32_bf16 v[98:101], v[138:141], v[190:193], v[98:101]
	v_mfma_f32_16x16x32_bf16 v[118:121], v[138:141], v[178:181], v[118:121]
	v_mfma_f32_16x16x32_bf16 v[122:125], v[146:149], v[178:181], v[122:125]
	v_mfma_f32_16x16x32_bf16 v[110:113], v[146:149], v[190:193], v[110:113]
	v_mfma_f32_16x16x32_bf16 v[94:97], v[146:149], v[198:201], v[94:97]
	v_mfma_f32_16x16x32_bf16 v[78:81], v[146:149], v[206:209], v[78:81]
	v_mfma_f32_16x16x32_bf16 v[78:81], v[150:153], v[210:213], v[78:81]
	v_mfma_f32_16x16x32_bf16 v[94:97], v[150:153], v[202:205], v[94:97]
	v_mfma_f32_16x16x32_bf16 v[110:113], v[150:153], v[194:197], v[110:113]
	v_mfma_f32_16x16x32_bf16 v[122:125], v[150:153], v[186:189], v[122:125]
	v_mfma_f32_16x16x32_bf16 v[126:129], v[174:177], v[186:189], v[126:129]
	v_mfma_f32_16x16x32_bf16 v[102:105], v[174:177], v[194:197], v[102:105]
	v_mfma_f32_16x16x32_bf16 v[86:89], v[174:177], v[202:205], v[86:89]
	v_mfma_f32_16x16x32_bf16 v[70:73], v[174:177], v[210:213], v[70:73]
	v_mfma_f32_16x16x32_bf16 v[70:73], v[170:173], v[206:209], v[70:73]
	v_mfma_f32_16x16x32_bf16 v[86:89], v[170:173], v[198:201], v[86:89]
	v_mfma_f32_16x16x32_bf16 v[102:105], v[170:173], v[190:193], v[102:105]
	v_mfma_f32_16x16x32_bf16 v[126:129], v[170:173], v[178:181], v[126:129]
	s_barrier
	s_add_i32 s20, s33, s24
	s_add_i32 m0, s20, 0xffffff80
	ds_read_b128 v[178:181], v184 offset:49152
	ds_read_b128 v[186:189], v184 offset:50176
	ds_read_b128 v[190:193], v184 offset:51200
	ds_read_b128 v[194:197], v184 offset:52224
	ds_read_b128 v[198:201], v184 offset:53248
	ds_read_b128 v[202:205], v184 offset:54272
	ds_read_b128 v[206:209], v184 offset:55296
	ds_read_b128 v[210:213], v184 offset:56320
	global_load_lds_dwordx4 v156, s[16:17] offset:128
	s_add_i32 m0, s20, 0x1f80
	s_add_i32 s20, s42, s24
	global_load_lds_dwordx4 v160, s[16:17] offset:128
	s_add_u32 s16, s16, 0x2b0080
	s_addc_u32 s17, s17, 0
	s_mov_b32 m0, s20
	s_nop 0
	global_load_lds_dwordx4 v156, s[16:17]
	s_add_i32 m0, s20, 0x2000
	s_nop 0
	global_load_lds_dwordx4 v160, s[16:17]
	s_mov_b32 m0, s30
	s_nop 0
	global_load_lds_dwordx4 v154, s[100:101]
	s_mov_b32 m0, s31
	s_nop 0
	global_load_lds_dwordx4 v158, s[100:101]
	s_waitcnt vmcnt(8)
	s_waitcnt lgkmcnt(0)
	s_barrier
	s_waitcnt lgkmcnt(0)
	v_mfma_f32_16x16x32_bf16 v[58:61], v[130:133], v[178:181], v[58:61]
	v_mfma_f32_16x16x32_bf16 v[42:45], v[130:133], v[190:193], v[42:45]
	v_mfma_f32_16x16x32_bf16 v[26:29], v[130:133], v[198:201], v[26:29]
	v_mfma_f32_16x16x32_bf16 v[6:9], v[130:133], v[206:209], v[6:9]
	v_mfma_f32_16x16x32_bf16 v[6:9], v[134:137], v[210:213], v[6:9]
	v_mfma_f32_16x16x32_bf16 v[26:29], v[134:137], v[202:205], v[26:29]
	v_mfma_f32_16x16x32_bf16 v[42:45], v[134:137], v[194:197], v[42:45]
	v_mfma_f32_16x16x32_bf16 v[58:61], v[134:137], v[186:189], v[58:61]
	v_mfma_f32_16x16x32_bf16 v[54:57], v[142:145], v[186:189], v[54:57]
	v_mfma_f32_16x16x32_bf16 v[34:37], v[142:145], v[194:197], v[34:37]
	v_mfma_f32_16x16x32_bf16 v[18:21], v[142:145], v[202:205], v[18:21]
	v_mfma_f32_16x16x32_bf16 v[2:5], v[142:145], v[210:213], v[2:5]
	v_mfma_f32_16x16x32_bf16 v[2:5], v[138:141], v[206:209], v[2:5]
	v_mfma_f32_16x16x32_bf16 v[18:21], v[138:141], v[198:201], v[18:21]
	v_mfma_f32_16x16x32_bf16 v[34:37], v[138:141], v[190:193], v[34:37]
	v_mfma_f32_16x16x32_bf16 v[54:57], v[138:141], v[178:181], v[54:57]
	v_mfma_f32_16x16x32_bf16 v[62:65], v[146:149], v[178:181], v[62:65]
	v_mfma_f32_16x16x32_bf16 v[46:49], v[146:149], v[190:193], v[46:49]
	v_mfma_f32_16x16x32_bf16 v[30:33], v[146:149], v[198:201], v[30:33]
	v_mfma_f32_16x16x32_bf16 v[10:13], v[146:149], v[206:209], v[10:13]
	v_mfma_f32_16x16x32_bf16 v[10:13], v[150:153], v[210:213], v[10:13]
	v_mfma_f32_16x16x32_bf16 v[30:33], v[150:153], v[202:205], v[30:33]
	v_mfma_f32_16x16x32_bf16 v[46:49], v[150:153], v[194:197], v[46:49]
	v_mfma_f32_16x16x32_bf16 v[62:65], v[150:153], v[186:189], v[62:65]
	v_mfma_f32_16x16x32_bf16 v[50:53], v[174:177], v[186:189], v[50:53]
	v_mfma_f32_16x16x32_bf16 v[38:41], v[174:177], v[194:197], v[38:41]
	v_mfma_f32_16x16x32_bf16 v[22:25], v[174:177], v[202:205], v[22:25]
	v_mfma_f32_16x16x32_bf16 v[14:17], v[174:177], v[210:213], v[14:17]
	v_mfma_f32_16x16x32_bf16 v[14:17], v[170:173], v[206:209], v[14:17]
	v_mfma_f32_16x16x32_bf16 v[22:25], v[170:173], v[198:201], v[22:25]
	v_mfma_f32_16x16x32_bf16 v[38:41], v[170:173], v[190:193], v[38:41]
	v_mfma_f32_16x16x32_bf16 v[50:53], v[170:173], v[178:181], v[50:53]
	s_barrier
	s_add_i32 s48, s48, 2
	s_add_u32 s18, s18, 0x100
	s_addc_u32 s19, s19, 0
	s_add_u32 s46, s46, 0x100
	s_addc_u32 s47, s47, 0
	s_cmpk_gt_u32 s48, 0xa9
	s_cbranch_scc0 .LBB0_1801
	s_and_b64 vcc, exec, s[12:13]
	s_cbranch_vccz .LBB0_1804
	s_barrier
